# bulk 16-byte stores of the phases before the output projection made write-through (sc1) so the grid barrier's L2 write-back finds no dirty lines
# baseline (speedup 1.0000x reference)
; DI unsigned pk2(float lo, float hi) { f32x2 v = {lo, hi}; bf2_t b = __builtin_convertvector(v, bf2_t); return __builtin_bit_cast(unsigned, b); }
; DI void transpose_tile(bf16_t* dst, int dst_ld, int n0, int nvalid, int nwrite, const float* src, int src_ld, int col0, int k0,
;                        const float* gain, float* ldsf, int tid) {
;     ...
;     if (n < nwrite) {
;         u32x4 w = {0u, 0u, 0u, 0u};
;         if (n < nvalid) {
;             const float* s = ldsf + (kc * 8) * 65 + n;
;             w[0] = pk2(s[0], s[65]); w[1] = pk2(s[130], s[195]); w[2] = pk2(s[260], s[325]); w[3] = pk2(s[390], s[455]);
;         }
;         *(u32x4*)(dst + (size_t)(n0 + n) * dst_ld + k0 + kc * 8) = w;
;     }
.LBB0_67:
	s_or_b64 exec, exec, s[44:45]
	v_add_u32_e32 v4, s24, v24
	v_ashrrev_i32_e32 v5, 31, v4
	v_lshlrev_b64 v[4:5], 11, v[4:5]
	v_lshl_add_u64 v[4:5], s[26:27], 0, v[4:5]
	s_lshl_b32 s24, s46, 1
	v_lshl_add_u64 v[4:5], v[4:5], 0, s[24:25]
	v_lshl_add_u64 v[4:5], v[4:5], 0, v[8:9]
	global_store_dwordx4 v[4:5], v[0:3], off sc1

; DI unsigned pk2(float lo, float hi) { f32x2 v = {lo, hi}; bf2_t b = __builtin_convertvector(v, bf2_t); return __builtin_bit_cast(unsigned, b); }
; DI void transpose_tile(bf16_t* dst, int dst_ld, int n0, int nvalid, int nwrite, const float* src, int src_ld, int col0, int k0,
;                        const float* gain, float* ldsf, int tid) {
;     ...
;         for (int r = 0; r < 2; ++r) {
;             const int c = tid + NT * r, kk = c >> 4, n4 = (c & 15) * 4;
;             f32x4 v = __builtin_nontemporal_load((const f32x4*)(src + (size_t)(k0 + kk) * src_ld + col0 + n4));
;             const float g = gain ? gain[k0 + kk] : 1.0f;
;             float* d = ldsf + kk * 65 + n4;
;             d[0] = v[0] * g; d[1] = v[1] * g; d[2] = v[2] * g; d[3] = v[3] * g;
;         }
;     }
;     __syncthreads();
;     const int n = tid >> 3, kc = tid & 7;
;     if (n < nwrite) {
;         u32x4 w = {0u, 0u, 0u, 0u};
;         if (n < nvalid) {
;             const float* s = ldsf + (kc * 8) * 65 + n;
;             w[0] = pk2(s[0], s[65]); w[1] = pk2(s[130], s[195]); w[2] = pk2(s[260], s[325]); w[3] = pk2(s[390], s[455]);
;         }
;         *(u32x4*)(dst + (size_t)(n0 + n) * dst_ld + k0 + kc * 8) = w;
; DI void weight_tile(const Params& p, int id, float* ldsf, int tid) {
;     ...
;     else {
;         const int j = id - WJ10; const int which = j >> 8, jj = j & 255;
;         const float* src = which == 0 ? p.w_bm : which == 1 ? p.w_bf : p.w_out;
;         bf16_t* dst = (bf16_t*)(ws + (which == 0 ? OFF_WBM : which == 1 ? OFF_WBF : OFF_WOUT));
;         transpose_tile(dst, 1024, (jj >> 4) * 64, 64, 64, src, 1024, (jj >> 4) * 64, (jj & 15) * 64, nullptr, ldsf, tid);
;     }
.LBB0_70:
	s_cmpk_gt_i32 s55, 0x38f
	s_mov_b64 s[6:7], -1
	s_cbranch_scc0 .LBB0_123
	s_cmpk_gt_u32 s55, 0x48f
	s_cbranch_scc0 .LBB0_114
	s_cmpk_gt_u32 s55, 0x58f
	s_cbranch_scc0 .LBB0_105
	s_cmpk_gt_u32 s55, 0x78f
	s_cbranch_scc0 .LBB0_96
	s_cmpk_gt_u32 s55, 0x7ef
	s_cbranch_scc0 .LBB0_87
	s_cmpk_gt_u32 s55, 0x82f
	s_cbranch_scc0 .LBB0_79
	s_add_i32 s24, s55, 0xfffff7d0
	s_cmpk_lt_u32 s24, 0x100
	s_cselect_b64 s[6:7], -1, 0
	s_and_b32 s24, s24, 0xffffff00
	s_cmpk_eq_i32 s24, 0x100
	s_cselect_b64 s[44:45], -1, 0
	s_and_b64 s[46:47], s[44:45], exec
	s_cselect_b32 s24, s51, 0x58
	s_and_b64 s[46:47], s[6:7], exec
	s_cselect_b32 s24, 0x48, s24
	s_add_u32 s46, s0, s24
	s_addc_u32 s47, s1, 0
	s_load_dwordx2 s[46:47], s[46:47], 0x0
	s_and_b32 s58, s16, 0x3c0
	s_and_b32 s24, s33, 0x3c0
	s_lshl_b32 s59, s58, 2
	v_add_u32_e32 v0, s24, v19
	s_waitcnt lgkmcnt(0)
	s_add_u32 s46, s46, s59
	s_addc_u32 s47, s47, 0
	v_mov_b32_e32 v17, v9
	v_ashrrev_i32_e32 v1, 31, v0
	v_lshl_add_u64 v[4:5], s[46:47], 0, v[16:17]
	v_lshlrev_b64 v[0:1], 12, v[0:1]
	v_add_u32_e32 v6, s24, v21
	v_lshl_add_u64 v[0:1], v[4:5], 0, v[0:1]
	v_ashrrev_i32_e32 v7, 31, v6
	global_load_dwordx4 v[0:3], v[0:1], off nt
	v_lshlrev_b64 v[6:7], 12, v[6:7]
	v_lshl_add_u64 v[4:5], v[4:5], 0, v[6:7]
	global_load_dwordx4 v[4:7], v[4:5], off nt
	s_waitcnt vmcnt(1)
	ds_write2_b32 v26, v0, v1 offset1:1
	ds_write2_b32 v27, v2, v3 offset1:1
	s_waitcnt vmcnt(0)
	ds_write2_b32 v28, v4, v5 offset1:1
	ds_write2_b32 v29, v6, v7 offset1:1
	s_waitcnt lgkmcnt(0)
	s_barrier
	s_and_saveexec_b64 s[46:47], s[4:5]
	s_cbranch_execz .LBB0_78
	ds_read2_b32 v[0:1], v30 offset1:65
	ds_read2_b32 v[2:3], v30 offset0:130 offset1:195
	ds_read2_b32 v[4:5], v31 offset0:4 offset1:69
	ds_read2_b32 v[6:7], v31 offset0:134 offset1:199
	s_and_b64 s[44:45], s[44:45], exec
	s_cselect_b32 s44, s52, 0x170fc00
	s_and_b64 s[6:7], s[6:7], exec
	s_cselect_b32 s6, 0x130fc00, s44
	s_waitcnt lgkmcnt(3)
	v_cvt_pk_bf16_f32 v0, v0, v1
	s_waitcnt lgkmcnt(2)
	v_cvt_pk_bf16_f32 v1, v2, v3
	s_waitcnt lgkmcnt(1)
	v_cvt_pk_bf16_f32 v2, v4, v5
	v_add_u32_e32 v4, s58, v24
	s_add_u32 s6, s56, s6
	v_ashrrev_i32_e32 v5, 31, v4
	s_addc_u32 s7, s57, 0
	v_lshlrev_b64 v[4:5], 11, v[4:5]
	v_lshl_add_u64 v[4:5], s[6:7], 0, v[4:5]
	s_lshl_b32 s24, s24, 1
	v_lshl_add_u64 v[4:5], v[4:5], 0, s[24:25]
	s_waitcnt lgkmcnt(0)
	v_cvt_pk_bf16_f32 v3, v6, v7
	v_lshl_add_u64 v[4:5], v[4:5], 0, v[8:9]
	global_store_dwordx4 v[4:5], v[0:3], off sc1

; DI unsigned pk2(float lo, float hi) { f32x2 v = {lo, hi}; bf2_t b = __builtin_convertvector(v, bf2_t); return __builtin_bit_cast(unsigned, b); }
; DI void transpose_tile(bf16_t* dst, int dst_ld, int n0, int nvalid, int nwrite, const float* src, int src_ld, int col0, int k0,
;                        const float* gain, float* ldsf, int tid) {
;     ...
;         for (int r = 0; r < 2; ++r) {
;             const int c = tid + NT * r, kk = c >> 4, n4 = (c & 15) * 4;
;             f32x4 v = __builtin_nontemporal_load((const f32x4*)(src + (size_t)(k0 + kk) * src_ld + col0 + n4));
;             const float g = gain ? gain[k0 + kk] : 1.0f;
;             float* d = ldsf + kk * 65 + n4;
;             d[0] = v[0] * g; d[1] = v[1] * g; d[2] = v[2] * g; d[3] = v[3] * g;
;         }
;     }
;     __syncthreads();
;     const int n = tid >> 3, kc = tid & 7;
;     if (n < nwrite) {
;         u32x4 w = {0u, 0u, 0u, 0u};
;         if (n < nvalid) {
;             const float* s = ldsf + (kc * 8) * 65 + n;
;             w[0] = pk2(s[0], s[65]); w[1] = pk2(s[130], s[195]); w[2] = pk2(s[260], s[325]); w[3] = pk2(s[390], s[455]);
;         }
;         *(u32x4*)(dst + (size_t)(n0 + n) * dst_ld + k0 + kc * 8) = w;
;     }
; DI void weight_tile(const Params& p, int id, float* ldsf, int tid) {
;     ...
;     else if (id < WJ10) { const int j = id - WJ9; const int nt = j >> 1; const int col0 = nt < 16 ? nt * 128 : (nt - 16) * 128 + 64;
;         transpose_tile((bf16_t*)(ws + OFF_WUKV), 128, nt * 64, 64, 64, p.w_ukv, 2048, col0, (j & 1) * 64, p.kvn_g, ldsf, tid); }
.LBB0_84:
	s_waitcnt vmcnt(0)
	v_pk_mul_f32 v[0:1], v[4:5], v[18:19] op_sel_hi:[1,0]
	ds_write2_b32 v28, v0, v1 offset1:1
	v_pk_mul_f32 v[0:1], v[6:7], v[18:19] op_sel_hi:[1,0]
	ds_write2_b32 v29, v0, v1 offset1:1
	s_waitcnt lgkmcnt(0)
	s_barrier
	s_and_saveexec_b64 s[6:7], s[4:5]
	s_cbranch_execz .LBB0_86
	ds_read2_b32 v[0:1], v30 offset1:65
	ds_read2_b32 v[2:3], v30 offset0:130 offset1:195
	ds_read2_b32 v[4:5], v31 offset0:4 offset1:69
	ds_read2_b32 v[6:7], v31 offset0:134 offset1:199
	s_lshl_b32 s24, s24, 1
	s_waitcnt lgkmcnt(3)
	v_cvt_pk_bf16_f32 v0, v0, v1
	s_waitcnt lgkmcnt(2)
	v_cvt_pk_bf16_f32 v1, v2, v3
	s_waitcnt lgkmcnt(1)
	v_cvt_pk_bf16_f32 v2, v4, v5
	v_lshl_add_u32 v4, s44, 6, v24
	v_ashrrev_i32_e32 v5, 31, v4
	v_lshlrev_b64 v[4:5], 8, v[4:5]
	v_lshl_add_u64 v[4:5], s[34:35], 0, v[4:5]
	v_lshl_add_u64 v[4:5], v[4:5], 0, s[24:25]
	s_waitcnt lgkmcnt(0)
	v_cvt_pk_bf16_f32 v3, v6, v7
	v_lshl_add_u64 v[4:5], v[4:5], 0, v[8:9]
	global_store_dwordx4 v[4:5], v[0:3], off sc1

; DI unsigned pk2(float lo, float hi) { f32x2 v = {lo, hi}; bf2_t b = __builtin_convertvector(v, bf2_t); return __builtin_bit_cast(unsigned, b); }
; DI void transpose_tile(bf16_t* dst, int dst_ld, int n0, int nvalid, int nwrite, const float* src, int src_ld, int col0, int k0,
;                        const float* gain, float* ldsf, int tid) {
;     ...
;         for (int r = 0; r < 2; ++r) {
;             const int c = tid + NT * r, kk = c >> 4, n4 = (c & 15) * 4;
;             f32x4 v = __builtin_nontemporal_load((const f32x4*)(src + (size_t)(k0 + kk) * src_ld + col0 + n4));
;             const float g = gain ? gain[k0 + kk] : 1.0f;
;             float* d = ldsf + kk * 65 + n4;
;             d[0] = v[0] * g; d[1] = v[1] * g; d[2] = v[2] * g; d[3] = v[3] * g;
;         }
;     }
;     __syncthreads();
;     const int n = tid >> 3, kc = tid & 7;
;     if (n < nwrite) {
;         u32x4 w = {0u, 0u, 0u, 0u};
;         if (n < nvalid) {
;             const float* s = ldsf + (kc * 8) * 65 + n;
;             w[0] = pk2(s[0], s[65]); w[1] = pk2(s[130], s[195]); w[2] = pk2(s[260], s[325]); w[3] = pk2(s[390], s[455]);
;         }
;         *(u32x4*)(dst + (size_t)(n0 + n) * dst_ld + k0 + kc * 8) = w;
;     }
; DI void weight_tile(const Params& p, int id, float* ldsf, int tid) {
;     ...
;     else if (id < WJ9) { const int j = id - WJ8; transpose_tile((bf16_t*)(ws + OFF_WUQ), 256, (j >> 2) * 64, 64, 64, p.w_uq, 1536, (j >> 2) * 64, (j & 3) * 64, p.qn_g, ldsf, tid); }
.LBB0_92:
	s_waitcnt vmcnt(0)
	v_pk_mul_f32 v[0:1], v[4:5], v[18:19] op_sel_hi:[1,0]
	ds_write2_b32 v28, v0, v1 offset1:1
	v_pk_mul_f32 v[0:1], v[6:7], v[18:19] op_sel_hi:[1,0]
	ds_write2_b32 v29, v0, v1 offset1:1
	s_waitcnt lgkmcnt(0)
	s_barrier
	s_and_saveexec_b64 s[6:7], s[4:5]
	s_cbranch_execz .LBB0_94
	ds_read2_b32 v[0:1], v30 offset1:65
	ds_read2_b32 v[2:3], v30 offset0:130 offset1:195
	ds_read2_b32 v[4:5], v31 offset0:4 offset1:69
	ds_read2_b32 v[6:7], v31 offset0:134 offset1:199
	s_waitcnt lgkmcnt(3)
	v_cvt_pk_bf16_f32 v0, v0, v1
	s_waitcnt lgkmcnt(2)
	v_cvt_pk_bf16_f32 v1, v2, v3
	s_waitcnt lgkmcnt(1)
	v_cvt_pk_bf16_f32 v2, v4, v5
	v_add_u32_e32 v4, s24, v24
	v_ashrrev_i32_e32 v5, 31, v4
	v_lshlrev_b64 v[4:5], 9, v[4:5]
	v_lshl_add_u64 v[4:5], s[36:37], 0, v[4:5]
	s_lshl_b32 s24, s44, 1
	v_lshl_add_u64 v[4:5], v[4:5], 0, s[24:25]
	s_waitcnt lgkmcnt(0)
	v_cvt_pk_bf16_f32 v3, v6, v7
	v_lshl_add_u64 v[4:5], v[4:5], 0, v[8:9]
	global_store_dwordx4 v[4:5], v[0:3], off sc1

; DI unsigned pk2(float lo, float hi) { f32x2 v = {lo, hi}; bf2_t b = __builtin_convertvector(v, bf2_t); return __builtin_bit_cast(unsigned, b); }
; DI void transpose_tile(bf16_t* dst, int dst_ld, int n0, int nvalid, int nwrite, const float* src, int src_ld, int col0, int k0,
;                        const float* gain, float* ldsf, int tid) {
;     ...
;         for (int r = 0; r < 2; ++r) {
;             const int c = tid + NT * r, kk = c >> 4, n4 = (c & 15) * 4;
;             f32x4 v = __builtin_nontemporal_load((const f32x4*)(src + (size_t)(k0 + kk) * src_ld + col0 + n4));
;             const float g = gain ? gain[k0 + kk] : 1.0f;
;             float* d = ldsf + kk * 65 + n4;
;             d[0] = v[0] * g; d[1] = v[1] * g; d[2] = v[2] * g; d[3] = v[3] * g;
;         }
;     }
;     __syncthreads();
;     const int n = tid >> 3, kc = tid & 7;
;     if (n < nwrite) {
;         u32x4 w = {0u, 0u, 0u, 0u};
;         if (n < nvalid) {
;             const float* s = ldsf + (kc * 8) * 65 + n;
;             w[0] = pk2(s[0], s[65]); w[1] = pk2(s[130], s[195]); w[2] = pk2(s[260], s[325]); w[3] = pk2(s[390], s[455]);
;         }
;         *(u32x4*)(dst + (size_t)(n0 + n) * dst_ld + k0 + kc * 8) = w;
;     }
; DI void weight_tile(const Params& p, int id, float* ldsf, int tid) {
;     ...
;     else if (id < WJ8) { const int j = id - WJ7; transpose_tile(wg, 1024, (j >> 4) * 64, 64, 64, p.w_in, 7600, 5552 + (j >> 4) * 64, (j & 15) * 64, p.pre_g, ldsf, tid); }
.LBB0_101:
	s_waitcnt vmcnt(0)
	v_pk_mul_f32 v[0:1], v[4:5], v[18:19] op_sel_hi:[1,0]
	ds_write2_b32 v28, v0, v1 offset1:1
	v_pk_mul_f32 v[0:1], v[6:7], v[18:19] op_sel_hi:[1,0]
	ds_write2_b32 v29, v0, v1 offset1:1
	s_waitcnt lgkmcnt(0)
	s_barrier
	s_and_saveexec_b64 s[6:7], s[4:5]
	s_cbranch_execz .LBB0_103
	ds_read2_b32 v[0:1], v30 offset1:65
	ds_read2_b32 v[2:3], v30 offset0:130 offset1:195
	ds_read2_b32 v[4:5], v31 offset0:4 offset1:69
	ds_read2_b32 v[6:7], v31 offset0:134 offset1:199
	s_waitcnt lgkmcnt(3)
	v_cvt_pk_bf16_f32 v0, v0, v1
	s_waitcnt lgkmcnt(2)
	v_cvt_pk_bf16_f32 v1, v2, v3
	s_waitcnt lgkmcnt(1)
	v_cvt_pk_bf16_f32 v2, v4, v5
	v_add_u32_e32 v4, s24, v24
	v_ashrrev_i32_e32 v5, 31, v4
	v_lshlrev_b64 v[4:5], 11, v[4:5]
	v_lshl_add_u64 v[4:5], s[30:31], 0, v[4:5]
	s_lshl_b32 s24, s44, 1
	v_lshl_add_u64 v[4:5], v[4:5], 0, s[24:25]
	s_waitcnt lgkmcnt(0)
	v_cvt_pk_bf16_f32 v3, v6, v7
	v_lshl_add_u64 v[4:5], v[4:5], 0, v[8:9]
	global_store_dwordx4 v[4:5], v[0:3], off sc1

; DI unsigned pk2(float lo, float hi) { f32x2 v = {lo, hi}; bf2_t b = __builtin_convertvector(v, bf2_t); return __builtin_bit_cast(unsigned, b); }
; DI void transpose_tile(bf16_t* dst, int dst_ld, int n0, int nvalid, int nwrite, const float* src, int src_ld, int col0, int k0,
;                        const float* gain, float* ldsf, int tid) {
;     ...
;         for (int r = 0; r < 2; ++r) {
;             const int c = tid + NT * r, kk = c >> 4, n4 = (c & 15) * 4;
;             f32x4 v = __builtin_nontemporal_load((const f32x4*)(src + (size_t)(k0 + kk) * src_ld + col0 + n4));
;             const float g = gain ? gain[k0 + kk] : 1.0f;
;             float* d = ldsf + kk * 65 + n4;
;             d[0] = v[0] * g; d[1] = v[1] * g; d[2] = v[2] * g; d[3] = v[3] * g;
;         }
;     }
;     __syncthreads();
;     const int n = tid >> 3, kc = tid & 7;
;     if (n < nwrite) {
;         u32x4 w = {0u, 0u, 0u, 0u};
;         if (n < nvalid) {
;             const float* s = ldsf + (kc * 8) * 65 + n;
;             w[0] = pk2(s[0], s[65]); w[1] = pk2(s[130], s[195]); w[2] = pk2(s[260], s[325]); w[3] = pk2(s[390], s[455]);
;         }
;         *(u32x4*)(dst + (size_t)(n0 + n) * dst_ld + k0 + kc * 8) = w;
;     }
; DI void weight_tile(const Params& p, int id, float* ldsf, int tid) {
;     ...
;     else if (id < WJ7) { const int j = id - WJ6; transpose_tile(wz, 1024, 1024 + (j >> 4) * 64, 64, 64, p.w_in, 7600, 4528 + (j >> 4) * 64, (j & 15) * 64, p.pre_g, ldsf, tid); }
.LBB0_110:
	s_waitcnt vmcnt(0)
	v_pk_mul_f32 v[0:1], v[4:5], v[18:19] op_sel_hi:[1,0]
	ds_write2_b32 v28, v0, v1 offset1:1
	v_pk_mul_f32 v[0:1], v[6:7], v[18:19] op_sel_hi:[1,0]
	ds_write2_b32 v29, v0, v1 offset1:1
	s_waitcnt lgkmcnt(0)
	s_barrier
	s_and_saveexec_b64 s[6:7], s[4:5]
	s_cbranch_execz .LBB0_112
	ds_read2_b32 v[0:1], v30 offset1:65
	ds_read2_b32 v[2:3], v30 offset0:130 offset1:195
	ds_read2_b32 v[4:5], v31 offset0:4 offset1:69
	ds_read2_b32 v[6:7], v31 offset0:134 offset1:199
	s_waitcnt lgkmcnt(3)
	v_cvt_pk_bf16_f32 v0, v0, v1
	s_waitcnt lgkmcnt(2)
	v_cvt_pk_bf16_f32 v1, v2, v3
	s_waitcnt lgkmcnt(1)
	v_cvt_pk_bf16_f32 v2, v4, v5
	v_add_u32_e32 v4, s24, v25
	v_ashrrev_i32_e32 v5, 31, v4
	v_lshlrev_b64 v[4:5], 11, v[4:5]
	v_lshl_add_u64 v[4:5], s[28:29], 0, v[4:5]
	s_lshl_b32 s24, s44, 1
	v_lshl_add_u64 v[4:5], v[4:5], 0, s[24:25]
	s_waitcnt lgkmcnt(0)
	v_cvt_pk_bf16_f32 v3, v6, v7
	v_lshl_add_u64 v[4:5], v[4:5], 0, v[8:9]
	global_store_dwordx4 v[4:5], v[0:3], off sc1

; DI unsigned pk2(float lo, float hi) { f32x2 v = {lo, hi}; bf2_t b = __builtin_convertvector(v, bf2_t); return __builtin_bit_cast(unsigned, b); }
; DI void transpose_tile(bf16_t* dst, int dst_ld, int n0, int nvalid, int nwrite, const float* src, int src_ld, int col0, int k0,
;                        const float* gain, float* ldsf, int tid) {
;     ...
;         for (int r = 0; r < 2; ++r) {
;             const int c = tid + NT * r, kk = c >> 4, n4 = (c & 15) * 4;
;             f32x4 v = __builtin_nontemporal_load((const f32x4*)(src + (size_t)(k0 + kk) * src_ld + col0 + n4));
;             const float g = gain ? gain[k0 + kk] : 1.0f;
;             float* d = ldsf + kk * 65 + n4;
;             d[0] = v[0] * g; d[1] = v[1] * g; d[2] = v[2] * g; d[3] = v[3] * g;
;         }
;     }
;     __syncthreads();
;     const int n = tid >> 3, kc = tid & 7;
;     if (n < nwrite) {
;         u32x4 w = {0u, 0u, 0u, 0u};
;         if (n < nvalid) {
;             const float* s = ldsf + (kc * 8) * 65 + n;
;             w[0] = pk2(s[0], s[65]); w[1] = pk2(s[130], s[195]); w[2] = pk2(s[260], s[325]); w[3] = pk2(s[390], s[455]);
;         }
;         *(u32x4*)(dst + (size_t)(n0 + n) * dst_ld + k0 + kc * 8) = w;
;     }
; DI void weight_tile(const Params& p, int id, float* ldsf, int tid) {
;     ...
;     } else if (id < WJ6) { const int j = id - WJ5; transpose_tile(wz, 1024, (j >> 4) * 64, 64, 64, p.w_in, 7600, 416 + (j >> 4) * 64, (j & 15) * 64, p.pre_g, ldsf, tid); }
.LBB0_119:
	s_waitcnt vmcnt(0)
	v_pk_mul_f32 v[0:1], v[4:5], v[18:19] op_sel_hi:[1,0]
	ds_write2_b32 v28, v0, v1 offset1:1
	v_pk_mul_f32 v[0:1], v[6:7], v[18:19] op_sel_hi:[1,0]
	ds_write2_b32 v29, v0, v1 offset1:1
	s_waitcnt lgkmcnt(0)
	s_barrier
	s_and_saveexec_b64 s[6:7], s[4:5]
	s_cbranch_execz .LBB0_121
	ds_read2_b32 v[0:1], v30 offset1:65
	ds_read2_b32 v[2:3], v30 offset0:130 offset1:195
	ds_read2_b32 v[4:5], v31 offset0:4 offset1:69
	ds_read2_b32 v[6:7], v31 offset0:134 offset1:199
	s_waitcnt lgkmcnt(3)
	v_cvt_pk_bf16_f32 v0, v0, v1
	s_waitcnt lgkmcnt(2)
	v_cvt_pk_bf16_f32 v1, v2, v3
	s_waitcnt lgkmcnt(1)
	v_cvt_pk_bf16_f32 v2, v4, v5
	v_add_u32_e32 v4, s24, v24
	v_ashrrev_i32_e32 v5, 31, v4
	v_lshlrev_b64 v[4:5], 11, v[4:5]
	v_lshl_add_u64 v[4:5], s[28:29], 0, v[4:5]
	s_lshl_b32 s24, s44, 1
	v_lshl_add_u64 v[4:5], v[4:5], 0, s[24:25]
	s_waitcnt lgkmcnt(0)
	v_cvt_pk_bf16_f32 v3, v6, v7
	v_lshl_add_u64 v[4:5], v[4:5], 0, v[8:9]
	global_store_dwordx4 v[4:5], v[0:3], off sc1

; DI u32x2 pk4(float a, float b, float c, float d) { u32x2 r; r.x = pk2(a, b); r.y = pk2(c, d); return r; }
; template <int WI, int WGJ, class GetF, class FinF>
; DI void staged_rows(unsigned char* lds, int tid, GetF get, FinF fin) {
;     ...
;         for (int c = 0; c < ROWS * NCH / NT; ++c) {
;             const int idx = tid + c * NT, lr = idx / NCH, ch = idx % NCH;
;             const u32x4 v = *(const u32x4*)(lds + lr * RS + ch * 16);
;             fin((lr >> 5) * 64 + jt * 32 + (lr & 31), ch * 8, v);
; template <int MODE>
; DI void phase1(const Params& p, unsigned char* smem, int tid) {
;     ...
;             staged_rows<4, 4>(lds, te,
;                 [&](int it, int jt, int g) { const f32x4 rs = *(const f32x4*)(rstd + tt * 256 + wi * 128 + it * 32 + 8 * g + 4 * h);
;                     return pk4(acc[it][jt][4 * g] * rs[0], acc[it][jt][4 * g + 1] * rs[1], acc[it][jt][4 * g + 2] * rs[2], acc[it][jt][4 * g + 3] * rs[3]); },
;                 [&](int row, int col, u32x4 v) { const int feat = fn * 256 + row, t = tt * 256 + col;
;                     if (t < T) { const int b = t / L, l = t - b * L; __builtin_nontemporal_store(v, (u32x4*)(fvt + ((size_t)(b * NH + (feat >> 6)) * 64 + (feat & 63)) * LP + l)); } });
.LBB0_221:
	v_add_u32_e32 v64, s9, v216
	v_ashrrev_i32_e32 v65, 31, v64
	v_lshrrev_b32_e32 v65, 27, v65
	v_add_u32_e32 v66, v64, v65
	v_and_b32_e32 v65, 0xffffffe0, v66
	v_sub_u32_e32 v65, v64, v65
	v_lshl_add_u32 v64, v65, 3, s10
	v_cmp_gt_i32_e32 vcc, s51, v64
	s_and_saveexec_b64 s[12:13], vcc
	s_cbranch_execz .LBB0_220
	v_ashrrev_i32_e32 v72, 5, v66
	v_lshlrev_b32_e32 v66, 1, v72
	v_and_b32_e32 v70, 0xffffffc0, v66
	v_mul_lo_u32 v66, v72, s50
	v_lshlrev_b32_e32 v65, 4, v65
	v_add3_u32 v65, 0, v66, v65
	ds_read_b128 v[66:69], v65 offset:2048
	v_add_u32_e32 v65, s5, v70
	v_mul_hi_i32 v70, v64, s64
	v_lshrrev_b32_e32 v71, 31, v70
	v_ashrrev_i32_e32 v70, 11, v70
	v_add_u32_e32 v70, v70, v71
	v_ashrrev_i32_e32 v65, 6, v65
	v_mad_i32_i24 v64, v70, s65, v64
	v_lshl_add_u32 v70, v70, 4, v65
	v_ashrrev_i32_e32 v71, 31, v70
	v_lshlrev_b64 v[70:71], 6, v[70:71]
	v_and_or_b32 v65, v72, 31, v70
	v_mov_b64_e32 v[72:73], s[42:43]
	v_mad_u64_u32 v[72:73], s[14:15], v65, s52, v[72:73]
	v_mad_i32_i24 v73, v71, s52, v73
	v_ashrrev_i32_e32 v65, 31, v64
	v_lshl_add_u64 v[64:65], v[64:65], 1, v[72:73]
	s_waitcnt lgkmcnt(0)
	global_store_dwordx4 v[64:65], v[66:69], off nt sc1
	s_branch .LBB0_220

; DI u32x2 pk4(float a, float b, float c, float d) { u32x2 r; r.x = pk2(a, b); r.y = pk2(c, d); return r; }
; template <int WI, int WGJ, class GetF, class FinF>
; DI void staged_rows(unsigned char* lds, int tid, GetF get, FinF fin) {
;     ...
;         for (int c = 0; c < ROWS * NCH / NT; ++c) {
;             const int idx = tid + c * NT, lr = idx / NCH, ch = idx % NCH;
;             const u32x4 v = *(const u32x4*)(lds + lr * RS + ch * 16);
;             fin((lr >> 5) * 64 + jt * 32 + (lr & 31), ch * 8, v);
; template <int MODE>
; DI void phase1(const Params& p, unsigned char* smem, int tid) {
;     ...
;             staged_rows<4, 4>(lds, te,
;                 [&](int it, int jt, int g) { const f32x4 rs = *(const f32x4*)(rstd + tt * 256 + wi * 128 + it * 32 + 8 * g + 4 * h);
;                     return pk4(acc[it][jt][4 * g] * rs[0], acc[it][jt][4 * g + 1] * rs[1], acc[it][jt][4 * g + 2] * rs[2], acc[it][jt][4 * g + 3] * rs[3]); },
;                 [&](int row, int col, u32x4 v) { const int feat = fn * 256 + row, t = tt * 256 + col;
;                     if (t < T) { const int b = t / L, l = t - b * L; __builtin_nontemporal_store(v, (u32x4*)(fvt + ((size_t)(b * NH + (feat >> 6)) * 64 + (feat & 63)) * LP + l)); } });
.LBB0_225:
	v_add_u32_e32 v0, s11, v216
	v_ashrrev_i32_e32 v1, 31, v0
	v_lshrrev_b32_e32 v1, 27, v1
	v_add_u32_e32 v2, v0, v1
	v_and_b32_e32 v1, 0xffffffe0, v2
	v_sub_u32_e32 v1, v0, v1
	v_lshl_add_u32 v0, v1, 3, s10
	v_cmp_gt_i32_e32 vcc, s51, v0
	s_and_saveexec_b64 s[8:9], vcc
	s_cbranch_execz .LBB0_224
	v_ashrrev_i32_e32 v2, 5, v2
	v_lshlrev_b32_e32 v3, 1, v2
	v_and_b32_e32 v8, 31, v2
	v_mul_lo_u32 v2, v2, s50
	v_lshlrev_b32_e32 v1, 4, v1
	v_and_b32_e32 v6, 0xffffffc0, v3
	v_add3_u32 v1, 0, v2, v1
	ds_read_b128 v[2:5], v1 offset:2048
	v_add_u32_e32 v1, s5, v6
	v_mul_hi_i32 v6, v0, s64
	v_lshrrev_b32_e32 v7, 31, v6
	v_ashrrev_i32_e32 v6, 11, v6
	v_add_u32_e32 v6, v6, v7
	v_ashrrev_i32_e32 v1, 6, v1
	v_mad_i32_i24 v0, v6, s65, v0
	v_lshl_add_u32 v6, v6, 4, v1
	v_ashrrev_i32_e32 v7, 31, v6
	v_lshlrev_b64 v[6:7], 6, v[6:7]
	v_or3_b32 v1, v8, v6, 32
	v_mov_b64_e32 v[8:9], s[42:43]
	v_mad_u64_u32 v[8:9], s[12:13], v1, s52, v[8:9]
	v_mad_i32_i24 v9, v7, s52, v9
	v_ashrrev_i32_e32 v1, 31, v0
	v_lshl_add_u64 v[0:1], v[0:1], 1, v[8:9]
	s_waitcnt lgkmcnt(0)
	global_store_dwordx4 v[0:1], v[2:5], off nt sc1
	s_branch .LBB0_224

; template <int MODE>
; DI void phase1(const Params& p, unsigned char* smem, int tid) {
;     ...
;                     } else if (fb == 3456) {
;                         float* dst = (float*)(ob + OUT_KPE) + (size_t)t * 32;
; #pragma unroll
;                         for (int g = 0; g < 4; ++g)
;                             *(f32x4*)(dst + 8 * g + 4 * h) = (f32x4){acc[it][jt][4 * g] * rs, acc[it][jt][4 * g + 1] * rs, acc[it][jt][4 * g + 2] * rs, acc[it][jt][4 * g + 3] * rs};
.LBB0_235:
	s_or_b64 exec, exec, s[10:11]
	v_ashrrev_i32_e32 v130, 1, v195
	v_and_b32_e32 v130, 0xffffff80, v130
	v_readlane_b32 s8, v247, 9
	v_add_u32_e32 v208, s88, v130
	v_lshlrev_b32_e32 v130, 4, v197
	v_mov_b32_e32 v131, v209
	v_readlane_b32 s9, v247, 10
	s_nop 1
	v_lshl_add_u64 v[130:131], s[8:9], 0, v[130:131]
	s_movk_i32 s8, 0xd7f
	v_cmp_lt_i32_e64 s[8:9], s8, v208
	s_and_saveexec_b64 s[10:11], s[8:9]
	s_xor_b64 s[10:11], exec, s[10:11]
	s_cbranch_execz .LBB0_239
	v_cmp_eq_u32_e32 vcc, s53, v208
	s_and_saveexec_b64 s[12:13], vcc
	s_cbranch_execz .LBB0_238
	v_lshlrev_b64 v[132:133], 7, v[128:129]
	v_lshl_add_u64 v[132:133], v[130:131], 0, v[132:133]
	s_waitcnt vmcnt(0)
	v_pk_mul_f32 v[136:137], v[112:113], v[134:135] op_sel_hi:[1,0]
	v_pk_mul_f32 v[138:139], v[114:115], v[134:135] op_sel_hi:[1,0]
	global_store_dwordx4 v[132:133], v[136:139], off sc1
	s_nop 1
	v_pk_mul_f32 v[136:137], v[116:117], v[134:135] op_sel_hi:[1,0]
	v_pk_mul_f32 v[138:139], v[118:119], v[134:135] op_sel_hi:[1,0]
	global_store_dwordx4 v[132:133], v[136:139], off offset:32 sc1
	s_nop 1
	v_pk_mul_f32 v[136:137], v[120:121], v[134:135] op_sel_hi:[1,0]
	v_pk_mul_f32 v[138:139], v[122:123], v[134:135] op_sel_hi:[1,0]
	global_store_dwordx4 v[132:133], v[136:139], off offset:64 sc1
	s_nop 1
	v_pk_mul_f32 v[136:137], v[124:125], v[134:135] op_sel_hi:[1,0]
	v_pk_mul_f32 v[138:139], v[126:127], v[134:135] op_sel_hi:[1,0]
	global_store_dwordx4 v[132:133], v[136:139], off offset:96 sc1

; template <int MODE>
; DI void phase1(const Params& p, unsigned char* smem, int tid) {
;     ...
;                     } else if (fb == 3488) {
;                         float* dst = (float*)(ws + OFF_FLOGIT) + (size_t)t * 16;
; #pragma unroll
;                         for (int g = 0; g < 2; ++g)
;                             *(f32x4*)(dst + 8 * g + 4 * h) = (f32x4){acc[it][jt][4 * g] * rs, acc[it][jt][4 * g + 1] * rs, acc[it][jt][4 * g + 2] * rs, acc[it][jt][4 * g + 3] * rs};
.LBB0_253:
	s_or_b64 exec, exec, s[10:11]
	v_lshlrev_b32_e32 v132, 2, v135
	v_mov_b32_e32 v133, v209
	v_or_b32_e32 v145, 32, v208
	s_movk_i32 s10, 0xd7f
	v_lshl_add_u64 v[132:133], s[62:63], 0, v[132:133]
	v_cmp_lt_i32_e64 s[10:11], s10, v145
	s_and_saveexec_b64 s[12:13], s[10:11]
	s_xor_b64 s[12:13], exec, s[12:13]
	s_cbranch_execz .LBB0_257
	v_cmp_eq_u32_e32 vcc, s53, v208
	s_and_saveexec_b64 s[14:15], vcc
	s_cbranch_execz .LBB0_256
	v_lshlrev_b64 v[142:143], 6, v[128:129]
	v_lshl_add_u64 v[142:143], v[132:133], 0, v[142:143]
	v_pk_mul_f32 v[150:151], v[96:97], v[134:135] op_sel_hi:[1,0]
	v_pk_mul_f32 v[152:153], v[98:99], v[134:135] op_sel_hi:[1,0]
	global_store_dwordx4 v[142:143], v[150:153], off sc1
	s_nop 1
	v_pk_mul_f32 v[150:151], v[100:101], v[134:135] op_sel_hi:[1,0]
	v_pk_mul_f32 v[152:153], v[102:103], v[134:135] op_sel_hi:[1,0]
	global_store_dwordx4 v[142:143], v[150:153], off offset:32 sc1

; template <int MODE>
; DI void phase1(const Params& p, unsigned char* smem, int tid) {
;     ...
;                     } else if (fb == 3456) {
;                         float* dst = (float*)(ob + OUT_KPE) + (size_t)t * 32;
; #pragma unroll
;                         for (int g = 0; g < 4; ++g)
;                             *(f32x4*)(dst + 8 * g + 4 * h) = (f32x4){acc[it][jt][4 * g] * rs, acc[it][jt][4 * g + 1] * rs, acc[it][jt][4 * g + 2] * rs, acc[it][jt][4 * g + 3] * rs};
.LBB0_302:
	s_or_b64 exec, exec, s[94:95]
	s_and_saveexec_b64 s[4:5], s[8:9]
	s_xor_b64 s[4:5], exec, s[4:5]
	s_cbranch_execz .LBB0_306
	v_cmp_eq_u32_e32 vcc, s53, v208
	s_and_saveexec_b64 s[6:7], vcc
	s_cbranch_execz .LBB0_305
	v_lshlrev_b64 v[136:137], 7, v[140:141]
	v_lshl_add_u64 v[130:131], v[130:131], 0, v[136:137]
	s_waitcnt vmcnt(0)
	v_pk_mul_f32 v[136:137], v[48:49], v[134:135] op_sel_hi:[1,0]
	v_pk_mul_f32 v[138:139], v[50:51], v[134:135] op_sel_hi:[1,0]
	global_store_dwordx4 v[130:131], v[136:139], off sc1
	s_nop 1
	v_pk_mul_f32 v[136:137], v[52:53], v[134:135] op_sel_hi:[1,0]
	v_pk_mul_f32 v[138:139], v[54:55], v[134:135] op_sel_hi:[1,0]
	global_store_dwordx4 v[130:131], v[136:139], off offset:32 sc1
	s_nop 1
	v_pk_mul_f32 v[136:137], v[56:57], v[134:135] op_sel_hi:[1,0]
	v_pk_mul_f32 v[138:139], v[58:59], v[134:135] op_sel_hi:[1,0]
	global_store_dwordx4 v[130:131], v[136:139], off offset:64 sc1
	s_nop 1
	v_pk_mul_f32 v[136:137], v[60:61], v[134:135] op_sel_hi:[1,0]
	v_pk_mul_f32 v[138:139], v[62:63], v[134:135] op_sel_hi:[1,0]
	global_store_dwordx4 v[130:131], v[136:139], off offset:96 sc1

; template <int MODE>
; DI void phase1(const Params& p, unsigned char* smem, int tid) {
;     ...
;                     } else if (fb == 3488) {
;                         float* dst = (float*)(ws + OFF_FLOGIT) + (size_t)t * 16;
; #pragma unroll
;                         for (int g = 0; g < 2; ++g)
;                             *(f32x4*)(dst + 8 * g + 4 * h) = (f32x4){acc[it][jt][4 * g] * rs, acc[it][jt][4 * g + 1] * rs, acc[it][jt][4 * g + 2] * rs, acc[it][jt][4 * g + 3] * rs};
.LBB0_336:
	v_cmp_eq_u32_e32 vcc, s53, v208
	s_and_saveexec_b64 s[6:7], vcc
	s_cbranch_execz .LBB0_338
	v_lshlrev_b64 v[140:141], 6, v[140:141]
	v_lshl_add_u64 v[132:133], v[132:133], 0, v[140:141]
	v_pk_mul_f32 v[140:141], v[32:33], v[134:135] op_sel_hi:[1,0]
	v_pk_mul_f32 v[142:143], v[34:35], v[134:135] op_sel_hi:[1,0]
	global_store_dwordx4 v[132:133], v[140:143], off sc1
	s_nop 1
	v_pk_mul_f32 v[140:141], v[36:37], v[134:135] op_sel_hi:[1,0]
	v_pk_mul_f32 v[142:143], v[38:39], v[134:135] op_sel_hi:[1,0]
	global_store_dwordx4 v[132:133], v[140:143], off offset:32 sc1

; DI u32x2 pk4(float a, float b, float c, float d) { u32x2 r; r.x = pk2(a, b); r.y = pk2(c, d); return r; }
; template <int WI, int WGJ, class GetF, class FinF>
; DI void staged_rows(unsigned char* lds, int tid, GetF get, FinF fin) {
;     ...
;     for (int jt = 0; jt < 2; ++jt) {
;         unsigned char* wrow = lds + (wj * 32 + ln) * RS + (wi * WI * 32 + 4 * h) * 2;
; #pragma unroll
;         for (int it = 0; it < WI; ++it)
; #pragma unroll
;             for (int g = 0; g < 4; ++g) *(u32x2*)(wrow + (it * 32 + 8 * g) * 2) = get(it, jt, g);
;         __syncthreads();
; #pragma unroll 1
;         for (int c = 0; c < ROWS * NCH / NT; ++c) {
;             const int idx = tid + c * NT, lr = idx / NCH, ch = idx % NCH;
;             const u32x4 v = *(const u32x4*)(lds + lr * RS + ch * 16);
;             fin((lr >> 5) * 64 + jt * 32 + (lr & 31), ch * 8, v);
;         }
;         __syncthreads();
; template <int MODE>
; DI void phase1(const Params& p, unsigned char* smem, int tid) {
;     ...
;                 staged_rows<4, 4>(lds, te,
;                     [&](int it, int jt, int g) { const float sc = rsj[jt]; return pk4(acc[it][jt][4 * g] * sc, acc[it][jt][4 * g + 1] * sc, acc[it][jt][4 * g + 2] * sc, acc[it][jt][4 * g + 3] * sc); },
;                     [&](int row, int col, u32x4 v) { __builtin_nontemporal_store(v, (u32x4*)(dbase + (size_t)(tt * 256 + row) * dld + col)); });
.LBB0_383:
	v_add_u32_e32 v65, s7, v195
	v_ashrrev_i32_e32 v66, 31, v65
	v_lshrrev_b32_e32 v66, 27, v66
	v_add_u32_e32 v66, v65, v66
	v_ashrrev_i32_e32 v67, 5, v66
	v_and_b32_e32 v66, 0xffffffe0, v66
	v_sub_u32_e32 v65, v65, v66
	v_mul_lo_u32 v66, v67, s50
	v_lshlrev_b32_e32 v68, 1, v67
	v_lshlrev_b32_e32 v69, 4, v65
	v_and_or_b32 v67, v67, 31, s92
	v_and_b32_e32 v68, 0xffffffc0, v68
	v_lshlrev_b32_e32 v70, 3, v65
	v_add3_u32 v65, 0, v66, v69
	v_add_u32_e32 v72, v67, v68
	ds_read_b128 v[66:69], v65 offset:2048
	v_mad_i64_i32 v[72:73], s[8:9], s6, v72, 0
	s_addk_i32 s7, 0x200
	v_ashrrev_i32_e32 v71, 31, v70
	v_lshl_add_u64 v[72:73], v[72:73], 1, s[4:5]
	s_cmpk_eq_i32 s7, 0x1000
	v_lshl_add_u64 v[70:71], v[70:71], 1, v[72:73]
	s_waitcnt lgkmcnt(0)
	global_store_dwordx4 v[70:71], v[66:69], off nt sc1
	s_cbranch_scc0 .LBB0_383
	v_pk_mul_f32 v[48:49], v[48:49], v[128:129] op_sel_hi:[1,0]
	v_pk_mul_f32 v[50:51], v[50:51], v[128:129] op_sel_hi:[1,0]
	v_pk_mul_f32 v[32:33], v[32:33], v[128:129] op_sel_hi:[1,0]
	v_pk_mul_f32 v[34:35], v[34:35], v[128:129] op_sel_hi:[1,0]
	v_pk_mul_f32 v[16:17], v[16:17], v[128:129] op_sel_hi:[1,0]
	v_pk_mul_f32 v[18:19], v[18:19], v[128:129] op_sel_hi:[1,0]
	v_pk_mul_f32 v[0:1], v[0:1], v[128:129] op_sel_hi:[1,0]
	v_pk_mul_f32 v[2:3], v[2:3], v[128:129] op_sel_hi:[1,0]
	v_cvt_pk_bf16_f32 v48, v48, v49
	v_cvt_pk_bf16_f32 v49, v50, v51
	v_pk_mul_f32 v[50:51], v[52:53], v[128:129] op_sel_hi:[1,0]
	v_pk_mul_f32 v[52:53], v[54:55], v[128:129] op_sel_hi:[1,0]
	v_cvt_pk_bf16_f32 v32, v32, v33
	v_cvt_pk_bf16_f32 v33, v34, v35
	v_pk_mul_f32 v[34:35], v[36:37], v[128:129] op_sel_hi:[1,0]
	v_pk_mul_f32 v[36:37], v[38:39], v[128:129] op_sel_hi:[1,0]
	v_cvt_pk_bf16_f32 v16, v16, v17
	v_cvt_pk_bf16_f32 v17, v18, v19
	v_pk_mul_f32 v[18:19], v[20:21], v[128:129] op_sel_hi:[1,0]
	v_pk_mul_f32 v[20:21], v[22:23], v[128:129] op_sel_hi:[1,0]
	v_cvt_pk_bf16_f32 v0, v0, v1
	v_cvt_pk_bf16_f32 v1, v2, v3
	v_pk_mul_f32 v[2:3], v[4:5], v[128:129] op_sel_hi:[1,0]
	v_pk_mul_f32 v[4:5], v[6:7], v[128:129] op_sel_hi:[1,0]
	v_cvt_pk_bf16_f32 v50, v50, v51
	v_cvt_pk_bf16_f32 v51, v52, v53
	v_cvt_pk_bf16_f32 v34, v34, v35
	v_cvt_pk_bf16_f32 v35, v36, v37
	v_cvt_pk_bf16_f32 v18, v18, v19
	v_cvt_pk_bf16_f32 v19, v20, v21
	v_cvt_pk_bf16_f32 v2, v2, v3
	v_cvt_pk_bf16_f32 v3, v4, v5
	s_barrier
	ds_write2_b64 v64, v[48:49], v[50:51] offset1:2
	v_pk_mul_f32 v[48:49], v[56:57], v[128:129] op_sel_hi:[1,0]
	v_pk_mul_f32 v[50:51], v[58:59], v[128:129] op_sel_hi:[1,0]
	ds_write2_b64 v64, v[32:33], v[34:35] offset0:8 offset1:10
	v_pk_mul_f32 v[32:33], v[40:41], v[128:129] op_sel_hi:[1,0]
	v_pk_mul_f32 v[34:35], v[42:43], v[128:129] op_sel_hi:[1,0]
	ds_write2_b64 v64, v[16:17], v[18:19] offset0:16 offset1:18
	v_pk_mul_f32 v[16:17], v[24:25], v[128:129] op_sel_hi:[1,0]
	v_pk_mul_f32 v[18:19], v[26:27], v[128:129] op_sel_hi:[1,0]
	ds_write2_b64 v64, v[0:1], v[2:3] offset0:24 offset1:26
	v_pk_mul_f32 v[0:1], v[8:9], v[128:129] op_sel_hi:[1,0]
	v_pk_mul_f32 v[2:3], v[10:11], v[128:129] op_sel_hi:[1,0]
	v_cvt_pk_bf16_f32 v48, v48, v49
	v_cvt_pk_bf16_f32 v49, v50, v51
	v_pk_mul_f32 v[50:51], v[60:61], v[128:129] op_sel_hi:[1,0]
	v_pk_mul_f32 v[52:53], v[62:63], v[128:129] op_sel_hi:[1,0]
	v_cvt_pk_bf16_f32 v32, v32, v33
	v_cvt_pk_bf16_f32 v33, v34, v35
	v_pk_mul_f32 v[34:35], v[44:45], v[128:129] op_sel_hi:[1,0]
	v_pk_mul_f32 v[36:37], v[46:47], v[128:129] op_sel_hi:[1,0]
	v_cvt_pk_bf16_f32 v16, v16, v17
	v_cvt_pk_bf16_f32 v17, v18, v19
	v_pk_mul_f32 v[18:19], v[28:29], v[128:129] op_sel_hi:[1,0]
	v_pk_mul_f32 v[20:21], v[30:31], v[128:129] op_sel_hi:[1,0]
	v_cvt_pk_bf16_f32 v0, v0, v1
	v_cvt_pk_bf16_f32 v1, v2, v3
	v_pk_mul_f32 v[2:3], v[12:13], v[128:129] op_sel_hi:[1,0]
	v_pk_mul_f32 v[4:5], v[14:15], v[128:129] op_sel_hi:[1,0]
	v_cvt_pk_bf16_f32 v50, v50, v51
	v_cvt_pk_bf16_f32 v51, v52, v53
	v_cvt_pk_bf16_f32 v34, v34, v35
	v_cvt_pk_bf16_f32 v35, v36, v37
	v_cvt_pk_bf16_f32 v18, v18, v19
	v_cvt_pk_bf16_f32 v19, v20, v21
	v_cvt_pk_bf16_f32 v2, v2, v3
	v_cvt_pk_bf16_f32 v3, v4, v5
	s_or_b32 s7, s92, 32
	s_mov_b32 s8, 0
	ds_write2_b64 v64, v[48:49], v[50:51] offset0:4 offset1:6
	ds_write2_b64 v64, v[32:33], v[34:35] offset0:12 offset1:14
	ds_write2_b64 v64, v[16:17], v[18:19] offset0:20 offset1:22
	ds_write2_b64 v64, v[0:1], v[2:3] offset0:28 offset1:30
	s_waitcnt lgkmcnt(0)
	s_barrier
.LBB0_385:
	s_nop 0
	v_add_u32_e32 v0, s8, v195
	v_ashrrev_i32_e32 v1, 31, v0
	v_lshrrev_b32_e32 v1, 27, v1
	v_add_u32_e32 v1, v0, v1
	v_ashrrev_i32_e32 v2, 5, v1
	v_and_b32_e32 v1, 0xffffffe0, v1
	v_sub_u32_e32 v0, v0, v1
	v_mul_lo_u32 v1, v2, s50
	v_lshlrev_b32_e32 v3, 1, v2
	v_lshlrev_b32_e32 v5, 4, v0
	v_and_or_b32 v2, v2, 31, s7
	v_and_b32_e32 v3, 0xffffffc0, v3
	v_lshlrev_b32_e32 v4, 3, v0
	v_add3_u32 v0, 0, v1, v5
	v_add_u32_e32 v6, v2, v3
	ds_read_b128 v[0:3], v0 offset:2048
	v_mad_i64_i32 v[6:7], s[10:11], s6, v6, 0
	s_addk_i32 s8, 0x200
	v_ashrrev_i32_e32 v5, 31, v4
	v_lshl_add_u64 v[6:7], v[6:7], 1, s[4:5]
	s_cmpk_eq_i32 s8, 0x1000
	v_lshl_add_u64 v[4:5], v[4:5], 1, v[6:7]
	s_waitcnt lgkmcnt(0)
	global_store_dwordx4 v[4:5], v[0:3], off nt sc1
	s_cbranch_scc0 .LBB0_385
	s_barrier

; DI unsigned pk2(float lo, float hi) { f32x2 v = {lo, hi}; bf2_t b = __builtin_convertvector(v, bf2_t); return __builtin_bit_cast(unsigned, b); }
; DI void transpose_tile(bf16_t* dst, int dst_ld, int n0, int nvalid, int nwrite, const float* src, int src_ld, int col0, int k0,
;                        const float* gain, float* ldsf, int tid) {
;     ...
;     if (n < nwrite) {
;         u32x4 w = {0u, 0u, 0u, 0u};
;         if (n < nvalid) {
;             const float* s = ldsf + (kc * 8) * 65 + n;
;             w[0] = pk2(s[0], s[65]); w[1] = pk2(s[130], s[195]); w[2] = pk2(s[260], s[325]); w[3] = pk2(s[390], s[455]);
;         }
;         *(u32x4*)(dst + (size_t)(n0 + n) * dst_ld + k0 + kc * 8) = w;
;     }
.LBB0_392:
	s_or_b64 exec, exec, s[8:9]
	v_add_u32_e32 v4, s10, v25
	v_ashrrev_i32_e32 v5, 31, v4
	v_lshlrev_b64 v[4:5], 11, v[4:5]
	v_lshl_add_u64 v[4:5], s[34:35], 0, v[4:5]
	s_lshl_b32 s74, s82, 1
	v_lshl_add_u64 v[4:5], v[4:5], 0, s[74:75]
	v_lshlrev_b32_e32 v208, 1, v10
	v_lshl_add_u64 v[4:5], v[4:5], 0, v[208:209]
	global_store_dwordx4 v[4:5], v[0:3], off sc1

; DI unsigned pk2(float lo, float hi) { f32x2 v = {lo, hi}; bf2_t b = __builtin_convertvector(v, bf2_t); return __builtin_bit_cast(unsigned, b); }
; DI void transpose_tile(bf16_t* dst, int dst_ld, int n0, int nvalid, int nwrite, const float* src, int src_ld, int col0, int k0,
;                        const float* gain, float* ldsf, int tid) {
;     ...
;         for (int r = 0; r < 2; ++r) {
;             const int c = tid + NT * r, kk = c >> 4, n4 = (c & 15) * 4;
;             f32x4 v = __builtin_nontemporal_load((const f32x4*)(src + (size_t)(k0 + kk) * src_ld + col0 + n4));
;             const float g = gain ? gain[k0 + kk] : 1.0f;
;             float* d = ldsf + kk * 65 + n4;
;             d[0] = v[0] * g; d[1] = v[1] * g; d[2] = v[2] * g; d[3] = v[3] * g;
;         }
;     }
;     __syncthreads();
;     const int n = tid >> 3, kc = tid & 7;
;     if (n < nwrite) {
;         u32x4 w = {0u, 0u, 0u, 0u};
;         if (n < nvalid) {
;             const float* s = ldsf + (kc * 8) * 65 + n;
;             w[0] = pk2(s[0], s[65]); w[1] = pk2(s[130], s[195]); w[2] = pk2(s[260], s[325]); w[3] = pk2(s[390], s[455]);
;         }
;         *(u32x4*)(dst + (size_t)(n0 + n) * dst_ld + k0 + kc * 8) = w;
; DI void weight_tile(const Params& p, int id, float* ldsf, int tid) {
;     ...
;     else {
;         const int j = id - WJ10; const int which = j >> 8, jj = j & 255;
;         const float* src = which == 0 ? p.w_bm : which == 1 ? p.w_bf : p.w_out;
;         bf16_t* dst = (bf16_t*)(ws + (which == 0 ? OFF_WBM : which == 1 ? OFF_WBF : OFF_WOUT));
;         transpose_tile(dst, 1024, (jj >> 4) * 64, 64, 64, src, 1024, (jj >> 4) * 64, (jj & 15) * 64, nullptr, ldsf, tid);
;     }
.LBB0_395:
	s_add_i32 s80, s15, 0x830
	s_cmpk_gt_i32 s80, 0x38f
	s_mov_b64 s[6:7], -1
	s_cbranch_scc0 .LBB0_448
	s_cmpk_gt_u32 s80, 0x48f
	s_cbranch_scc0 .LBB0_439
	s_cmpk_gt_u32 s80, 0x58f
	s_cbranch_scc0 .LBB0_430
	s_cmpk_gt_u32 s80, 0x78f
	s_cbranch_scc0 .LBB0_421
	s_cmpk_gt_u32 s80, 0x7ef
	s_cbranch_scc0 .LBB0_412
	s_cmpk_gt_u32 s80, 0x82f
	s_cbranch_scc0 .LBB0_404
	s_cmpk_lt_u32 s15, 0x100
	s_cselect_b64 s[6:7], -1, 0
	s_and_b32 s8, s15, 0xffffff00
	s_cmpk_eq_i32 s8, 0x100
	s_cselect_b64 s[8:9], -1, 0
	s_and_b64 s[10:11], s[8:9], exec
	s_movk_i32 s10, 0x58
	s_cselect_b32 s44, 0x50, s10
	s_and_b64 s[10:11], s[6:7], exec
	s_cselect_b32 s10, 0x48, s44
	s_add_u32 s10, s0, s10
	s_addc_u32 s11, s1, 0
	s_load_dwordx2 s[10:11], s[10:11], 0x0
	v_readlane_b32 s44, v247, 27
	s_add_i32 s44, s44, s69
	s_and_b32 s81, s44, 0x3c0
	s_and_b32 s74, s14, 0x3c0
	s_lshl_b32 s44, s81, 2
	s_waitcnt lgkmcnt(0)
	s_add_u32 s10, s10, s44
	v_add_u32_e32 v0, s74, v11
	s_addc_u32 s11, s11, 0
	v_lshlrev_b32_e32 v208, 2, v8
	v_ashrrev_i32_e32 v1, 31, v0
	v_lshl_add_u64 v[4:5], s[10:11], 0, v[208:209]
	v_lshlrev_b64 v[0:1], 12, v[0:1]
	v_add_u32_e32 v6, s74, v21
	v_lshl_add_u64 v[0:1], v[4:5], 0, v[0:1]
	v_ashrrev_i32_e32 v7, 31, v6
	global_load_dwordx4 v[0:3], v[0:1], off nt
	v_lshlrev_b64 v[6:7], 12, v[6:7]
	v_lshl_add_u64 v[4:5], v[4:5], 0, v[6:7]
	global_load_dwordx4 v[4:7], v[4:5], off nt
	v_add_u32_e32 v18, v9, v19
	v_add_u32_e32 v20, v9, v24
	v_add_u32_e32 v22, 0x800, v18
	v_add_u32_e32 v18, 0x808, v18
	v_add_u32_e32 v23, 0x800, v20
	v_add_u32_e32 v20, 0x808, v20
	s_waitcnt vmcnt(1)
	ds_write2_b32 v22, v0, v1 offset1:1
	ds_write2_b32 v18, v2, v3 offset1:1
	s_waitcnt vmcnt(0)
	ds_write2_b32 v23, v4, v5 offset1:1
	ds_write2_b32 v20, v6, v7 offset1:1
	s_waitcnt lgkmcnt(0)
	s_barrier
	s_and_saveexec_b64 s[10:11], s[4:5]
	s_cbranch_execz .LBB0_403
	v_add_u32_e32 v2, 0x800, v26
	ds_read2_b32 v[0:1], v2 offset1:65
	ds_read2_b32 v[2:3], v2 offset0:130 offset1:195
	v_add_u32_e32 v6, 0xc00, v26
	ds_read2_b32 v[4:5], v6 offset0:4 offset1:69
	ds_read2_b32 v[6:7], v6 offset0:134 offset1:199
	s_and_b64 s[8:9], s[8:9], exec
	s_mov_b32 s8, 0x150fc00
	s_cselect_b32 s8, s8, 0x170fc00
	s_and_b64 s[6:7], s[6:7], exec
	s_cselect_b32 s6, 0x130fc00, s8
	s_waitcnt lgkmcnt(3)
	v_cvt_pk_bf16_f32 v0, v0, v1
	s_waitcnt lgkmcnt(2)
	v_cvt_pk_bf16_f32 v1, v2, v3
	s_waitcnt lgkmcnt(1)
	v_cvt_pk_bf16_f32 v2, v4, v5
	v_add_u32_e32 v4, s81, v25
	s_add_u32 s6, s30, s6
	v_ashrrev_i32_e32 v5, 31, v4
	s_addc_u32 s7, s31, 0
	v_lshlrev_b64 v[4:5], 11, v[4:5]
	v_lshl_add_u64 v[4:5], s[6:7], 0, v[4:5]
	s_lshl_b32 s74, s74, 1
	v_lshl_add_u64 v[4:5], v[4:5], 0, s[74:75]
	v_lshlrev_b32_e32 v208, 1, v10
	s_waitcnt lgkmcnt(0)
	v_cvt_pk_bf16_f32 v3, v6, v7
	v_lshl_add_u64 v[4:5], v[4:5], 0, v[208:209]
	global_store_dwordx4 v[4:5], v[0:3], off sc1

; DI unsigned pk2(float lo, float hi) { f32x2 v = {lo, hi}; bf2_t b = __builtin_convertvector(v, bf2_t); return __builtin_bit_cast(unsigned, b); }
; DI void transpose_tile(bf16_t* dst, int dst_ld, int n0, int nvalid, int nwrite, const float* src, int src_ld, int col0, int k0,
;                        const float* gain, float* ldsf, int tid) {
;     ...
;         for (int r = 0; r < 2; ++r) {
;             const int c = tid + NT * r, kk = c >> 4, n4 = (c & 15) * 4;
;             f32x4 v = __builtin_nontemporal_load((const f32x4*)(src + (size_t)(k0 + kk) * src_ld + col0 + n4));
;             const float g = gain ? gain[k0 + kk] : 1.0f;
;             float* d = ldsf + kk * 65 + n4;
;             d[0] = v[0] * g; d[1] = v[1] * g; d[2] = v[2] * g; d[3] = v[3] * g;
;         }
;     }
;     __syncthreads();
;     const int n = tid >> 3, kc = tid & 7;
;     if (n < nwrite) {
;         u32x4 w = {0u, 0u, 0u, 0u};
;         if (n < nvalid) {
;             const float* s = ldsf + (kc * 8) * 65 + n;
;             w[0] = pk2(s[0], s[65]); w[1] = pk2(s[130], s[195]); w[2] = pk2(s[260], s[325]); w[3] = pk2(s[390], s[455]);
;         }
;         *(u32x4*)(dst + (size_t)(n0 + n) * dst_ld + k0 + kc * 8) = w;
;     }
; DI void weight_tile(const Params& p, int id, float* ldsf, int tid) {
;     ...
;     else if (id < WJ10) { const int j = id - WJ9; const int nt = j >> 1; const int col0 = nt < 16 ? nt * 128 : (nt - 16) * 128 + 64;
;         transpose_tile((bf16_t*)(ws + OFF_WUKV), 128, nt * 64, 64, 64, p.w_ukv, 2048, col0, (j & 1) * 64, p.kvn_g, ldsf, tid); }
.LBB0_409:
	v_add_u32_e32 v2, v9, v24
	s_waitcnt vmcnt(0)
	v_pk_mul_f32 v[0:1], v[4:5], v[18:19] op_sel_hi:[1,0]
	v_add_u32_e32 v3, 0x800, v2
	ds_write2_b32 v3, v0, v1 offset1:1
	v_pk_mul_f32 v[0:1], v[6:7], v[18:19] op_sel_hi:[1,0]
	v_add_u32_e32 v2, 0x808, v2
	ds_write2_b32 v2, v0, v1 offset1:1
	s_waitcnt lgkmcnt(0)
	s_barrier
	s_and_saveexec_b64 s[6:7], s[4:5]
	s_cbranch_execz .LBB0_411
	v_add_u32_e32 v2, 0x800, v26
	ds_read2_b32 v[0:1], v2 offset1:65
	ds_read2_b32 v[2:3], v2 offset0:130 offset1:195
	v_add_u32_e32 v6, 0xc00, v26
	ds_read2_b32 v[4:5], v6 offset0:4 offset1:69
	ds_read2_b32 v[6:7], v6 offset0:134 offset1:199
	v_readlane_b32 s10, v247, 21
	s_waitcnt lgkmcnt(3)
	v_cvt_pk_bf16_f32 v0, v0, v1
	s_waitcnt lgkmcnt(2)
	v_cvt_pk_bf16_f32 v1, v2, v3
	s_waitcnt lgkmcnt(1)
	v_cvt_pk_bf16_f32 v2, v4, v5
	v_lshl_add_u32 v4, s9, 6, v25
	v_ashrrev_i32_e32 v5, 31, v4
	v_lshlrev_b64 v[4:5], 8, v[4:5]
	v_readlane_b32 s11, v247, 22
	s_lshl_b32 s74, s8, 1
	v_lshlrev_b32_e32 v208, 1, v10
	v_lshl_add_u64 v[4:5], s[10:11], 0, v[4:5]
	v_lshl_add_u64 v[4:5], v[4:5], 0, s[74:75]
	s_waitcnt lgkmcnt(0)
	v_cvt_pk_bf16_f32 v3, v6, v7
	v_lshl_add_u64 v[4:5], v[4:5], 0, v[208:209]
	global_store_dwordx4 v[4:5], v[0:3], off sc1

; DI unsigned pk2(float lo, float hi) { f32x2 v = {lo, hi}; bf2_t b = __builtin_convertvector(v, bf2_t); return __builtin_bit_cast(unsigned, b); }
; DI void transpose_tile(bf16_t* dst, int dst_ld, int n0, int nvalid, int nwrite, const float* src, int src_ld, int col0, int k0,
;                        const float* gain, float* ldsf, int tid) {
;     ...
;         for (int r = 0; r < 2; ++r) {
;             const int c = tid + NT * r, kk = c >> 4, n4 = (c & 15) * 4;
;             f32x4 v = __builtin_nontemporal_load((const f32x4*)(src + (size_t)(k0 + kk) * src_ld + col0 + n4));
;             const float g = gain ? gain[k0 + kk] : 1.0f;
;             float* d = ldsf + kk * 65 + n4;
;             d[0] = v[0] * g; d[1] = v[1] * g; d[2] = v[2] * g; d[3] = v[3] * g;
;         }
;     }
;     __syncthreads();
;     const int n = tid >> 3, kc = tid & 7;
;     if (n < nwrite) {
;         u32x4 w = {0u, 0u, 0u, 0u};
;         if (n < nvalid) {
;             const float* s = ldsf + (kc * 8) * 65 + n;
;             w[0] = pk2(s[0], s[65]); w[1] = pk2(s[130], s[195]); w[2] = pk2(s[260], s[325]); w[3] = pk2(s[390], s[455]);
;         }
;         *(u32x4*)(dst + (size_t)(n0 + n) * dst_ld + k0 + kc * 8) = w;
;     }
; DI void weight_tile(const Params& p, int id, float* ldsf, int tid) {
;     ...
;     else if (id < WJ9) { const int j = id - WJ8; transpose_tile((bf16_t*)(ws + OFF_WUQ), 256, (j >> 2) * 64, 64, 64, p.w_uq, 1536, (j >> 2) * 64, (j & 3) * 64, p.qn_g, ldsf, tid); }
.LBB0_417:
	v_add_u32_e32 v2, v9, v24
	s_waitcnt vmcnt(0)
	v_pk_mul_f32 v[0:1], v[4:5], v[18:19] op_sel_hi:[1,0]
	v_add_u32_e32 v3, 0x800, v2
	ds_write2_b32 v3, v0, v1 offset1:1
	v_pk_mul_f32 v[0:1], v[6:7], v[18:19] op_sel_hi:[1,0]
	v_add_u32_e32 v2, 0x808, v2
	ds_write2_b32 v2, v0, v1 offset1:1
	s_waitcnt lgkmcnt(0)
	s_barrier
	s_and_saveexec_b64 s[6:7], s[4:5]
	s_cbranch_execz .LBB0_419
	v_add_u32_e32 v2, 0x800, v26
	ds_read2_b32 v[0:1], v2 offset1:65
	ds_read2_b32 v[2:3], v2 offset0:130 offset1:195
	v_add_u32_e32 v6, 0xc00, v26
	ds_read2_b32 v[4:5], v6 offset0:4 offset1:69
	ds_read2_b32 v[6:7], v6 offset0:134 offset1:199
	v_readlane_b32 s10, v247, 25
	s_waitcnt lgkmcnt(3)
	v_cvt_pk_bf16_f32 v0, v0, v1
	s_waitcnt lgkmcnt(2)
	v_cvt_pk_bf16_f32 v1, v2, v3
	s_waitcnt lgkmcnt(1)
	v_cvt_pk_bf16_f32 v2, v4, v5
	v_add_u32_e32 v4, s74, v25
	v_ashrrev_i32_e32 v5, 31, v4
	v_lshlrev_b64 v[4:5], 9, v[4:5]
	v_readlane_b32 s11, v247, 26
	s_lshl_b32 s74, s8, 1
	v_lshlrev_b32_e32 v208, 1, v10
	v_lshl_add_u64 v[4:5], s[10:11], 0, v[4:5]
	v_lshl_add_u64 v[4:5], v[4:5], 0, s[74:75]
	s_waitcnt lgkmcnt(0)
	v_cvt_pk_bf16_f32 v3, v6, v7
	v_lshl_add_u64 v[4:5], v[4:5], 0, v[208:209]
	global_store_dwordx4 v[4:5], v[0:3], off sc1

; DI unsigned pk2(float lo, float hi) { f32x2 v = {lo, hi}; bf2_t b = __builtin_convertvector(v, bf2_t); return __builtin_bit_cast(unsigned, b); }
; DI void transpose_tile(bf16_t* dst, int dst_ld, int n0, int nvalid, int nwrite, const float* src, int src_ld, int col0, int k0,
;                        const float* gain, float* ldsf, int tid) {
;     ...
;         for (int r = 0; r < 2; ++r) {
;             const int c = tid + NT * r, kk = c >> 4, n4 = (c & 15) * 4;
;             f32x4 v = __builtin_nontemporal_load((const f32x4*)(src + (size_t)(k0 + kk) * src_ld + col0 + n4));
;             const float g = gain ? gain[k0 + kk] : 1.0f;
;             float* d = ldsf + kk * 65 + n4;
;             d[0] = v[0] * g; d[1] = v[1] * g; d[2] = v[2] * g; d[3] = v[3] * g;
;         }
;     }
;     __syncthreads();
;     const int n = tid >> 3, kc = tid & 7;
;     if (n < nwrite) {
;         u32x4 w = {0u, 0u, 0u, 0u};
;         if (n < nvalid) {
;             const float* s = ldsf + (kc * 8) * 65 + n;
;             w[0] = pk2(s[0], s[65]); w[1] = pk2(s[130], s[195]); w[2] = pk2(s[260], s[325]); w[3] = pk2(s[390], s[455]);
;         }
;         *(u32x4*)(dst + (size_t)(n0 + n) * dst_ld + k0 + kc * 8) = w;
;     }
; DI void weight_tile(const Params& p, int id, float* ldsf, int tid) {
;     ...
;     else if (id < WJ8) { const int j = id - WJ7; transpose_tile(wg, 1024, (j >> 4) * 64, 64, 64, p.w_in, 7600, 5552 + (j >> 4) * 64, (j & 15) * 64, p.pre_g, ldsf, tid); }
.LBB0_426:
	v_add_u32_e32 v2, v9, v24
	s_waitcnt vmcnt(0)
	v_pk_mul_f32 v[0:1], v[4:5], v[18:19] op_sel_hi:[1,0]
	v_add_u32_e32 v3, 0x800, v2
	ds_write2_b32 v3, v0, v1 offset1:1
	v_pk_mul_f32 v[0:1], v[6:7], v[18:19] op_sel_hi:[1,0]
	v_add_u32_e32 v2, 0x808, v2
	ds_write2_b32 v2, v0, v1 offset1:1
	s_waitcnt lgkmcnt(0)
	s_barrier
	s_and_saveexec_b64 s[6:7], s[4:5]
	s_cbranch_execz .LBB0_428
	v_add_u32_e32 v2, 0x800, v26
	ds_read2_b32 v[0:1], v2 offset1:65
	ds_read2_b32 v[2:3], v2 offset0:130 offset1:195
	v_add_u32_e32 v6, 0xc00, v26
	ds_read2_b32 v[4:5], v6 offset0:4 offset1:69
	ds_read2_b32 v[6:7], v6 offset0:134 offset1:199
	v_readlane_b32 s10, v247, 19
	s_waitcnt lgkmcnt(3)
	v_cvt_pk_bf16_f32 v0, v0, v1
	s_waitcnt lgkmcnt(2)
	v_cvt_pk_bf16_f32 v1, v2, v3
	s_waitcnt lgkmcnt(1)
	v_cvt_pk_bf16_f32 v2, v4, v5
	v_add_u32_e32 v4, s74, v25
	v_ashrrev_i32_e32 v5, 31, v4
	v_lshlrev_b64 v[4:5], 11, v[4:5]
	v_readlane_b32 s11, v247, 20
	s_lshl_b32 s74, s8, 1
	v_lshlrev_b32_e32 v208, 1, v10
	v_lshl_add_u64 v[4:5], s[10:11], 0, v[4:5]
	v_lshl_add_u64 v[4:5], v[4:5], 0, s[74:75]
	s_waitcnt lgkmcnt(0)
	v_cvt_pk_bf16_f32 v3, v6, v7
	v_lshl_add_u64 v[4:5], v[4:5], 0, v[208:209]
	global_store_dwordx4 v[4:5], v[0:3], off sc1

; DI unsigned pk2(float lo, float hi) { f32x2 v = {lo, hi}; bf2_t b = __builtin_convertvector(v, bf2_t); return __builtin_bit_cast(unsigned, b); }
; DI void transpose_tile(bf16_t* dst, int dst_ld, int n0, int nvalid, int nwrite, const float* src, int src_ld, int col0, int k0,
;                        const float* gain, float* ldsf, int tid) {
;     ...
;         for (int r = 0; r < 2; ++r) {
;             const int c = tid + NT * r, kk = c >> 4, n4 = (c & 15) * 4;
;             f32x4 v = __builtin_nontemporal_load((const f32x4*)(src + (size_t)(k0 + kk) * src_ld + col0 + n4));
;             const float g = gain ? gain[k0 + kk] : 1.0f;
;             float* d = ldsf + kk * 65 + n4;
;             d[0] = v[0] * g; d[1] = v[1] * g; d[2] = v[2] * g; d[3] = v[3] * g;
;         }
;     }
;     __syncthreads();
;     const int n = tid >> 3, kc = tid & 7;
;     if (n < nwrite) {
;         u32x4 w = {0u, 0u, 0u, 0u};
;         if (n < nvalid) {
;             const float* s = ldsf + (kc * 8) * 65 + n;
;             w[0] = pk2(s[0], s[65]); w[1] = pk2(s[130], s[195]); w[2] = pk2(s[260], s[325]); w[3] = pk2(s[390], s[455]);
;         }
;         *(u32x4*)(dst + (size_t)(n0 + n) * dst_ld + k0 + kc * 8) = w;
;     }
; DI void weight_tile(const Params& p, int id, float* ldsf, int tid) {
;     ...
;     else if (id < WJ7) { const int j = id - WJ6; transpose_tile(wz, 1024, 1024 + (j >> 4) * 64, 64, 64, p.w_in, 7600, 4528 + (j >> 4) * 64, (j & 15) * 64, p.pre_g, ldsf, tid); }
.LBB0_435:
	v_add_u32_e32 v2, v9, v24
	s_waitcnt vmcnt(0)
	v_pk_mul_f32 v[0:1], v[4:5], v[18:19] op_sel_hi:[1,0]
	v_add_u32_e32 v3, 0x800, v2
	ds_write2_b32 v3, v0, v1 offset1:1
	v_pk_mul_f32 v[0:1], v[6:7], v[18:19] op_sel_hi:[1,0]
	v_add_u32_e32 v2, 0x808, v2
	ds_write2_b32 v2, v0, v1 offset1:1
	s_waitcnt lgkmcnt(0)
	s_barrier
	s_and_saveexec_b64 s[6:7], s[4:5]
	s_cbranch_execz .LBB0_437
	v_add_u32_e32 v2, 0x800, v26
	ds_read2_b32 v[0:1], v2 offset1:65
	ds_read2_b32 v[2:3], v2 offset0:130 offset1:195
	v_add_u32_e32 v6, 0xc00, v26
	ds_read2_b32 v[4:5], v6 offset0:4 offset1:69
	ds_read2_b32 v[6:7], v6 offset0:134 offset1:199
	v_lshlrev_b32_e32 v208, 1, v10
	s_waitcnt lgkmcnt(3)
	v_cvt_pk_bf16_f32 v0, v0, v1
	s_waitcnt lgkmcnt(2)
	v_cvt_pk_bf16_f32 v1, v2, v3
	s_waitcnt lgkmcnt(1)
	v_cvt_pk_bf16_f32 v2, v4, v5
	v_add_u32_e32 v4, s74, v27
	v_ashrrev_i32_e32 v5, 31, v4
	v_lshlrev_b64 v[4:5], 11, v[4:5]
	v_lshl_add_u64 v[4:5], s[60:61], 0, v[4:5]
	s_lshl_b32 s74, s8, 1
	v_lshl_add_u64 v[4:5], v[4:5], 0, s[74:75]
	s_waitcnt lgkmcnt(0)
	v_cvt_pk_bf16_f32 v3, v6, v7
	v_lshl_add_u64 v[4:5], v[4:5], 0, v[208:209]
	global_store_dwordx4 v[4:5], v[0:3], off sc1

; DI unsigned pk2(float lo, float hi) { f32x2 v = {lo, hi}; bf2_t b = __builtin_convertvector(v, bf2_t); return __builtin_bit_cast(unsigned, b); }
; DI void transpose_tile(bf16_t* dst, int dst_ld, int n0, int nvalid, int nwrite, const float* src, int src_ld, int col0, int k0,
;                        const float* gain, float* ldsf, int tid) {
;     ...
;         for (int r = 0; r < 2; ++r) {
;             const int c = tid + NT * r, kk = c >> 4, n4 = (c & 15) * 4;
;             f32x4 v = __builtin_nontemporal_load((const f32x4*)(src + (size_t)(k0 + kk) * src_ld + col0 + n4));
;             const float g = gain ? gain[k0 + kk] : 1.0f;
;             float* d = ldsf + kk * 65 + n4;
;             d[0] = v[0] * g; d[1] = v[1] * g; d[2] = v[2] * g; d[3] = v[3] * g;
;         }
;     }
;     __syncthreads();
;     const int n = tid >> 3, kc = tid & 7;
;     if (n < nwrite) {
;         u32x4 w = {0u, 0u, 0u, 0u};
;         if (n < nvalid) {
;             const float* s = ldsf + (kc * 8) * 65 + n;
;             w[0] = pk2(s[0], s[65]); w[1] = pk2(s[130], s[195]); w[2] = pk2(s[260], s[325]); w[3] = pk2(s[390], s[455]);
;         }
;         *(u32x4*)(dst + (size_t)(n0 + n) * dst_ld + k0 + kc * 8) = w;
;     }
; DI void weight_tile(const Params& p, int id, float* ldsf, int tid) {
;     ...
;     } else if (id < WJ6) { const int j = id - WJ5; transpose_tile(wz, 1024, (j >> 4) * 64, 64, 64, p.w_in, 7600, 416 + (j >> 4) * 64, (j & 15) * 64, p.pre_g, ldsf, tid); }
.LBB0_444:
	v_add_u32_e32 v2, v9, v24
	s_waitcnt vmcnt(0)
	v_pk_mul_f32 v[0:1], v[4:5], v[18:19] op_sel_hi:[1,0]
	v_add_u32_e32 v3, 0x800, v2
	ds_write2_b32 v3, v0, v1 offset1:1
	v_pk_mul_f32 v[0:1], v[6:7], v[18:19] op_sel_hi:[1,0]
	v_add_u32_e32 v2, 0x808, v2
	ds_write2_b32 v2, v0, v1 offset1:1
	s_waitcnt lgkmcnt(0)
	s_barrier
	s_and_saveexec_b64 s[6:7], s[4:5]
	s_cbranch_execz .LBB0_446
	v_add_u32_e32 v2, 0x800, v26
	ds_read2_b32 v[0:1], v2 offset1:65
	ds_read2_b32 v[2:3], v2 offset0:130 offset1:195
	v_add_u32_e32 v6, 0xc00, v26
	ds_read2_b32 v[4:5], v6 offset0:4 offset1:69
	ds_read2_b32 v[6:7], v6 offset0:134 offset1:199
	v_lshlrev_b32_e32 v208, 1, v10
	s_waitcnt lgkmcnt(3)
	v_cvt_pk_bf16_f32 v0, v0, v1
	s_waitcnt lgkmcnt(2)
	v_cvt_pk_bf16_f32 v1, v2, v3
	s_waitcnt lgkmcnt(1)
	v_cvt_pk_bf16_f32 v2, v4, v5
	v_add_u32_e32 v4, s74, v25
	v_ashrrev_i32_e32 v5, 31, v4
	v_lshlrev_b64 v[4:5], 11, v[4:5]
	v_lshl_add_u64 v[4:5], s[60:61], 0, v[4:5]
	s_lshl_b32 s74, s8, 1
	v_lshl_add_u64 v[4:5], v[4:5], 0, s[74:75]
	s_waitcnt lgkmcnt(0)
	v_cvt_pk_bf16_f32 v3, v6, v7
	v_lshl_add_u64 v[4:5], v[4:5], 0, v[208:209]
	global_store_dwordx4 v[4:5], v[0:3], off sc1

; DI u32x2 pk4(float a, float b, float c, float d) { u32x2 r; r.x = pk2(a, b); r.y = pk2(c, d); return r; }
; template <int WI, int WGJ, class GetF, class FinF>
; DI void staged_rows(unsigned char* lds, int tid, GetF get, FinF fin) {
;     ...
;         for (int c = 0; c < ROWS * NCH / NT; ++c) {
;             const int idx = tid + c * NT, lr = idx / NCH, ch = idx % NCH;
;             const u32x4 v = *(const u32x4*)(lds + lr * RS + ch * 16);
;             fin((lr >> 5) * 64 + jt * 32 + (lr & 31), ch * 8, v);
; DI void phase2(const Params& p, unsigned char* smem, int tid) {
;     ...
;             staged_rows<4, 4>(lds, te,
;                 [&](int it, int jt, int g) { const f32x4 rs = *(const f32x4*)((const float*)(ws + OFF_RKV) + tt * 256 + wi * 128 + it * 32 + 8 * g + 4 * h);
;                     return pk4(acc[it][jt][4 * g] * rs[0], acc[it][jt][4 * g + 1] * rs[1], acc[it][jt][4 * g + 2] * rs[2], acc[it][jt][4 * g + 3] * rs[3]); },
;                 [&](int row, int col, u32x4 v) { const int feat = fn * 256 + row, t = tt * 256 + col;
;                     if (t < T) { const int b = t / L, l = t - b * L; __builtin_nontemporal_store(v, (u32x4*)(vmt + ((size_t)(b * NH + (feat >> 6)) * 64 + (feat & 63)) * LP + l)); } });
.LBB0_556:
	v_add_u32_e32 v64, s3, v134
	v_ashrrev_i32_e32 v65, 31, v64
	v_lshrrev_b32_e32 v65, 27, v65
	v_add_u32_e32 v66, v64, v65
	v_and_b32_e32 v65, 0xffffffe0, v66
	v_sub_u32_e32 v65, v64, v65
	v_lshl_add_u32 v64, v65, 3, s4
	v_cmp_gt_i32_e32 vcc, s64, v64
	s_and_saveexec_b64 s[6:7], vcc
	s_cbranch_execz .LBB0_555
	v_ashrrev_i32_e32 v72, 5, v66
	v_mul_lo_u32 v66, v72, s80
	v_lshlrev_b32_e32 v65, 4, v65
	v_add3_u32 v65, 0, v66, v65
	v_mul_hi_i32 v70, v64, s62
	ds_read_b128 v[66:69], v65 offset:2048
	v_lshl_add_u32 v65, v72, 1, s2
	v_lshrrev_b32_e32 v71, 31, v70
	v_ashrrev_i32_e32 v70, 11, v70
	v_add_u32_e32 v70, v70, v71
	v_ashrrev_i32_e32 v65, 6, v65
	v_mad_i32_i24 v64, v70, s81, v64
	v_lshl_add_u32 v70, v70, 4, v65
	v_ashrrev_i32_e32 v71, 31, v70
	v_lshlrev_b64 v[70:71], 6, v[70:71]
	v_and_or_b32 v65, v72, 31, v70
	v_mov_b64_e32 v[72:73], s[28:29]
	v_mad_u64_u32 v[72:73], s[8:9], v65, s82, v[72:73]
	v_mad_i32_i24 v73, v71, s82, v73
	v_ashrrev_i32_e32 v65, 31, v64
	v_lshl_add_u64 v[64:65], v[64:65], 1, v[72:73]
	s_waitcnt lgkmcnt(0)
	global_store_dwordx4 v[64:65], v[66:69], off nt sc1
	s_branch .LBB0_555

; DI u32x2 pk4(float a, float b, float c, float d) { u32x2 r; r.x = pk2(a, b); r.y = pk2(c, d); return r; }
; template <int WI, int WGJ, class GetF, class FinF>
; DI void staged_rows(unsigned char* lds, int tid, GetF get, FinF fin) {
;     ...
;         for (int c = 0; c < ROWS * NCH / NT; ++c) {
;             const int idx = tid + c * NT, lr = idx / NCH, ch = idx % NCH;
;             const u32x4 v = *(const u32x4*)(lds + lr * RS + ch * 16);
;             fin((lr >> 5) * 64 + jt * 32 + (lr & 31), ch * 8, v);
; DI void phase2(const Params& p, unsigned char* smem, int tid) {
;     ...
;             staged_rows<4, 4>(lds, te,
;                 [&](int it, int jt, int g) { const f32x4 rs = *(const f32x4*)((const float*)(ws + OFF_RKV) + tt * 256 + wi * 128 + it * 32 + 8 * g + 4 * h);
;                     return pk4(acc[it][jt][4 * g] * rs[0], acc[it][jt][4 * g + 1] * rs[1], acc[it][jt][4 * g + 2] * rs[2], acc[it][jt][4 * g + 3] * rs[3]); },
;                 [&](int row, int col, u32x4 v) { const int feat = fn * 256 + row, t = tt * 256 + col;
;                     if (t < T) { const int b = t / L, l = t - b * L; __builtin_nontemporal_store(v, (u32x4*)(vmt + ((size_t)(b * NH + (feat >> 6)) * 64 + (feat & 63)) * LP + l)); } });
.LBB0_561:
	v_add_u32_e32 v0, s3, v134
	v_ashrrev_i32_e32 v1, 31, v0
	v_lshrrev_b32_e32 v1, 27, v1
	v_add_u32_e32 v2, v0, v1
	v_and_b32_e32 v1, 0xffffffe0, v2
	v_sub_u32_e32 v1, v0, v1
	v_lshl_add_u32 v0, v1, 3, s4
	v_cmp_gt_i32_e32 vcc, s64, v0
	s_and_saveexec_b64 s[6:7], vcc
	s_cbranch_execz .LBB0_560
	v_ashrrev_i32_e32 v2, 5, v2
	v_lshlrev_b32_e32 v3, 1, v2
	v_and_b32_e32 v8, 31, v2
	v_mul_lo_u32 v2, v2, s80
	v_lshlrev_b32_e32 v1, 4, v1
	v_and_b32_e32 v6, 0xffffffc0, v3
	v_add3_u32 v1, 0, v2, v1
	ds_read_b128 v[2:5], v1 offset:2048
	v_add_u32_e32 v1, s2, v6
	v_mul_hi_i32 v6, v0, s62
	v_lshrrev_b32_e32 v7, 31, v6
	v_ashrrev_i32_e32 v6, 11, v6
	v_add_u32_e32 v6, v6, v7
	v_ashrrev_i32_e32 v1, 6, v1
	v_mad_i32_i24 v0, v6, s81, v0
	v_lshl_add_u32 v6, v6, 4, v1
	v_ashrrev_i32_e32 v7, 31, v6
	v_lshlrev_b64 v[6:7], 6, v[6:7]
	v_or3_b32 v1, v8, v6, 32
	v_mov_b64_e32 v[8:9], s[28:29]
	v_mad_u64_u32 v[8:9], s[8:9], v1, s82, v[8:9]
	v_mad_i32_i24 v9, v7, s82, v9
	v_ashrrev_i32_e32 v1, 31, v0
	v_lshl_add_u64 v[0:1], v[0:1], 1, v[8:9]
	s_waitcnt lgkmcnt(0)
	global_store_dwordx4 v[0:1], v[2:5], off nt sc1
	s_branch .LBB0_560

; DI u32x2 pk4(float a, float b, float c, float d) { u32x2 r; r.x = pk2(a, b); r.y = pk2(c, d); return r; }
; template <int WI, int WGJ, class GetF, class FinF>
; DI void staged_rows(unsigned char* lds, int tid, GetF get, FinF fin) {
;     ...
;     for (int jt = 0; jt < 2; ++jt) {
;         unsigned char* wrow = lds + (wj * 32 + ln) * RS + (wi * WI * 32 + 4 * h) * 2;
; #pragma unroll
;         for (int it = 0; it < WI; ++it)
; #pragma unroll
;             for (int g = 0; g < 4; ++g) *(u32x2*)(wrow + (it * 32 + 8 * g) * 2) = get(it, jt, g);
;         __syncthreads();
; #pragma unroll 1
;         for (int c = 0; c < ROWS * NCH / NT; ++c) {
;             const int idx = tid + c * NT, lr = idx / NCH, ch = idx % NCH;
;             const u32x4 v = *(const u32x4*)(lds + lr * RS + ch * 16);
;             fin((lr >> 5) * 64 + jt * 32 + (lr & 31), ch * 8, v);
;         }
;         __syncthreads();
; DI void phase2(const Params& p, unsigned char* smem, int tid) {
;     ...
;                 staged_rows<4, 4>(lds, te,
;                     [&](int it, int jt, int g) { const float sc = rk[jt]; return pk4(acc[it][jt][4 * g] * sc, acc[it][jt][4 * g + 1] * sc, acc[it][jt][4 * g + 2] * sc, acc[it][jt][4 * g + 3] * sc); },
;                     [&](int row, int col, u32x4 v) { const int t = tt * 256 + row, ff = f * 256 + col;
;                         __builtin_nontemporal_store(v, (u32x4*)(km + (size_t)t * 1536 + (ff >> 6) * 96 + (ff & 63))); });
.LBB0_569:
	s_nop 0
	v_add_u32_e32 v64, s4, v129
	v_ashrrev_i32_e32 v65, 31, v64
	v_lshrrev_b32_e32 v65, 27, v65
	v_add_u32_e32 v65, v64, v65
	v_ashrrev_i32_e32 v66, 5, v65
	v_and_b32_e32 v65, 0xffffffe0, v65
	v_sub_u32_e32 v64, v64, v65
	v_mul_lo_u32 v65, v66, s80
	v_lshlrev_b32_e32 v67, 1, v66
	v_lshlrev_b32_e32 v70, 4, v64
	v_and_or_b32 v66, v66, 31, s3
	v_and_b32_e32 v67, 0xffffffc0, v67
	v_lshl_add_u32 v64, v64, 3, s2
	v_add3_u32 v65, 0, v65, v70
	v_add_u32_e32 v71, v66, v67
	v_ashrrev_i32_e32 v72, 6, v64
	ds_read_b128 v[64:67], v65 offset:2048
	v_mov_b64_e32 v[68:69], s[20:21]
	v_and_b32_e32 v168, 0x70, v70
	v_mul_lo_u32 v70, v72, s83
	v_mad_i64_i32 v[68:69], s[6:7], v71, s63, v[68:69]
	v_ashrrev_i32_e32 v71, 31, v70
	s_addk_i32 s4, 0x200
	v_lshl_add_u64 v[68:69], v[70:71], 1, v[68:69]
	s_cmpk_eq_i32 s4, 0x1000
	v_lshl_add_u64 v[68:69], v[68:69], 0, v[168:169]
	s_waitcnt lgkmcnt(0)
	global_store_dwordx4 v[68:69], v[64:67], off nt sc1
	s_cbranch_scc0 .LBB0_569
	s_waitcnt vmcnt(1)
	v_pk_mul_f32 v[0:1], v[0:1], v[128:129] op_sel_hi:[1,0]
	v_pk_mul_f32 v[2:3], v[2:3], v[128:129] op_sel_hi:[1,0]
	v_cvt_pk_bf16_f32 v0, v0, v1
	v_cvt_pk_bf16_f32 v1, v2, v3
	v_pk_mul_f32 v[2:3], v[4:5], v[128:129] op_sel_hi:[1,0]
	v_pk_mul_f32 v[4:5], v[6:7], v[128:129] op_sel_hi:[1,0]
	v_cvt_pk_bf16_f32 v2, v2, v3
	v_cvt_pk_bf16_f32 v3, v4, v5
	s_barrier
	ds_write2_b64 v131, v[0:1], v[2:3] offset1:2
	v_pk_mul_f32 v[0:1], v[8:9], v[128:129] op_sel_hi:[1,0]
	v_pk_mul_f32 v[2:3], v[10:11], v[128:129] op_sel_hi:[1,0]
	v_cvt_pk_bf16_f32 v0, v0, v1
	v_cvt_pk_bf16_f32 v1, v2, v3
	v_pk_mul_f32 v[2:3], v[12:13], v[128:129] op_sel_hi:[1,0]
	v_pk_mul_f32 v[4:5], v[14:15], v[128:129] op_sel_hi:[1,0]
	v_cvt_pk_bf16_f32 v2, v2, v3
	v_cvt_pk_bf16_f32 v3, v4, v5
	ds_write2_b64 v131, v[0:1], v[2:3] offset0:4 offset1:6
	v_pk_mul_f32 v[0:1], v[48:49], v[128:129] op_sel_hi:[1,0]
	v_pk_mul_f32 v[2:3], v[50:51], v[128:129] op_sel_hi:[1,0]
	v_cvt_pk_bf16_f32 v0, v0, v1
	v_cvt_pk_bf16_f32 v1, v2, v3
	v_pk_mul_f32 v[2:3], v[52:53], v[128:129] op_sel_hi:[1,0]
	v_pk_mul_f32 v[4:5], v[54:55], v[128:129] op_sel_hi:[1,0]
	v_cvt_pk_bf16_f32 v2, v2, v3
	v_cvt_pk_bf16_f32 v3, v4, v5
	ds_write2_b64 v131, v[0:1], v[2:3] offset0:8 offset1:10
	v_pk_mul_f32 v[0:1], v[56:57], v[128:129] op_sel_hi:[1,0]
	v_pk_mul_f32 v[2:3], v[58:59], v[128:129] op_sel_hi:[1,0]
	v_cvt_pk_bf16_f32 v0, v0, v1
	v_cvt_pk_bf16_f32 v1, v2, v3
	v_pk_mul_f32 v[2:3], v[60:61], v[128:129] op_sel_hi:[1,0]
	v_pk_mul_f32 v[4:5], v[62:63], v[128:129] op_sel_hi:[1,0]
	v_cvt_pk_bf16_f32 v2, v2, v3
	v_cvt_pk_bf16_f32 v3, v4, v5
	ds_write2_b64 v131, v[0:1], v[2:3] offset0:12 offset1:14
	v_pk_mul_f32 v[0:1], v[32:33], v[128:129] op_sel_hi:[1,0]
	v_pk_mul_f32 v[2:3], v[34:35], v[128:129] op_sel_hi:[1,0]
	v_cvt_pk_bf16_f32 v0, v0, v1
	v_cvt_pk_bf16_f32 v1, v2, v3
	v_pk_mul_f32 v[2:3], v[36:37], v[128:129] op_sel_hi:[1,0]
	v_pk_mul_f32 v[4:5], v[38:39], v[128:129] op_sel_hi:[1,0]
	v_cvt_pk_bf16_f32 v2, v2, v3
	v_cvt_pk_bf16_f32 v3, v4, v5
	ds_write2_b64 v131, v[0:1], v[2:3] offset0:16 offset1:18
	v_pk_mul_f32 v[0:1], v[40:41], v[128:129] op_sel_hi:[1,0]
	v_pk_mul_f32 v[2:3], v[42:43], v[128:129] op_sel_hi:[1,0]
	v_cvt_pk_bf16_f32 v0, v0, v1
	v_cvt_pk_bf16_f32 v1, v2, v3
	v_pk_mul_f32 v[2:3], v[44:45], v[128:129] op_sel_hi:[1,0]
	v_pk_mul_f32 v[4:5], v[46:47], v[128:129] op_sel_hi:[1,0]
	v_cvt_pk_bf16_f32 v2, v2, v3
	v_cvt_pk_bf16_f32 v3, v4, v5
	ds_write2_b64 v131, v[0:1], v[2:3] offset0:20 offset1:22
	v_pk_mul_f32 v[0:1], v[16:17], v[128:129] op_sel_hi:[1,0]
	v_pk_mul_f32 v[2:3], v[18:19], v[128:129] op_sel_hi:[1,0]
	v_cvt_pk_bf16_f32 v0, v0, v1
	v_cvt_pk_bf16_f32 v1, v2, v3
	v_pk_mul_f32 v[2:3], v[20:21], v[128:129] op_sel_hi:[1,0]
	v_pk_mul_f32 v[4:5], v[22:23], v[128:129] op_sel_hi:[1,0]
	v_cvt_pk_bf16_f32 v2, v2, v3
	v_cvt_pk_bf16_f32 v3, v4, v5
	ds_write2_b64 v131, v[0:1], v[2:3] offset0:24 offset1:26
	v_pk_mul_f32 v[0:1], v[24:25], v[128:129] op_sel_hi:[1,0]
	v_pk_mul_f32 v[2:3], v[26:27], v[128:129] op_sel_hi:[1,0]
	v_cvt_pk_bf16_f32 v0, v0, v1
	v_cvt_pk_bf16_f32 v1, v2, v3
	v_pk_mul_f32 v[2:3], v[28:29], v[128:129] op_sel_hi:[1,0]
	v_pk_mul_f32 v[4:5], v[30:31], v[128:129] op_sel_hi:[1,0]
	v_cvt_pk_bf16_f32 v2, v2, v3
	v_cvt_pk_bf16_f32 v3, v4, v5
	s_or_b32 s3, s3, 32
	s_mov_b32 s4, 0
	ds_write2_b64 v131, v[0:1], v[2:3] offset0:28 offset1:30
	s_waitcnt lgkmcnt(0)
	s_barrier
.LBB0_571:
	s_nop 0
	v_add_u32_e32 v0, s4, v129
	v_ashrrev_i32_e32 v1, 31, v0
	v_lshrrev_b32_e32 v1, 27, v1
	v_add_u32_e32 v1, v0, v1
	v_ashrrev_i32_e32 v2, 5, v1
	v_and_b32_e32 v1, 0xffffffe0, v1
	v_sub_u32_e32 v0, v0, v1
	v_mul_lo_u32 v1, v2, s80
	v_lshlrev_b32_e32 v3, 1, v2
	v_lshlrev_b32_e32 v6, 4, v0
	v_and_or_b32 v2, v2, 31, s3
	v_and_b32_e32 v3, 0xffffffc0, v3
	v_lshl_add_u32 v0, v0, 3, s2
	v_add3_u32 v1, 0, v1, v6
	v_add_u32_e32 v7, v2, v3
	v_ashrrev_i32_e32 v8, 6, v0
	ds_read_b128 v[0:3], v1 offset:2048
	v_mov_b64_e32 v[4:5], s[20:21]
	v_and_b32_e32 v168, 0x70, v6
	v_mul_lo_u32 v6, v8, s83
	v_mad_i64_i32 v[4:5], s[6:7], v7, s63, v[4:5]
	v_ashrrev_i32_e32 v7, 31, v6
	s_addk_i32 s4, 0x200
	v_lshl_add_u64 v[4:5], v[6:7], 1, v[4:5]
	s_cmpk_eq_i32 s4, 0x1000
	v_lshl_add_u64 v[4:5], v[4:5], 0, v[168:169]
	s_waitcnt lgkmcnt(0)
	global_store_dwordx4 v[4:5], v[0:3], off nt sc1
	s_cbranch_scc0 .LBB0_571
	s_barrier

; DI u32x2 pk4(float a, float b, float c, float d) { u32x2 r; r.x = pk2(a, b); r.y = pk2(c, d); return r; }
; DI void phase2(const Params& p, unsigned char* smem, int tid) {
;     ...
;                 staged_rows<4, 4>(lds, te,
;                     [&](int it, int jt, int g) { return pk4(acc[it][jt][4 * g], acc[it][jt][4 * g + 1], acc[it][jt][4 * g + 2], acc[it][jt][4 * g + 3]); },
;                     [&](int row, int col, u32x4 v) { const int t = tt * 256 + row, ff = f * 256 + col, blk = ff >> 5, hd = blk / 3, part = blk - hd * 3;
;                         bf16_t* d = part < 2 ? qn + (size_t)t * 1024 + hd * 64 + part * 32 + (ff & 31) : qpe + (size_t)t * 512 + hd * 32 + (ff & 31);
;                         __builtin_nontemporal_store(v, (u32x4*)d); });
.LBB0_610:
	s_or_b64 exec, exec, s[4:5]
	v_lshlrev_b32_e32 v4, 5, v12
	v_ashrrev_i32_e32 v5, 31, v4
	v_lshl_add_u64 v[4:5], v[4:5], 1, v[6:7]
	v_and_b32_e32 v6, 24, v11
	v_lshlrev_b32_e32 v168, 1, v6
	s_addk_i32 s6, 0x200
	v_lshl_add_u64 v[4:5], v[4:5], 0, v[168:169]
	s_cmpk_eq_i32 s6, 0x1000
	s_waitcnt lgkmcnt(0)
	global_store_dwordx4 v[4:5], v[0:3], off nt sc1
	s_cbranch_scc1 .LBB0_615

; DI u32x2 pk4(float a, float b, float c, float d) { u32x2 r; r.x = pk2(a, b); r.y = pk2(c, d); return r; }
; DI void phase2(const Params& p, unsigned char* smem, int tid) {
;     ...
;                 staged_rows<4, 4>(lds, te,
;                     [&](int it, int jt, int g) { return pk4(acc[it][jt][4 * g], acc[it][jt][4 * g + 1], acc[it][jt][4 * g + 2], acc[it][jt][4 * g + 3]); },
;                     [&](int row, int col, u32x4 v) { const int t = tt * 256 + row, ff = f * 256 + col, blk = ff >> 5, hd = blk / 3, part = blk - hd * 3;
;                         bf16_t* d = part < 2 ? qn + (size_t)t * 1024 + hd * 64 + part * 32 + (ff & 31) : qpe + (size_t)t * 512 + hd * 32 + (ff & 31);
;                         __builtin_nontemporal_store(v, (u32x4*)d); });
.LBB0_616:
	s_or_b64 exec, exec, s[4:5]
	v_lshlrev_b32_e32 v4, 5, v11
	v_ashrrev_i32_e32 v5, 31, v4
	v_and_b32_e32 v6, 24, v10
	v_lshl_add_u64 v[4:5], v[4:5], 1, v[8:9]
	v_lshlrev_b32_e32 v168, 1, v6
	s_addk_i32 s6, 0x200
	v_lshl_add_u64 v[4:5], v[4:5], 0, v[168:169]
	s_cmpk_eq_i32 s6, 0x1000
	s_waitcnt lgkmcnt(0)
	global_store_dwordx4 v[4:5], v[0:3], off nt sc1
	s_cbranch_scc1 .LBB0_621

; DI void phase2(const Params& p, unsigned char* smem, int tid) {
;     ...
;             float* bias = (float*)(ws + OFF_BIAS) + (size_t)(b * NH + hd) * LP;
; #pragma unroll
;             for (int i = 0; i < 9; ++i) { const int l = l0 + i; if (l < LP) bias[l] = (l < L) ? -(base + v[i]) * LOG2E : 0.f; }
.LBB0_673:
	s_or_b64 exec, exec, s[8:9]
	v_cmp_gt_i32_e64 s[6:7], s96, v188
	s_and_saveexec_b64 s[8:9], s[6:7]
	s_cbranch_execz .LBB0_536
	v_lshl_add_u64 v[16:17], v[0:1], 2, s[10:11]
	v_add_f32_e32 v0, v9, v10
	v_mul_f32_e32 v0, 0xbfb8aa3b, v0
	v_cndmask_b32_e32 v12, 0, v0, vcc
	v_add_f32_e32 v0, v8, v10
	v_mul_f32_e32 v0, 0xbfb8aa3b, v0
	v_cndmask_b32_e32 v13, 0, v0, vcc
	v_add_f32_e32 v0, v7, v10
	v_mul_f32_e32 v0, 0xbfb8aa3b, v0
	v_cndmask_b32_e32 v14, 0, v0, vcc
	v_add_f32_e32 v0, v6, v10
	v_mul_f32_e32 v0, 0xbfb8aa3b, v0
	v_cndmask_b32_e32 v15, 0, v0, vcc
	v_add_f32_e32 v0, v5, v10
	v_add_f32_e32 v1, v4, v10
	v_add_f32_e32 v2, v3, v10
	v_mul_f32_e32 v0, 0xbfb8aa3b, v0
	v_mul_f32_e32 v1, 0xbfb8aa3b, v1
	v_mul_f32_e32 v2, 0xbfb8aa3b, v2
	v_cndmask_b32_e32 v0, 0, v0, vcc
	v_cndmask_b32_e32 v1, 0, v1, vcc
	v_cndmask_b32_e64 v2, 0, v2, s[4:5]
	global_store_dwordx4 v[16:17], v[12:15], off offset:8 sc1
	global_store_dwordx3 v[16:17], v[0:2], off offset:24
	s_branch .LBB0_536

; DI u32x2 pk4(float a, float b, float c, float d) { u32x2 r; r.x = pk2(a, b); r.y = pk2(c, d); return r; }
;     ...
;     { const auto sw = __builtin_amdgcn_permlane32_swap(__float_as_uint(lsum), __float_as_uint(lsum), false, false);
;       lsum = __uint_as_float(sw[0]) + __uint_as_float(sw[1]); }
;     const float inv = 1.0f / lsum;
;     {
;         unsigned char* sb = lds + 2 * STG + wid * (32 * 144);
; #pragma unroll
;         for (int d = 0; d < 2; ++d)
; #pragma unroll
;             for (int g = 0; g < 4; ++g)
;                 *(u32x2*)(sb + ln * 144 + (d * 32 + 8 * g + 4 * h) * 2) = pk4(o[d][4 * g] * inv, o[d][4 * g + 1] * inv, o[d][4 * g + 2] * inv, o[d][4 * g + 3] * inv);
;         __builtin_amdgcn_fence(__ATOMIC_RELEASE, "wavefront");
;         __builtin_amdgcn_wave_barrier();
;         __builtin_amdgcn_fence(__ATOMIC_ACQUIRE, "wavefront");
; #pragma unroll
;         for (int ps = 0; ps < 4; ++ps) {
;             const int row = ps * 8 + (lane >> 3), ch = lane & 7;
;             const u32x4 v = *(const u32x4*)(sb + row * 144 + ch * 16);
;             *(u32x4*)(obase + (size_t)(qw0 + row) * ldo + ch * 8) = v;
;         }
.LBB0_736:
	v_add_f32_e32 v248, v248, v249
	v_add_f32_e32 v250, v250, v251
	v_add_f32_e32 v252, v252, v253
	v_add_f32_e32 v254, v254, v255
	v_add_f32_e32 v248, v248, v250
	v_add_f32_e32 v252, v252, v254
	v_add_f32_e32 v220, v248, v252
	v_mov_b32_e32 v1, v220
	s_nop 1
	v_permlane32_swap_b32_e32 v220, v1
	v_add_f32_e32 v1, v220, v1
	v_div_scale_f32 v34, s[8:9], v1, v1, 1.0
	v_rcp_f32_e32 v35, v34
	s_mov_b64 s[8:9], 0
	v_fma_f32 v36, -v34, v35, 1.0
	v_fmac_f32_e32 v35, v36, v35
	v_div_scale_f32 v36, vcc, 1.0, v1, 1.0
	v_mul_f32_e32 v37, v36, v35
	v_fma_f32 v38, -v34, v37, v36
	v_fmac_f32_e32 v37, v38, v35
	v_fma_f32 v34, -v34, v37, v36
	v_div_fmas_f32 v34, v34, v35, v37
	v_div_fixup_f32 v34, v34, v1, 1.0
	v_pk_mul_f32 v[18:19], v[18:19], v[34:35] op_sel_hi:[1,0]
	v_pk_mul_f32 v[20:21], v[20:21], v[34:35] op_sel_hi:[1,0]
	v_pk_mul_f32 v[2:3], v[2:3], v[34:35] op_sel_hi:[1,0]
	v_pk_mul_f32 v[4:5], v[4:5], v[34:35] op_sel_hi:[1,0]
	v_cvt_pk_bf16_f32 v18, v18, v19
	v_cvt_pk_bf16_f32 v19, v20, v21
	v_pk_mul_f32 v[20:21], v[22:23], v[34:35] op_sel_hi:[1,0]
	v_pk_mul_f32 v[22:23], v[24:25], v[34:35] op_sel_hi:[1,0]
	v_cvt_pk_bf16_f32 v2, v2, v3
	v_cvt_pk_bf16_f32 v3, v4, v5
	v_pk_mul_f32 v[4:5], v[6:7], v[34:35] op_sel_hi:[1,0]
	v_pk_mul_f32 v[6:7], v[8:9], v[34:35] op_sel_hi:[1,0]
	v_cvt_pk_bf16_f32 v20, v20, v21
	v_cvt_pk_bf16_f32 v21, v22, v23
	v_add_u32_e32 v1, 0xb000, v214
	v_cvt_pk_bf16_f32 v4, v4, v5
	v_cvt_pk_bf16_f32 v5, v6, v7
	ds_write2_b64 v1, v[18:19], v[20:21] offset0:192 offset1:194
	v_pk_mul_f32 v[18:19], v[26:27], v[34:35] op_sel_hi:[1,0]
	v_pk_mul_f32 v[20:21], v[28:29], v[34:35] op_sel_hi:[1,0]
	ds_write2_b64 v1, v[2:3], v[4:5] offset0:200 offset1:202
	v_pk_mul_f32 v[2:3], v[10:11], v[34:35] op_sel_hi:[1,0]
	v_pk_mul_f32 v[4:5], v[12:13], v[34:35] op_sel_hi:[1,0]
	v_cvt_pk_bf16_f32 v18, v18, v19
	v_cvt_pk_bf16_f32 v19, v20, v21
	v_pk_mul_f32 v[20:21], v[30:31], v[34:35] op_sel_hi:[1,0]
	v_pk_mul_f32 v[22:23], v[32:33], v[34:35] op_sel_hi:[1,0]
	v_cvt_pk_bf16_f32 v2, v2, v3
	v_cvt_pk_bf16_f32 v3, v4, v5
	v_pk_mul_f32 v[4:5], v[14:15], v[34:35] op_sel_hi:[1,0]
	v_pk_mul_f32 v[6:7], v[16:17], v[34:35] op_sel_hi:[1,0]
	v_cvt_pk_bf16_f32 v20, v20, v21
	v_cvt_pk_bf16_f32 v21, v22, v23
	v_cvt_pk_bf16_f32 v4, v4, v5
	v_cvt_pk_bf16_f32 v5, v6, v7
	ds_write2_b64 v1, v[18:19], v[20:21] offset0:196 offset1:198
	ds_write2_b64 v1, v[2:3], v[4:5] offset0:204 offset1:206
	ds_read_b128 v[2:5], v215 offset:46592
	v_or_b32_e32 v6, v159, v202
	v_ashrrev_i32_e32 v7, 31, v6
	v_lshlrev_b64 v[6:7], 11, v[6:7]
	v_lshl_add_u64 v[10:11], v[168:169], 0, v[6:7]
	ds_read_b128 v[6:9], v215 offset:47744
	s_waitcnt lgkmcnt(1)
	global_store_dwordx4 v[10:11], v[2:5], off sc1
	s_and_b64 vcc, exec, s[48:49]
	s_nop 0
	v_or_b32_e32 v2, v159, v188
	v_ashrrev_i32_e32 v3, 31, v2
	v_lshlrev_b64 v[2:3], 11, v[2:3]
	v_lshl_add_u64 v[2:3], v[168:169], 0, v[2:3]
	s_waitcnt lgkmcnt(0)
	global_store_dwordx4 v[2:3], v[6:9], off sc1
	ds_read_b128 v[2:5], v215 offset:48896
	s_nop 0
	v_add_u32_e32 v6, v159, v192
	v_ashrrev_i32_e32 v7, 31, v6
	v_lshlrev_b64 v[6:7], 11, v[6:7]
	v_lshl_add_u64 v[10:11], v[168:169], 0, v[6:7]
	ds_read_b128 v[6:9], v215 offset:50048
	s_waitcnt lgkmcnt(1)
	global_store_dwordx4 v[10:11], v[2:5], off sc1
	s_nop 1
	v_add_u32_e32 v2, v159, v194
	v_ashrrev_i32_e32 v3, 31, v2
	v_lshlrev_b64 v[2:3], 11, v[2:3]
	v_lshl_add_u64 v[2:3], v[168:169], 0, v[2:3]
	s_waitcnt lgkmcnt(0)
	global_store_dwordx4 v[2:3], v[6:9], off sc1
	s_cbranch_vccnz .LBB0_734

; DI u32x2 pk4(float a, float b, float c, float d) { u32x2 r; r.x = pk2(a, b); r.y = pk2(c, d); return r; }
;     ...
;     { const auto sw = __builtin_amdgcn_permlane32_swap(__float_as_uint(lsum), __float_as_uint(lsum), false, false);
;       lsum = __uint_as_float(sw[0]) + __uint_as_float(sw[1]); }
;     const float inv = 1.0f / lsum;
;     {
;         unsigned char* sb = lds + 2 * STG + wid * (32 * 144);
; #pragma unroll
;         for (int d = 0; d < 2; ++d)
; #pragma unroll
;             for (int g = 0; g < 4; ++g)
;                 *(u32x2*)(sb + ln * 144 + (d * 32 + 8 * g + 4 * h) * 2) = pk4(o[d][4 * g] * inv, o[d][4 * g + 1] * inv, o[d][4 * g + 2] * inv, o[d][4 * g + 3] * inv);
;         __builtin_amdgcn_fence(__ATOMIC_RELEASE, "wavefront");
;         __builtin_amdgcn_wave_barrier();
;         __builtin_amdgcn_fence(__ATOMIC_ACQUIRE, "wavefront");
; #pragma unroll
;         for (int ps = 0; ps < 4; ++ps) {
;             const int row = ps * 8 + (lane >> 3), ch = lane & 7;
;             const u32x4 v = *(const u32x4*)(sb + row * 144 + ch * 16);
;             *(u32x4*)(obase + (size_t)(qw0 + row) * ldo + ch * 8) = v;
;         }
.LBB0_768:
	v_mov_b32_e32 v1, v210
	s_nop 1
	v_permlane32_swap_b32_e32 v210, v1
	v_add_f32_e32 v1, v210, v1
	v_div_scale_f32 v2, s[18:19], v1, v1, 1.0
	v_rcp_f32_e32 v3, v2
	s_mov_b32 s2, s91
	v_fma_f32 v4, -v2, v3, 1.0
	v_fmac_f32_e32 v3, v4, v3
	v_div_scale_f32 v4, vcc, 1.0, v1, 1.0
	v_mul_f32_e32 v5, v4, v3
	v_fma_f32 v6, -v2, v5, v4
	v_fmac_f32_e32 v5, v6, v3
	v_fma_f32 v2, -v2, v5, v4
	v_div_fmas_f32 v2, v2, v3, v5
	v_div_fixup_f32 v2, v2, v1, 1.0
	v_pk_mul_f32 v[4:5], v[32:33], v[2:3] op_sel_hi:[1,0]
	v_pk_mul_f32 v[6:7], v[34:35], v[2:3] op_sel_hi:[1,0]
	v_cvt_pk_bf16_f32 v4, v4, v5
	v_cvt_pk_bf16_f32 v5, v6, v7
	v_add_u32_e32 v1, v174, v146
	v_pk_mul_f32 v[6:7], v[36:37], v[2:3] op_sel_hi:[1,0]
	v_pk_mul_f32 v[8:9], v[38:39], v[2:3] op_sel_hi:[1,0]
	v_cvt_pk_bf16_f32 v6, v6, v7
	v_cvt_pk_bf16_f32 v7, v8, v9
	v_add_u32_e32 v1, 0xb000, v1
	ds_write2_b64 v1, v[4:5], v[6:7] offset0:192 offset1:194
	v_pk_mul_f32 v[4:5], v[40:41], v[2:3] op_sel_hi:[1,0]
	v_pk_mul_f32 v[6:7], v[42:43], v[2:3] op_sel_hi:[1,0]
	v_cvt_pk_bf16_f32 v4, v4, v5
	v_cvt_pk_bf16_f32 v5, v6, v7
	v_pk_mul_f32 v[6:7], v[44:45], v[2:3] op_sel_hi:[1,0]
	v_pk_mul_f32 v[8:9], v[46:47], v[2:3] op_sel_hi:[1,0]
	v_cvt_pk_bf16_f32 v6, v6, v7
	v_cvt_pk_bf16_f32 v7, v8, v9
	ds_write2_b64 v1, v[4:5], v[6:7] offset0:196 offset1:198
	v_pk_mul_f32 v[4:5], v[16:17], v[2:3] op_sel_hi:[1,0]
	v_pk_mul_f32 v[6:7], v[18:19], v[2:3] op_sel_hi:[1,0]
	v_cvt_pk_bf16_f32 v4, v4, v5
	v_cvt_pk_bf16_f32 v5, v6, v7
	v_pk_mul_f32 v[6:7], v[20:21], v[2:3] op_sel_hi:[1,0]
	v_pk_mul_f32 v[8:9], v[22:23], v[2:3] op_sel_hi:[1,0]
	v_cvt_pk_bf16_f32 v6, v6, v7
	v_cvt_pk_bf16_f32 v7, v8, v9
	ds_write2_b64 v1, v[4:5], v[6:7] offset0:200 offset1:202
	v_pk_mul_f32 v[4:5], v[24:25], v[2:3] op_sel_hi:[1,0]
	v_pk_mul_f32 v[6:7], v[26:27], v[2:3] op_sel_hi:[1,0]
	v_cvt_pk_bf16_f32 v4, v4, v5
	v_cvt_pk_bf16_f32 v5, v6, v7
	v_pk_mul_f32 v[6:7], v[28:29], v[2:3] op_sel_hi:[1,0]
	v_pk_mul_f32 v[2:3], v[30:31], v[2:3] op_sel_hi:[1,0]
	v_cvt_pk_bf16_f32 v6, v6, v7
	v_cvt_pk_bf16_f32 v7, v2, v3
	ds_write2_b64 v1, v[4:5], v[6:7] offset0:204 offset1:206
	v_add_u32_e32 v1, v175, v187
	ds_read_b128 v[2:5], v1 offset:46592
	v_or_b32_e32 v8, v209, v167
	v_ashrrev_i32_e32 v9, 31, v8
	v_lshl_add_u64 v[6:7], v[142:143], 1, s[68:69]
	v_lshlrev_b64 v[8:9], 11, v[8:9]
	v_lshl_add_u64 v[6:7], v[6:7], 0, v[8:9]
	s_waitcnt lgkmcnt(0)
	global_store_dwordx4 v[6:7], v[2:5], off sc1
.LBB0_769:
	v_add3_u32 v1, s2, v185, v186
	s_lshl_b32 s18, s92, 1
	v_add_u32_e32 v2, v1, v190
	s_add_u32 s18, s66, s18
	ds_read_b128 v[2:5], v2
	v_or_b32_e32 v6, v209, v188
	s_addc_u32 s19, s67, 0
	v_ashrrev_i32_e32 v7, 31, v6
	v_lshl_add_u64 v[10:11], v[142:143], 1, s[18:19]
	v_lshlrev_b64 v[6:7], 11, v[6:7]
	v_lshl_add_u64 v[12:13], v[10:11], 0, v[6:7]
	v_add_u32_e32 v6, v1, v193
	ds_read_b128 v[6:9], v6
	s_waitcnt lgkmcnt(1)
	global_store_dwordx4 v[12:13], v[2:5], off sc1
	v_add_u32_e32 v1, v1, v195
	s_mov_b64 s[18:19], 0
	v_add_u32_e32 v2, v209, v192
	v_ashrrev_i32_e32 v3, 31, v2
	v_lshlrev_b64 v[2:3], 11, v[2:3]
	v_lshl_add_u64 v[2:3], v[10:11], 0, v[2:3]
	s_waitcnt lgkmcnt(0)
	global_store_dwordx4 v[2:3], v[6:9], off sc1
	ds_read_b128 v[2:5], v1
	s_nop 0
	v_add_u32_e32 v6, v209, v194
	v_ashrrev_i32_e32 v7, 31, v6
	v_lshlrev_b64 v[6:7], 11, v[6:7]
	v_lshl_add_u64 v[6:7], v[10:11], 0, v[6:7]
	s_waitcnt lgkmcnt(0)
	global_store_dwordx4 v[6:7], v[2:5], off sc1

; DI u32x2 pk4(float a, float b, float c, float d) { u32x2 r; r.x = pk2(a, b); r.y = pk2(c, d); return r; }
;     ...
;     if (FOX) __syncthreads();
;     { const auto sw = __builtin_amdgcn_permlane32_swap(__float_as_uint(lsum), __float_as_uint(lsum), false, false);
;       lsum = __uint_as_float(sw[0]) + __uint_as_float(sw[1]); }
;     const float inv = 1.0f / lsum;
;     {
;         unsigned char* sb = lds + 2 * STG + wid * (32 * 144);
; #pragma unroll
;         for (int d = 0; d < 2; ++d)
; #pragma unroll
;             for (int g = 0; g < 4; ++g)
;                 *(u32x2*)(sb + ln * 144 + (d * 32 + 8 * g + 4 * h) * 2) = pk4(o[d][4 * g] * inv, o[d][4 * g + 1] * inv, o[d][4 * g + 2] * inv, o[d][4 * g + 3] * inv);
;         __builtin_amdgcn_fence(__ATOMIC_RELEASE, "wavefront");
;         __builtin_amdgcn_wave_barrier();
;         __builtin_amdgcn_fence(__ATOMIC_ACQUIRE, "wavefront");
; #pragma unroll
;         for (int ps = 0; ps < 4; ++ps) {
;             const int row = ps * 8 + (lane >> 3), ch = lane & 7;
;             const u32x4 v = *(const u32x4*)(sb + row * 144 + ch * 16);
;             *(u32x4*)(obase + (size_t)(qw0 + row) * ldo + ch * 8) = v;
;         }
.LBB0_821:
	v_mov_b32_e32 v1, v132
	s_nop 1
	v_permlane32_swap_b32_e32 v132, v1
	v_add_f32_e32 v1, v132, v1
	v_div_scale_f32 v2, s[18:19], v1, v1, 1.0
	v_rcp_f32_e32 v3, v2
	s_barrier
	v_fma_f32 v4, -v2, v3, 1.0
	v_fmac_f32_e32 v3, v4, v3
	v_div_scale_f32 v4, vcc, 1.0, v1, 1.0
	v_mul_f32_e32 v5, v4, v3
	v_fma_f32 v6, -v2, v5, v4
	v_fmac_f32_e32 v5, v6, v3
	v_fma_f32 v2, -v2, v5, v4
	v_div_fmas_f32 v2, v2, v3, v5
	v_div_fixup_f32 v2, v2, v1, 1.0
	v_pk_mul_f32 v[4:5], v[32:33], v[2:3] op_sel_hi:[1,0]
	v_pk_mul_f32 v[6:7], v[34:35], v[2:3] op_sel_hi:[1,0]
	v_cvt_pk_bf16_f32 v4, v4, v5
	v_cvt_pk_bf16_f32 v5, v6, v7
	v_add_u32_e32 v1, v174, v146
	v_pk_mul_f32 v[6:7], v[36:37], v[2:3] op_sel_hi:[1,0]
	v_pk_mul_f32 v[8:9], v[38:39], v[2:3] op_sel_hi:[1,0]
	v_cvt_pk_bf16_f32 v6, v6, v7
	v_cvt_pk_bf16_f32 v7, v8, v9
	v_add_u32_e32 v1, 0x9000, v1
	ds_write2_b64 v1, v[4:5], v[6:7] offset0:192 offset1:194
	v_pk_mul_f32 v[4:5], v[40:41], v[2:3] op_sel_hi:[1,0]
	v_pk_mul_f32 v[6:7], v[42:43], v[2:3] op_sel_hi:[1,0]
	v_cvt_pk_bf16_f32 v4, v4, v5
	v_cvt_pk_bf16_f32 v5, v6, v7
	v_pk_mul_f32 v[6:7], v[44:45], v[2:3] op_sel_hi:[1,0]
	v_pk_mul_f32 v[8:9], v[46:47], v[2:3] op_sel_hi:[1,0]
	v_cvt_pk_bf16_f32 v6, v6, v7
	v_cvt_pk_bf16_f32 v7, v8, v9
	ds_write2_b64 v1, v[4:5], v[6:7] offset0:196 offset1:198
	v_pk_mul_f32 v[4:5], v[16:17], v[2:3] op_sel_hi:[1,0]
	v_pk_mul_f32 v[6:7], v[18:19], v[2:3] op_sel_hi:[1,0]
	v_cvt_pk_bf16_f32 v4, v4, v5
	v_cvt_pk_bf16_f32 v5, v6, v7
	v_pk_mul_f32 v[6:7], v[20:21], v[2:3] op_sel_hi:[1,0]
	v_pk_mul_f32 v[8:9], v[22:23], v[2:3] op_sel_hi:[1,0]
	v_cvt_pk_bf16_f32 v6, v6, v7
	v_cvt_pk_bf16_f32 v7, v8, v9
	ds_write2_b64 v1, v[4:5], v[6:7] offset0:200 offset1:202
	v_pk_mul_f32 v[4:5], v[24:25], v[2:3] op_sel_hi:[1,0]
	v_pk_mul_f32 v[6:7], v[26:27], v[2:3] op_sel_hi:[1,0]
	v_cvt_pk_bf16_f32 v4, v4, v5
	v_cvt_pk_bf16_f32 v5, v6, v7
	v_pk_mul_f32 v[6:7], v[28:29], v[2:3] op_sel_hi:[1,0]
	v_pk_mul_f32 v[2:3], v[30:31], v[2:3] op_sel_hi:[1,0]
	v_cvt_pk_bf16_f32 v6, v6, v7
	v_cvt_pk_bf16_f32 v7, v2, v3
	ds_write2_b64 v1, v[4:5], v[6:7] offset0:204 offset1:206
	v_add_u32_e32 v1, v175, v187
	ds_read_b128 v[2:5], v1 offset:38400
	v_or_b32_e32 v8, v209, v167
	v_ashrrev_i32_e32 v9, 31, v8
	v_lshl_add_u64 v[6:7], v[142:143], 1, s[68:69]
	v_lshlrev_b64 v[8:9], 11, v[8:9]
	v_lshl_add_u64 v[6:7], v[6:7], 0, v[8:9]
	s_mov_b64 s[18:19], 0
	s_waitcnt lgkmcnt(0)
	global_store_dwordx4 v[6:7], v[2:5], off sc1

; DI unsigned pk2(float lo, float hi) { f32x2 v = {lo, hi}; bf2_t b = __builtin_convertvector(v, bf2_t); return __builtin_bit_cast(unsigned, b); }
; DI float fsigmoid(float z) { return __builtin_amdgcn_rcpf(1.0f + __expf(-z)); }
; DI void phase3b(const Params& p, unsigned char* smem, int tid) {
;     ...
;         } else {
;             unsigned char* gt = ws + OFF_G + ((size_t)(f * 64 + tt) * 8 + wid) * 16384 + lane * 16;
; #pragma unroll
;             for (int it = 0; it < 4; ++it)
; #pragma unroll
;                 for (int jt = 0; jt < 2; ++jt)
; #pragma unroll
;                     for (int gp = 0; gp < 2; ++gp) {
;                         const float sc = rsj[jt];
;                         u32x4 w;
; #pragma unroll
;                         for (int e = 0; e < 4; ++e) w[e] = pk2(fsigmoid(acc[it][jt][8 * gp + 2 * e] * sc), fsigmoid(acc[it][jt][8 * gp + 2 * e + 1] * sc));
;                         __builtin_nontemporal_store(w, (u32x4*)(gt + ((it * 2 + jt) * 2 + gp) * 1024));
;                     }
.LBB0_926:
	s_add_i32 s24, s14, s17
	s_lshr_b32 s22, s24, 3
	s_and_b32 s14, s22, 60
	s_and_b32 s23, s24, 3
	s_or_b32 s14, s14, s23
	s_bfe_u32 s22, s22, 0x20004
	s_lshl_b32 s23, s14, 8
	s_mulk_i32 s22, 0x1010
	s_and_b32 s23, s23, 0xf00
	s_add_i32 s26, s22, s23
	v_mov_b32_e32 v177, v198
	s_add_i32 s26, s26, 16
	s_bfe_u32 s25, s24, 0x30002
	v_and_b32_e32 v179, 31, v177
	v_and_b32_e32 v176, 0xc0, v177
	v_add3_u32 v184, v176, s26, v179
	v_lshl_add_u64 v[180:181], v[184:185], 2, s[10:11]
	global_load_dword v178, v[180:181], off
	global_load_dword v176, v[180:181], off offset:128
	v_ashrrev_i32_e32 v180, 6, v177
	s_mov_b64 s[22:23], -1
	s_cmpk_gt_u32 s24, 0x1ff
	v_ashrrev_i32_e32 v181, 31, v180
	s_cbranch_scc0 .LBB0_928
	s_waitcnt vmcnt(1)
	v_mul_f32_e32 v186, v112, v178
	v_mul_f32_e32 v187, v113, v178
	s_lshl_b32 s22, s25, 9
	s_lshl_b32 s14, s14, 3
	v_mul_f32_e32 v186, 0xbfb8aa3b, v186
	v_mul_f32_e32 v187, 0xbfb8aa3b, v187
	s_or_b32 s14, s14, s22
	v_exp_f32_e32 v186, v186
	v_exp_f32_e32 v187, v187
	v_lshl_add_u64 v[182:183], v[180:181], 0, s[14:15]
	v_lshlrev_b64 v[182:183], 14, v[182:183]
	v_lshlrev_b32_e32 v184, 4, v177
	v_lshl_add_u64 v[182:183], s[12:13], 0, v[182:183]
	v_and_b32_e32 v184, 0x3f0, v184
	v_lshl_add_u64 v[182:183], v[182:183], 0, v[184:185]
	v_add_f32_e32 v184, 1.0, v186
	v_add_f32_e32 v186, 1.0, v187
	v_mul_f32_e32 v187, v114, v178
	v_mul_f32_e32 v188, v115, v178
	v_mul_f32_e32 v189, v116, v178
	v_mul_f32_e32 v190, v117, v178
	v_mul_f32_e32 v187, 0xbfb8aa3b, v187
	v_mul_f32_e32 v188, 0xbfb8aa3b, v188
	v_mul_f32_e32 v189, 0xbfb8aa3b, v189
	v_mul_f32_e32 v190, 0xbfb8aa3b, v190
	v_exp_f32_e32 v187, v187
	v_exp_f32_e32 v188, v188
	v_exp_f32_e32 v189, v189
	v_exp_f32_e32 v190, v190
	v_mul_f32_e32 v191, v118, v178
	v_mul_f32_e32 v192, v119, v178
	v_add_f32_e32 v187, 1.0, v187
	v_add_f32_e32 v188, 1.0, v188
	v_add_f32_e32 v189, 1.0, v189
	v_add_f32_e32 v190, 1.0, v190
	v_mul_f32_e32 v191, 0xbfb8aa3b, v191
	v_mul_f32_e32 v192, 0xbfb8aa3b, v192
	v_rcp_f32_e32 v187, v187
	v_rcp_f32_e32 v188, v188
	v_rcp_f32_e32 v189, v189
	v_exp_f32_e32 v191, v191
	v_exp_f32_e32 v192, v192
	v_rcp_f32_e32 v190, v190
	v_cvt_pk_bf16_f32 v187, v187, v188
	v_add_f32_e32 v191, 1.0, v191
	v_add_f32_e32 v192, 1.0, v192
	v_cvt_pk_bf16_f32 v188, v189, v190
	v_mul_f32_e32 v190, v121, v178
	v_rcp_f32_e32 v184, v184
	v_rcp_f32_e32 v186, v186
	v_rcp_f32_e32 v191, v191
	v_rcp_f32_e32 v192, v192
	v_mul_f32_e32 v190, 0xbfb8aa3b, v190
	v_exp_f32_e32 v190, v190
	v_cvt_pk_bf16_f32 v186, v184, v186
	v_cvt_pk_bf16_f32 v189, v191, v192
	global_store_dwordx4 v[182:183], v[186:189], off nt sc1
	v_mul_f32_e32 v184, v120, v178
	v_mul_f32_e32 v191, v126, v178
	v_add_f32_e32 v186, 1.0, v190
	v_mul_f32_e32 v187, v122, v178
	v_mul_f32_e32 v188, v123, v178
	v_mul_f32_e32 v189, v124, v178
	v_mul_f32_e32 v190, v125, v178
	v_mul_f32_e32 v187, 0xbfb8aa3b, v187
	v_mul_f32_e32 v188, 0xbfb8aa3b, v188
	v_mul_f32_e32 v189, 0xbfb8aa3b, v189
	v_mul_f32_e32 v190, 0xbfb8aa3b, v190
	v_exp_f32_e32 v187, v187
	v_exp_f32_e32 v188, v188
	v_exp_f32_e32 v189, v189
	v_exp_f32_e32 v190, v190
	v_mul_f32_e32 v192, v127, v178
	v_mul_f32_e32 v184, 0xbfb8aa3b, v184
	v_add_f32_e32 v187, 1.0, v187
	v_add_f32_e32 v188, 1.0, v188
	v_add_f32_e32 v189, 1.0, v189
	v_add_f32_e32 v190, 1.0, v190
	v_mul_f32_e32 v191, 0xbfb8aa3b, v191
	v_mul_f32_e32 v192, 0xbfb8aa3b, v192
	v_exp_f32_e32 v184, v184
	v_rcp_f32_e32 v187, v187
	v_rcp_f32_e32 v188, v188
	v_rcp_f32_e32 v189, v189
	v_exp_f32_e32 v191, v191
	v_exp_f32_e32 v192, v192
	v_rcp_f32_e32 v190, v190
	v_add_f32_e32 v184, 1.0, v184
	v_add_f32_e32 v191, 1.0, v191
	v_add_f32_e32 v192, 1.0, v192
	v_cvt_pk_bf16_f32 v187, v187, v188
	v_cvt_pk_bf16_f32 v188, v189, v190
	s_waitcnt vmcnt(1)
	v_mul_f32_e32 v190, v49, v176
	v_rcp_f32_e32 v184, v184
	v_rcp_f32_e32 v186, v186
	v_rcp_f32_e32 v191, v191
	v_rcp_f32_e32 v192, v192
	v_mul_f32_e32 v190, 0xbfb8aa3b, v190
	v_exp_f32_e32 v190, v190
	v_cvt_pk_bf16_f32 v186, v184, v186
	v_cvt_pk_bf16_f32 v189, v191, v192
	global_store_dwordx4 v[182:183], v[186:189], off offset:1024 nt sc1
	v_mul_f32_e32 v184, v48, v176
	v_mul_f32_e32 v191, v54, v176
	v_add_f32_e32 v186, 1.0, v190
	v_mul_f32_e32 v187, v50, v176
	v_mul_f32_e32 v188, v51, v176
	v_mul_f32_e32 v189, v52, v176
	v_mul_f32_e32 v190, v53, v176
	v_mul_f32_e32 v187, 0xbfb8aa3b, v187
	v_mul_f32_e32 v188, 0xbfb8aa3b, v188
	v_mul_f32_e32 v189, 0xbfb8aa3b, v189
	v_mul_f32_e32 v190, 0xbfb8aa3b, v190
	v_exp_f32_e32 v187, v187
	v_exp_f32_e32 v188, v188
	v_exp_f32_e32 v189, v189
	v_exp_f32_e32 v190, v190
	v_mul_f32_e32 v192, v55, v176
	v_mul_f32_e32 v184, 0xbfb8aa3b, v184
	v_add_f32_e32 v187, 1.0, v187
	v_add_f32_e32 v188, 1.0, v188
	v_add_f32_e32 v189, 1.0, v189
	v_add_f32_e32 v190, 1.0, v190
	v_mul_f32_e32 v191, 0xbfb8aa3b, v191
	v_mul_f32_e32 v192, 0xbfb8aa3b, v192
	v_exp_f32_e32 v184, v184
	v_rcp_f32_e32 v187, v187
	v_rcp_f32_e32 v188, v188
	v_rcp_f32_e32 v189, v189
	v_exp_f32_e32 v191, v191
	v_exp_f32_e32 v192, v192
	v_rcp_f32_e32 v190, v190
	v_add_f32_e32 v184, 1.0, v184
	v_add_f32_e32 v191, 1.0, v191
	v_add_f32_e32 v192, 1.0, v192
	v_cvt_pk_bf16_f32 v187, v187, v188
	v_cvt_pk_bf16_f32 v188, v189, v190
	v_mul_f32_e32 v190, v57, v176
	v_rcp_f32_e32 v184, v184
	v_rcp_f32_e32 v186, v186
	v_rcp_f32_e32 v191, v191
	v_rcp_f32_e32 v192, v192
	v_mul_f32_e32 v190, 0xbfb8aa3b, v190
	v_exp_f32_e32 v190, v190
	v_cvt_pk_bf16_f32 v186, v184, v186
	v_cvt_pk_bf16_f32 v189, v191, v192
	global_store_dwordx4 v[182:183], v[186:189], off offset:2048 nt sc1
	v_mul_f32_e32 v184, v56, v176
	v_mul_f32_e32 v191, v62, v176
	v_add_f32_e32 v186, 1.0, v190
	v_mul_f32_e32 v187, v58, v176
	v_mul_f32_e32 v188, v59, v176
; DI unsigned pk2(float lo, float hi) { f32x2 v = {lo, hi}; bf2_t b = __builtin_convertvector(v, bf2_t); return __builtin_bit_cast(unsigned, b); }
; DI float fsigmoid(float z) { return __builtin_amdgcn_rcpf(1.0f + __expf(-z)); }
; DI void phase3b(const Params& p, unsigned char* smem, int tid) {
;     ...
;         } else {
;             unsigned char* gt = ws + OFF_G + ((size_t)(f * 64 + tt) * 8 + wid) * 16384 + lane * 16;
; #pragma unroll
;             for (int it = 0; it < 4; ++it)
; #pragma unroll
;                 for (int jt = 0; jt < 2; ++jt)
; #pragma unroll
;                     for (int gp = 0; gp < 2; ++gp) {
;                         const float sc = rsj[jt];
;                         u32x4 w;
; #pragma unroll
;                         for (int e = 0; e < 4; ++e) w[e] = pk2(fsigmoid(acc[it][jt][8 * gp + 2 * e] * sc), fsigmoid(acc[it][jt][8 * gp + 2 * e + 1] * sc));
;                         __builtin_nontemporal_store(w, (u32x4*)(gt + ((it * 2 + jt) * 2 + gp) * 1024));
;                     }
	v_mul_f32_e32 v189, v60, v176
	v_mul_f32_e32 v190, v61, v176
	v_mul_f32_e32 v187, 0xbfb8aa3b, v187
	v_mul_f32_e32 v188, 0xbfb8aa3b, v188
	v_mul_f32_e32 v189, 0xbfb8aa3b, v189
	v_mul_f32_e32 v190, 0xbfb8aa3b, v190
	v_exp_f32_e32 v187, v187
	v_exp_f32_e32 v188, v188
	v_exp_f32_e32 v189, v189
	v_exp_f32_e32 v190, v190
	v_mul_f32_e32 v192, v63, v176
	v_mul_f32_e32 v184, 0xbfb8aa3b, v184
	v_mul_f32_e32 v191, 0xbfb8aa3b, v191
	v_mul_f32_e32 v192, 0xbfb8aa3b, v192
	v_exp_f32_e32 v184, v184
	v_exp_f32_e32 v191, v191
	v_exp_f32_e32 v192, v192
	v_add_f32_e32 v187, 1.0, v187
	v_add_f32_e32 v188, 1.0, v188
	v_add_f32_e32 v189, 1.0, v189
	v_add_f32_e32 v190, 1.0, v190
	v_rcp_f32_e32 v187, v187
	v_rcp_f32_e32 v188, v188
	v_rcp_f32_e32 v189, v189
	v_rcp_f32_e32 v190, v190
	v_add_f32_e32 v184, 1.0, v184
	v_add_f32_e32 v191, 1.0, v191
	v_add_f32_e32 v192, 1.0, v192
	v_rcp_f32_e32 v184, v184
	v_rcp_f32_e32 v186, v186
	v_rcp_f32_e32 v191, v191
	v_rcp_f32_e32 v192, v192
	v_cvt_pk_bf16_f32 v187, v187, v188
	v_cvt_pk_bf16_f32 v188, v189, v190
	v_mul_f32_e32 v190, v97, v178
	v_mul_f32_e32 v190, 0xbfb8aa3b, v190
	v_exp_f32_e32 v190, v190
	v_cvt_pk_bf16_f32 v186, v184, v186
	v_cvt_pk_bf16_f32 v189, v191, v192
	global_store_dwordx4 v[182:183], v[186:189], off offset:3072 nt sc1
	v_mul_f32_e32 v184, v96, v178
	v_mul_f32_e32 v184, 0xbfb8aa3b, v184
	v_mul_f32_e32 v188, v99, v178
	v_mul_f32_e32 v188, 0xbfb8aa3b, v188
	v_mul_f32_e32 v189, v100, v178
	v_add_f32_e32 v186, 1.0, v190
	v_exp_f32_e32 v188, v188
	v_mul_f32_e32 v189, 0xbfb8aa3b, v189
	v_mul_f32_e32 v190, v101, v178
	v_exp_f32_e32 v189, v189
	v_mul_f32_e32 v190, 0xbfb8aa3b, v190
	v_exp_f32_e32 v190, v190
	v_add_f32_e32 v188, 1.0, v188
	v_rcp_f32_e32 v191, v188
	v_add_f32_e32 v188, 1.0, v189
	v_mul_f32_e32 v189, v102, v178
	v_mul_f32_e32 v187, v98, v178
	v_rcp_f32_e32 v192, v188
	v_add_f32_e32 v188, 1.0, v190
	v_mul_f32_e32 v189, 0xbfb8aa3b, v189
	v_mul_f32_e32 v190, v103, v178
	v_mul_f32_e32 v187, 0xbfb8aa3b, v187
	v_exp_f32_e32 v189, v189
	v_mul_f32_e32 v190, 0xbfb8aa3b, v190
	v_exp_f32_e32 v187, v187
	v_exp_f32_e32 v190, v190
	v_rcp_f32_e32 v193, v188
	v_add_f32_e32 v188, 1.0, v189
	v_exp_f32_e32 v184, v184
	v_add_f32_e32 v187, 1.0, v187
	v_rcp_f32_e32 v194, v188
	v_add_f32_e32 v188, 1.0, v190
	v_rcp_f32_e32 v187, v187
	v_rcp_f32_e32 v195, v188
	v_add_f32_e32 v184, 1.0, v184
	v_rcp_f32_e32 v184, v184
	v_rcp_f32_e32 v186, v186
	v_cvt_pk_bf16_f32 v189, v187, v191
	v_cvt_pk_bf16_f32 v191, v194, v195
	v_mul_f32_e32 v194, v105, v178
	v_mul_f32_e32 v194, 0xbfb8aa3b, v194
	v_cvt_pk_bf16_f32 v190, v192, v193
	v_add_co_u32_e32 v192, vcc, s33, v182
	v_exp_f32_e32 v194, v194
	s_nop 0
	v_addc_co_u32_e32 v193, vcc, 0, v183, vcc
	v_cvt_pk_bf16_f32 v188, v184, v186
	v_add_co_u32_e32 v186, vcc, s34, v182
	v_mul_f32_e32 v184, v104, v178
	s_nop 0
	v_addc_co_u32_e32 v187, vcc, 0, v183, vcc
	global_store_dwordx4 v[186:187], v[188:191], off offset:-4096 nt sc1
	v_mul_f32_e32 v195, v110, v178
	v_mul_f32_e32 v196, v111, v178
	v_add_f32_e32 v188, 1.0, v194
	v_mul_f32_e32 v189, v106, v178
	v_mul_f32_e32 v190, v107, v178
	v_mul_f32_e32 v191, v108, v178
	v_mul_f32_e32 v194, v109, v178
	v_mul_f32_e32 v189, 0xbfb8aa3b, v189
	v_mul_f32_e32 v190, 0xbfb8aa3b, v190
	v_mul_f32_e32 v191, 0xbfb8aa3b, v191
	v_mul_f32_e32 v194, 0xbfb8aa3b, v194
	v_exp_f32_e32 v189, v189
	v_exp_f32_e32 v190, v190
	v_exp_f32_e32 v191, v191
	v_exp_f32_e32 v194, v194
	v_mul_f32_e32 v184, 0xbfb8aa3b, v184
	v_add_f32_e32 v189, 1.0, v189
	v_add_f32_e32 v190, 1.0, v190
	v_add_f32_e32 v191, 1.0, v191
	v_add_f32_e32 v194, 1.0, v194
	v_mul_f32_e32 v195, 0xbfb8aa3b, v195
	v_mul_f32_e32 v196, 0xbfb8aa3b, v196
	v_exp_f32_e32 v184, v184
	v_rcp_f32_e32 v189, v189
	v_rcp_f32_e32 v190, v190
	v_rcp_f32_e32 v191, v191
	v_exp_f32_e32 v195, v195
	v_exp_f32_e32 v196, v196
	v_rcp_f32_e32 v194, v194
	v_add_f32_e32 v184, 1.0, v184
	v_add_f32_e32 v195, 1.0, v195
	v_add_f32_e32 v196, 1.0, v196
	v_cvt_pk_bf16_f32 v189, v189, v190
	v_cvt_pk_bf16_f32 v190, v191, v194
	v_mul_f32_e32 v194, v33, v176
	v_rcp_f32_e32 v184, v184
	v_rcp_f32_e32 v188, v188
	v_rcp_f32_e32 v195, v195
	v_rcp_f32_e32 v196, v196
	v_mul_f32_e32 v194, 0xbfb8aa3b, v194
	v_exp_f32_e32 v194, v194
	v_cvt_pk_bf16_f32 v188, v184, v188
	v_cvt_pk_bf16_f32 v191, v195, v196
	global_store_dwordx4 v[192:193], v[188:191], off offset:1024 nt sc1
	v_mul_f32_e32 v184, v32, v176
	v_mul_f32_e32 v195, v38, v176
	v_add_f32_e32 v188, 1.0, v194
	v_mul_f32_e32 v189, v34, v176
	v_mul_f32_e32 v190, v35, v176
	v_mul_f32_e32 v191, v36, v176
	v_mul_f32_e32 v194, v37, v176
	v_mul_f32_e32 v189, 0xbfb8aa3b, v189
	v_mul_f32_e32 v190, 0xbfb8aa3b, v190
	v_mul_f32_e32 v191, 0xbfb8aa3b, v191
	v_mul_f32_e32 v194, 0xbfb8aa3b, v194
	v_exp_f32_e32 v189, v189
	v_exp_f32_e32 v190, v190
	v_exp_f32_e32 v191, v191
	v_exp_f32_e32 v194, v194
	v_mul_f32_e32 v196, v39, v176
	v_mul_f32_e32 v184, 0xbfb8aa3b, v184
	v_add_f32_e32 v189, 1.0, v189
	v_add_f32_e32 v190, 1.0, v190
	v_add_f32_e32 v191, 1.0, v191
	v_add_f32_e32 v194, 1.0, v194
	v_mul_f32_e32 v195, 0xbfb8aa3b, v195
	v_mul_f32_e32 v196, 0xbfb8aa3b, v196
	v_exp_f32_e32 v184, v184
	v_rcp_f32_e32 v189, v189
	v_rcp_f32_e32 v190, v190
	v_rcp_f32_e32 v191, v191
	v_exp_f32_e32 v195, v195
	v_exp_f32_e32 v196, v196
	v_rcp_f32_e32 v194, v194
	v_add_f32_e32 v184, 1.0, v184
	v_add_f32_e32 v195, 1.0, v195
	v_add_f32_e32 v196, 1.0, v196
	v_cvt_pk_bf16_f32 v189, v189, v190
	v_cvt_pk_bf16_f32 v190, v191, v194
	v_mul_f32_e32 v194, v41, v176
	v_rcp_f32_e32 v184, v184
	v_rcp_f32_e32 v188, v188
	v_rcp_f32_e32 v195, v195
	v_rcp_f32_e32 v196, v196
	v_mul_f32_e32 v194, 0xbfb8aa3b, v194
	v_exp_f32_e32 v194, v194
	v_cvt_pk_bf16_f32 v188, v184, v188
; DI unsigned pk2(float lo, float hi) { f32x2 v = {lo, hi}; bf2_t b = __builtin_convertvector(v, bf2_t); return __builtin_bit_cast(unsigned, b); }
; DI float fsigmoid(float z) { return __builtin_amdgcn_rcpf(1.0f + __expf(-z)); }
; DI void phase3b(const Params& p, unsigned char* smem, int tid) {
;     ...
; #pragma unroll
;             for (int it = 0; it < 4; ++it)
; #pragma unroll
;                 for (int jt = 0; jt < 2; ++jt)
; #pragma unroll
;                     for (int gp = 0; gp < 2; ++gp) {
;                         const float sc = rsj[jt];
;                         u32x4 w;
; #pragma unroll
;                         for (int e = 0; e < 4; ++e) w[e] = pk2(fsigmoid(acc[it][jt][8 * gp + 2 * e] * sc), fsigmoid(acc[it][jt][8 * gp + 2 * e + 1] * sc));
;                         __builtin_nontemporal_store(w, (u32x4*)(gt + ((it * 2 + jt) * 2 + gp) * 1024));
;                     }
	v_cvt_pk_bf16_f32 v191, v195, v196
	v_mul_f32_e32 v184, v40, v176
	global_store_dwordx4 v[192:193], v[188:191], off offset:2048 nt sc1
	v_mul_f32_e32 v195, v46, v176
	v_mul_f32_e32 v196, v47, v176
	v_add_f32_e32 v188, 1.0, v194
	v_mul_f32_e32 v189, v42, v176
	v_mul_f32_e32 v190, v43, v176
	v_mul_f32_e32 v191, v44, v176
	v_mul_f32_e32 v194, v45, v176
	v_mul_f32_e32 v184, 0xbfb8aa3b, v184
	v_mul_f32_e32 v189, 0xbfb8aa3b, v189
	v_mul_f32_e32 v190, 0xbfb8aa3b, v190
	v_mul_f32_e32 v191, 0xbfb8aa3b, v191
	v_mul_f32_e32 v194, 0xbfb8aa3b, v194
	v_mul_f32_e32 v195, 0xbfb8aa3b, v195
	v_mul_f32_e32 v196, 0xbfb8aa3b, v196
	v_exp_f32_e32 v184, v184
	v_exp_f32_e32 v189, v189
	v_exp_f32_e32 v190, v190
	v_exp_f32_e32 v191, v191
	v_exp_f32_e32 v194, v194
	v_exp_f32_e32 v195, v195
	v_exp_f32_e32 v196, v196
	v_add_f32_e32 v184, 1.0, v184
	v_add_f32_e32 v189, 1.0, v189
	v_add_f32_e32 v190, 1.0, v190
	v_add_f32_e32 v191, 1.0, v191
	v_add_f32_e32 v194, 1.0, v194
	v_add_f32_e32 v195, 1.0, v195
	v_add_f32_e32 v196, 1.0, v196
	v_rcp_f32_e32 v184, v184
	v_rcp_f32_e32 v188, v188
	v_rcp_f32_e32 v189, v189
	v_rcp_f32_e32 v190, v190
	v_rcp_f32_e32 v191, v191
	v_rcp_f32_e32 v194, v194
	v_rcp_f32_e32 v195, v195
	v_rcp_f32_e32 v196, v196
	v_cvt_pk_bf16_f32 v188, v184, v188
	v_cvt_pk_bf16_f32 v189, v189, v190
	v_cvt_pk_bf16_f32 v190, v191, v194
	v_cvt_pk_bf16_f32 v191, v195, v196
	v_mul_f32_e32 v194, v81, v178
	v_mul_f32_e32 v194, 0xbfb8aa3b, v194
	global_store_dwordx4 v[192:193], v[188:191], off offset:3072 nt sc1
	v_mul_f32_e32 v192, v85, v178
	v_exp_f32_e32 v194, v194
	v_mul_f32_e32 v189, v82, v178
	v_mul_f32_e32 v190, v83, v178
	v_mul_f32_e32 v191, v84, v178
	v_mul_f32_e32 v189, 0xbfb8aa3b, v189
	v_mul_f32_e32 v190, 0xbfb8aa3b, v190
	v_mul_f32_e32 v191, 0xbfb8aa3b, v191
	v_mul_f32_e32 v192, 0xbfb8aa3b, v192
	v_exp_f32_e32 v189, v189
	v_exp_f32_e32 v190, v190
	v_exp_f32_e32 v191, v191
	v_exp_f32_e32 v192, v192
	v_mul_f32_e32 v184, v80, v178
	v_add_f32_e32 v188, 1.0, v194
	v_mul_f32_e32 v193, v86, v178
	v_mul_f32_e32 v194, v87, v178
	v_mul_f32_e32 v184, 0xbfb8aa3b, v184
	v_add_f32_e32 v189, 1.0, v189
	v_add_f32_e32 v190, 1.0, v190
	v_add_f32_e32 v191, 1.0, v191
	v_add_f32_e32 v192, 1.0, v192
	v_mul_f32_e32 v193, 0xbfb8aa3b, v193
	v_mul_f32_e32 v194, 0xbfb8aa3b, v194
	v_exp_f32_e32 v184, v184
	v_rcp_f32_e32 v189, v189
	v_rcp_f32_e32 v190, v190
	v_rcp_f32_e32 v191, v191
	v_exp_f32_e32 v193, v193
	v_exp_f32_e32 v194, v194
	v_rcp_f32_e32 v192, v192
	v_add_f32_e32 v184, 1.0, v184
	v_add_f32_e32 v193, 1.0, v193
	v_add_f32_e32 v194, 1.0, v194
	v_cvt_pk_bf16_f32 v189, v189, v190
	v_cvt_pk_bf16_f32 v190, v191, v192
	v_mul_f32_e32 v192, v89, v178
	v_rcp_f32_e32 v184, v184
	v_rcp_f32_e32 v188, v188
	v_rcp_f32_e32 v193, v193
	v_rcp_f32_e32 v194, v194
	v_mul_f32_e32 v192, 0xbfb8aa3b, v192
	v_exp_f32_e32 v192, v192
	v_cvt_pk_bf16_f32 v188, v184, v188
	v_cvt_pk_bf16_f32 v191, v193, v194
	global_store_dwordx4 v[186:187], v[188:191], off nt sc1
	v_mul_f32_e32 v184, v88, v178
	v_mul_f32_e32 v193, v94, v178
	v_add_f32_e32 v188, 1.0, v192
	v_mul_f32_e32 v189, v90, v178
	v_mul_f32_e32 v190, v91, v178
	v_mul_f32_e32 v191, v92, v178
	v_mul_f32_e32 v192, v93, v178
	v_mul_f32_e32 v189, 0xbfb8aa3b, v189
	v_mul_f32_e32 v190, 0xbfb8aa3b, v190
	v_mul_f32_e32 v191, 0xbfb8aa3b, v191
	v_mul_f32_e32 v192, 0xbfb8aa3b, v192
	v_exp_f32_e32 v189, v189
	v_exp_f32_e32 v190, v190
	v_exp_f32_e32 v191, v191
	v_exp_f32_e32 v192, v192
	v_mul_f32_e32 v194, v95, v178
	v_mul_f32_e32 v184, 0xbfb8aa3b, v184
	v_add_f32_e32 v189, 1.0, v189
	v_add_f32_e32 v190, 1.0, v190
	v_add_f32_e32 v191, 1.0, v191
	v_add_f32_e32 v192, 1.0, v192
	v_mul_f32_e32 v193, 0xbfb8aa3b, v193
	v_mul_f32_e32 v194, 0xbfb8aa3b, v194
	v_exp_f32_e32 v184, v184
	v_rcp_f32_e32 v189, v189
	v_rcp_f32_e32 v190, v190
	v_rcp_f32_e32 v191, v191
	v_exp_f32_e32 v193, v193
	v_exp_f32_e32 v194, v194
	v_rcp_f32_e32 v192, v192
	v_add_f32_e32 v184, 1.0, v184
	v_add_f32_e32 v193, 1.0, v193
	v_add_f32_e32 v194, 1.0, v194
	v_cvt_pk_bf16_f32 v189, v189, v190
	v_cvt_pk_bf16_f32 v190, v191, v192
	v_mul_f32_e32 v192, v17, v176
	v_rcp_f32_e32 v184, v184
	v_rcp_f32_e32 v188, v188
	v_rcp_f32_e32 v193, v193
	v_rcp_f32_e32 v194, v194
	v_mul_f32_e32 v192, 0xbfb8aa3b, v192
	v_exp_f32_e32 v192, v192
	v_cvt_pk_bf16_f32 v188, v184, v188
	v_cvt_pk_bf16_f32 v191, v193, v194
	global_store_dwordx4 v[186:187], v[188:191], off offset:1024 nt sc1
	v_mul_f32_e32 v184, v16, v176
	v_mul_f32_e32 v193, v22, v176
	v_add_f32_e32 v188, 1.0, v192
	v_mul_f32_e32 v189, v18, v176
	v_mul_f32_e32 v190, v19, v176
	v_mul_f32_e32 v191, v20, v176
	v_mul_f32_e32 v192, v21, v176
	v_mul_f32_e32 v189, 0xbfb8aa3b, v189
	v_mul_f32_e32 v190, 0xbfb8aa3b, v190
	v_mul_f32_e32 v191, 0xbfb8aa3b, v191
	v_mul_f32_e32 v192, 0xbfb8aa3b, v192
	v_exp_f32_e32 v189, v189
	v_exp_f32_e32 v190, v190
	v_exp_f32_e32 v191, v191
	v_exp_f32_e32 v192, v192
	v_mul_f32_e32 v194, v23, v176
	v_mul_f32_e32 v184, 0xbfb8aa3b, v184
	v_add_f32_e32 v189, 1.0, v189
	v_add_f32_e32 v190, 1.0, v190
	v_add_f32_e32 v191, 1.0, v191
	v_add_f32_e32 v192, 1.0, v192
	v_mul_f32_e32 v193, 0xbfb8aa3b, v193
	v_mul_f32_e32 v194, 0xbfb8aa3b, v194
	v_exp_f32_e32 v184, v184
	v_rcp_f32_e32 v189, v189
	v_rcp_f32_e32 v190, v190
	v_rcp_f32_e32 v191, v191
	v_exp_f32_e32 v193, v193
	v_exp_f32_e32 v194, v194
	v_rcp_f32_e32 v192, v192
	v_add_f32_e32 v184, 1.0, v184
	v_add_f32_e32 v193, 1.0, v193
	v_add_f32_e32 v194, 1.0, v194
	v_cvt_pk_bf16_f32 v189, v189, v190
	v_cvt_pk_bf16_f32 v190, v191, v192
	v_mul_f32_e32 v192, v25, v176
	v_rcp_f32_e32 v184, v184
	v_rcp_f32_e32 v188, v188
	v_rcp_f32_e32 v193, v193
	v_rcp_f32_e32 v194, v194
	v_mul_f32_e32 v192, 0xbfb8aa3b, v192
; DI unsigned pk2(float lo, float hi) { f32x2 v = {lo, hi}; bf2_t b = __builtin_convertvector(v, bf2_t); return __builtin_bit_cast(unsigned, b); }
; DI float fsigmoid(float z) { return __builtin_amdgcn_rcpf(1.0f + __expf(-z)); }
; DI void phase3b(const Params& p, unsigned char* smem, int tid) {
;     ...
; #pragma unroll
;             for (int it = 0; it < 4; ++it)
; #pragma unroll
;                 for (int jt = 0; jt < 2; ++jt)
; #pragma unroll
;                     for (int gp = 0; gp < 2; ++gp) {
;                         const float sc = rsj[jt];
;                         u32x4 w;
; #pragma unroll
;                         for (int e = 0; e < 4; ++e) w[e] = pk2(fsigmoid(acc[it][jt][8 * gp + 2 * e] * sc), fsigmoid(acc[it][jt][8 * gp + 2 * e + 1] * sc));
;                         __builtin_nontemporal_store(w, (u32x4*)(gt + ((it * 2 + jt) * 2 + gp) * 1024));
;                     }
	v_exp_f32_e32 v192, v192
	v_cvt_pk_bf16_f32 v188, v184, v188
	v_cvt_pk_bf16_f32 v191, v193, v194
	v_mul_f32_e32 v184, v24, v176
	global_store_dwordx4 v[186:187], v[188:191], off offset:2048 nt sc1
	v_mul_f32_e32 v193, v30, v176
	v_mul_f32_e32 v194, v31, v176
	v_add_f32_e32 v188, 1.0, v192
	v_mul_f32_e32 v189, v26, v176
	v_mul_f32_e32 v190, v27, v176
	v_mul_f32_e32 v191, v28, v176
	v_mul_f32_e32 v192, v29, v176
	v_mul_f32_e32 v184, 0xbfb8aa3b, v184
	v_mul_f32_e32 v189, 0xbfb8aa3b, v189
	v_mul_f32_e32 v190, 0xbfb8aa3b, v190
	v_mul_f32_e32 v191, 0xbfb8aa3b, v191
	v_mul_f32_e32 v192, 0xbfb8aa3b, v192
	v_mul_f32_e32 v193, 0xbfb8aa3b, v193
	v_mul_f32_e32 v194, 0xbfb8aa3b, v194
	v_exp_f32_e32 v184, v184
	v_exp_f32_e32 v189, v189
	v_exp_f32_e32 v190, v190
	v_exp_f32_e32 v191, v191
	v_exp_f32_e32 v192, v192
	v_exp_f32_e32 v193, v193
	v_exp_f32_e32 v194, v194
	v_add_f32_e32 v184, 1.0, v184
	v_add_f32_e32 v189, 1.0, v189
	v_add_f32_e32 v190, 1.0, v190
	v_add_f32_e32 v191, 1.0, v191
	v_add_f32_e32 v192, 1.0, v192
	v_add_f32_e32 v193, 1.0, v193
	v_add_f32_e32 v194, 1.0, v194
	v_rcp_f32_e32 v184, v184
	v_rcp_f32_e32 v188, v188
	v_rcp_f32_e32 v189, v189
	v_rcp_f32_e32 v190, v190
	v_rcp_f32_e32 v191, v191
	v_rcp_f32_e32 v192, v192
	v_rcp_f32_e32 v193, v193
	v_rcp_f32_e32 v194, v194
	v_cvt_pk_bf16_f32 v188, v184, v188
	v_cvt_pk_bf16_f32 v189, v189, v190
	v_cvt_pk_bf16_f32 v190, v191, v192
	v_cvt_pk_bf16_f32 v191, v193, v194
	v_mul_f32_e32 v192, v65, v178
	v_mul_f32_e32 v192, 0xbfb8aa3b, v192
	global_store_dwordx4 v[186:187], v[188:191], off offset:3072 nt sc1
	v_mul_f32_e32 v187, v66, v178
	v_exp_f32_e32 v192, v192
	v_mul_f32_e32 v188, v67, v178
	v_mul_f32_e32 v189, v68, v178
	v_mul_f32_e32 v190, v69, v178
	v_mul_f32_e32 v187, 0xbfb8aa3b, v187
	v_mul_f32_e32 v188, 0xbfb8aa3b, v188
	v_mul_f32_e32 v189, 0xbfb8aa3b, v189
	v_mul_f32_e32 v190, 0xbfb8aa3b, v190
	v_exp_f32_e32 v187, v187
	v_exp_f32_e32 v188, v188
	v_exp_f32_e32 v189, v189
	v_exp_f32_e32 v190, v190
	v_mul_f32_e32 v184, v64, v178
	v_add_f32_e32 v186, 1.0, v192
	v_mul_f32_e32 v191, v70, v178
	v_mul_f32_e32 v192, v71, v178
	v_mul_f32_e32 v184, 0xbfb8aa3b, v184
	v_add_f32_e32 v187, 1.0, v187
	v_add_f32_e32 v188, 1.0, v188
	v_add_f32_e32 v189, 1.0, v189
	v_add_f32_e32 v190, 1.0, v190
	v_mul_f32_e32 v191, 0xbfb8aa3b, v191
	v_mul_f32_e32 v192, 0xbfb8aa3b, v192
	v_exp_f32_e32 v184, v184
	v_rcp_f32_e32 v187, v187
	v_rcp_f32_e32 v188, v188
	v_rcp_f32_e32 v189, v189
	v_exp_f32_e32 v191, v191
	v_exp_f32_e32 v192, v192
	v_rcp_f32_e32 v190, v190
	v_add_f32_e32 v184, 1.0, v184
	v_add_f32_e32 v191, 1.0, v191
	v_add_f32_e32 v192, 1.0, v192
	v_cvt_pk_bf16_f32 v187, v187, v188
	v_cvt_pk_bf16_f32 v188, v189, v190
	v_mul_f32_e32 v190, v73, v178
	v_rcp_f32_e32 v184, v184
	v_rcp_f32_e32 v186, v186
	v_rcp_f32_e32 v191, v191
	v_rcp_f32_e32 v192, v192
	v_mul_f32_e32 v190, 0xbfb8aa3b, v190
	v_exp_f32_e32 v190, v190
	v_add_co_u32_e32 v182, vcc, s35, v182
	v_cvt_pk_bf16_f32 v186, v184, v186
	v_cvt_pk_bf16_f32 v189, v191, v192
	v_addc_co_u32_e32 v183, vcc, 0, v183, vcc
	global_store_dwordx4 v[182:183], v[186:189], off nt sc1
	v_mul_f32_e32 v184, v72, v178
	v_mul_f32_e32 v191, v78, v178
	v_add_f32_e32 v186, 1.0, v190
	v_mul_f32_e32 v187, v74, v178
	v_mul_f32_e32 v188, v75, v178
	v_mul_f32_e32 v189, v76, v178
	v_mul_f32_e32 v190, v77, v178
	v_mul_f32_e32 v187, 0xbfb8aa3b, v187
	v_mul_f32_e32 v188, 0xbfb8aa3b, v188
	v_mul_f32_e32 v189, 0xbfb8aa3b, v189
	v_mul_f32_e32 v190, 0xbfb8aa3b, v190
	v_exp_f32_e32 v187, v187
	v_exp_f32_e32 v188, v188
	v_exp_f32_e32 v189, v189
	v_exp_f32_e32 v190, v190
	v_mul_f32_e32 v192, v79, v178
	v_mul_f32_e32 v184, 0xbfb8aa3b, v184
	v_add_f32_e32 v187, 1.0, v187
	v_add_f32_e32 v188, 1.0, v188
	v_add_f32_e32 v189, 1.0, v189
	v_add_f32_e32 v190, 1.0, v190
	v_mul_f32_e32 v191, 0xbfb8aa3b, v191
	v_mul_f32_e32 v192, 0xbfb8aa3b, v192
	v_exp_f32_e32 v184, v184
	v_rcp_f32_e32 v187, v187
	v_rcp_f32_e32 v188, v188
	v_rcp_f32_e32 v189, v189
	v_exp_f32_e32 v191, v191
	v_exp_f32_e32 v192, v192
	v_rcp_f32_e32 v190, v190
	v_add_f32_e32 v184, 1.0, v184
	v_add_f32_e32 v191, 1.0, v191
	v_add_f32_e32 v192, 1.0, v192
	v_cvt_pk_bf16_f32 v187, v187, v188
	v_cvt_pk_bf16_f32 v188, v189, v190
	v_mul_f32_e32 v190, v1, v176
	v_rcp_f32_e32 v184, v184
	v_rcp_f32_e32 v186, v186
	v_rcp_f32_e32 v191, v191
	v_rcp_f32_e32 v192, v192
	v_mul_f32_e32 v190, 0xbfb8aa3b, v190
	v_exp_f32_e32 v190, v190
	v_cvt_pk_bf16_f32 v186, v184, v186
	v_cvt_pk_bf16_f32 v189, v191, v192
	global_store_dwordx4 v[182:183], v[186:189], off offset:1024 nt sc1
	v_mul_f32_e32 v184, v0, v176
	v_mul_f32_e32 v191, v6, v176
	v_add_f32_e32 v186, 1.0, v190
	v_mul_f32_e32 v187, v2, v176
	v_mul_f32_e32 v188, v3, v176
	v_mul_f32_e32 v189, v4, v176
	v_mul_f32_e32 v190, v5, v176
	v_mul_f32_e32 v187, 0xbfb8aa3b, v187
	v_mul_f32_e32 v188, 0xbfb8aa3b, v188
	v_mul_f32_e32 v189, 0xbfb8aa3b, v189
	v_mul_f32_e32 v190, 0xbfb8aa3b, v190
	v_exp_f32_e32 v187, v187
	v_exp_f32_e32 v188, v188
	v_exp_f32_e32 v189, v189
	v_exp_f32_e32 v190, v190
	v_mul_f32_e32 v192, v7, v176
	v_mul_f32_e32 v184, 0xbfb8aa3b, v184
	v_add_f32_e32 v187, 1.0, v187
	v_add_f32_e32 v188, 1.0, v188
	v_add_f32_e32 v189, 1.0, v189
	v_add_f32_e32 v190, 1.0, v190
	v_mul_f32_e32 v191, 0xbfb8aa3b, v191
	v_mul_f32_e32 v192, 0xbfb8aa3b, v192
	v_exp_f32_e32 v184, v184
	v_rcp_f32_e32 v187, v187
	v_rcp_f32_e32 v188, v188
	v_rcp_f32_e32 v189, v189
	v_exp_f32_e32 v191, v191
	v_exp_f32_e32 v192, v192
	v_rcp_f32_e32 v190, v190
	v_add_f32_e32 v184, 1.0, v184
	v_add_f32_e32 v191, 1.0, v191
	v_add_f32_e32 v192, 1.0, v192
	v_cvt_pk_bf16_f32 v187, v187, v188
	v_cvt_pk_bf16_f32 v188, v189, v190
	v_mul_f32_e32 v190, v9, v176
; DI unsigned pk2(float lo, float hi) { f32x2 v = {lo, hi}; bf2_t b = __builtin_convertvector(v, bf2_t); return __builtin_bit_cast(unsigned, b); }
; DI u32x2 pk4(float a, float b, float c, float d) { u32x2 r; r.x = pk2(a, b); r.y = pk2(c, d); return r; }
; DI float fsigmoid(float z) { return __builtin_amdgcn_rcpf(1.0f + __expf(-z)); }
; DI float fsilu(float z) { return z * fsigmoid(z); }
; template <int WI, int WGJ, class GetF, class LdF, class FinF>
; DI void staged_rows_rmw(unsigned char* lds, int tid, GetF get, LdF ld, FinF fin) {
;     ...
;         for (int gq = 0; gq < NGRP; ++gq) {
;             decltype(ld(0, 0)) fetched[GSZ];
; #pragma unroll
;             for (int c = 0; c < GSZ; ++c) {
;                 const int idx = tid + (gq * GSZ + c) * NT, lr = idx / NCH, ch = idx % NCH;
;                 fetched[c] = ld((lr >> 5) * 64 + jt * 32 + (lr & 31), ch * 8);
; DI void phase3b(const Params& p, unsigned char* smem, int tid) {
;     ...
;         if (half == 0) {
;             bf16_t* obuf = (bf16_t*)(ws + (f < 4 ? OFF_QN : OFF_FQ)) + (f & 3) * 256;
;             staged_rows_rmw<4, 4>(lds, te,
;                 [&](int it, int jt, int g) { const float sc = rsj[jt];
;                     return pk4(fsilu(acc[it][jt][4 * g] * sc), fsilu(acc[it][jt][4 * g + 1] * sc), fsilu(acc[it][jt][4 * g + 2] * sc), fsilu(acc[it][jt][4 * g + 3] * sc)); },
;                 [&](int row, int col) { return *(const u32x4*)(obuf + (size_t)(r0 + row) * 1024 + col); },
;                 [&](int row, int col, u32x4 v, u32x4 o) { u32x4 w;
;     ...
;                     for (int gp = 0; gp < 2; ++gp) {
;                         const float sc = rsj[jt];
;                         u32x4 w;
; #pragma unroll
;                         for (int e = 0; e < 4; ++e) w[e] = pk2(fsigmoid(acc[it][jt][8 * gp + 2 * e] * sc), fsigmoid(acc[it][jt][8 * gp + 2 * e + 1] * sc));
;                         __builtin_nontemporal_store(w, (u32x4*)(gt + ((it * 2 + jt) * 2 + gp) * 1024));
;                     }
	v_rcp_f32_e32 v184, v184
	v_rcp_f32_e32 v186, v186
	v_rcp_f32_e32 v191, v191
	v_rcp_f32_e32 v192, v192
	v_mul_f32_e32 v190, 0xbfb8aa3b, v190
	v_exp_f32_e32 v190, v190
	v_cvt_pk_bf16_f32 v186, v184, v186
	v_cvt_pk_bf16_f32 v189, v191, v192
	v_mul_f32_e32 v184, v8, v176
	global_store_dwordx4 v[182:183], v[186:189], off offset:2048 nt sc1
	v_mul_f32_e32 v191, v14, v176
	v_mul_f32_e32 v192, v15, v176
	v_add_f32_e32 v186, 1.0, v190
	v_mul_f32_e32 v187, v10, v176
	v_mul_f32_e32 v188, v11, v176
	v_mul_f32_e32 v189, v12, v176
	v_mul_f32_e32 v190, v13, v176
	v_mul_f32_e32 v184, 0xbfb8aa3b, v184
	v_mul_f32_e32 v187, 0xbfb8aa3b, v187
	v_mul_f32_e32 v188, 0xbfb8aa3b, v188
	v_mul_f32_e32 v189, 0xbfb8aa3b, v189
	v_mul_f32_e32 v190, 0xbfb8aa3b, v190
	v_mul_f32_e32 v191, 0xbfb8aa3b, v191
	v_mul_f32_e32 v192, 0xbfb8aa3b, v192
	v_exp_f32_e32 v184, v184
	v_exp_f32_e32 v187, v187
	v_exp_f32_e32 v188, v188
	v_exp_f32_e32 v189, v189
	v_exp_f32_e32 v190, v190
	v_exp_f32_e32 v191, v191
	v_exp_f32_e32 v192, v192
	v_add_f32_e32 v184, 1.0, v184
	v_add_f32_e32 v187, 1.0, v187
	v_add_f32_e32 v188, 1.0, v188
	v_add_f32_e32 v189, 1.0, v189
	v_add_f32_e32 v190, 1.0, v190
	v_add_f32_e32 v191, 1.0, v191
	v_add_f32_e32 v192, 1.0, v192
	v_rcp_f32_e32 v184, v184
	v_rcp_f32_e32 v186, v186
	v_rcp_f32_e32 v187, v187
	v_rcp_f32_e32 v188, v188
	v_rcp_f32_e32 v189, v189
	v_rcp_f32_e32 v190, v190
	v_rcp_f32_e32 v191, v191
	v_rcp_f32_e32 v192, v192
	v_cvt_pk_bf16_f32 v186, v184, v186
	v_cvt_pk_bf16_f32 v187, v187, v188
	v_cvt_pk_bf16_f32 v188, v189, v190
	v_cvt_pk_bf16_f32 v189, v191, v192
	global_store_dwordx4 v[182:183], v[186:189], off offset:3072 nt sc1
	s_mov_b64 s[22:23], 0
.LBB0_928:
	s_andn2_b64 vcc, exec, s[22:23]
	s_cbranch_vccnz .LBB0_912
	s_cmp_lt_u32 s25, 4
	s_cselect_b32 s98, s36, 0x398fc00
	s_lshr_b32 s99, s24, 2
	s_lshl_b32 s99, s99, 9
	s_and_b32 s99, s99, 0x600
	s_add_u32 s98, s98, s99
	s_add_u32 s100, s56, s98
	s_addc_u32 s101, s57, 0
	v_lshrrev_b32_e32 v196, 5, v177
	v_add_u32_e32 v196, s26, v196
	v_lshlrev_b32_e32 v196, 11, v196
	v_and_b32_e32 v197, 31, v177
	v_lshl_add_u32 v196, v197, 4, v196
	v_lshrrev_b32_e32 v244, 5, v177
	v_mul_u32_u24_e32 v244, 0x210, v244
	v_lshl_add_u32 v197, v197, 4, v244
	global_load_dwordx4 v[188:191], v196, s[100:101]
	v_add_u32_e32 v245, 0x8000, v196
	global_load_dwordx4 v[192:195], v245, s[100:101]
	v_add_u32_e32 v244, 0x20000, v196
	global_load_dwordx4 v[200:203], v244, s[100:101]
	v_add_u32_e32 v245, 0x28000, v196
	global_load_dwordx4 v[204:207], v245, s[100:101]
	v_add_u32_e32 v244, 0x40000, v196
	global_load_dwordx4 v[208:211], v244, s[100:101]
	v_add_u32_e32 v245, 0x48000, v196
	global_load_dwordx4 v[212:215], v245, s[100:101]
	v_add_u32_e32 v244, 0x60000, v196
	global_load_dwordx4 v[216:219], v244, s[100:101]
	v_add_u32_e32 v245, 0x68000, v196
	global_load_dwordx4 v[220:223], v245, s[100:101]
	v_add_u32_e32 v244, 0x10000, v196
	global_load_dwordx4 v[224:227], v244, s[100:101]
	v_add_u32_e32 v245, 0x18000, v196
	global_load_dwordx4 v[228:231], v245, s[100:101]
	v_add_u32_e32 v244, 0x30000, v196
	global_load_dwordx4 v[232:235], v244, s[100:101]
	v_add_u32_e32 v245, 0x38000, v196
	global_load_dwordx4 v[236:239], v245, s[100:101]
	v_lshrrev_b32_e32 v181, 30, v181
	v_add_u32_e32 v181, v180, v181
	v_and_b32_e32 v182, 0x7ffffc, v181
	v_sub_u32_e32 v180, v180, v182
	v_lshl_or_b32 v179, v180, 5, v179
	v_lshlrev_b32_e32 v180, 6, v181
	v_mul_lo_u32 v179, v179, s37
	v_and_b32_e32 v180, 0xffffff00, v180
	v_add3_u32 v179, 0, v179, v180
	s_waitcnt vmcnt(13)
	v_pk_mul_f32 v[112:113], v[112:113], v[178:179] op_sel_hi:[1,0]
	v_lshrrev_b32_e32 v181, 2, v177
	v_mul_f32_e32 v180, 0xbfb8aa3b, v112
	v_mul_f32_e32 v182, 0xbfb8aa3b, v113
	v_exp_f32_e32 v180, v180
	v_exp_f32_e32 v182, v182
	v_and_b32_e32 v181, 8, v181
	v_add_u32_e32 v179, v179, v181
	v_pk_mul_f32 v[114:115], v[114:115], v[178:179] op_sel_hi:[1,0]
	v_add_f32_e32 v180, 1.0, v180
	v_add_f32_e32 v181, 1.0, v182
	v_mul_f32_e32 v182, 0xbfb8aa3b, v114
	v_mul_f32_e32 v183, 0xbfb8aa3b, v115
	v_rcp_f32_e32 v180, v180
	v_rcp_f32_e32 v181, v181
	v_exp_f32_e32 v182, v182
	v_exp_f32_e32 v183, v183
	v_pk_mul_f32 v[116:117], v[116:117], v[178:179] op_sel_hi:[1,0]
	v_pk_mul_f32 v[112:113], v[112:113], v[180:181]
	v_add_f32_e32 v180, 1.0, v182
	v_add_f32_e32 v181, 1.0, v183
	v_mul_f32_e32 v182, 0xbfb8aa3b, v116
	v_mul_f32_e32 v183, 0xbfb8aa3b, v117
	v_rcp_f32_e32 v180, v180
	v_rcp_f32_e32 v181, v181
	v_exp_f32_e32 v182, v182
	v_exp_f32_e32 v183, v183
	v_pk_mul_f32 v[118:119], v[118:119], v[178:179] op_sel_hi:[1,0]
	v_pk_mul_f32 v[114:115], v[114:115], v[180:181]
	v_add_f32_e32 v180, 1.0, v182
	v_add_f32_e32 v181, 1.0, v183
	v_mul_f32_e32 v182, 0xbfb8aa3b, v118
	v_mul_f32_e32 v183, 0xbfb8aa3b, v119
	v_exp_f32_e32 v182, v182
	v_exp_f32_e32 v183, v183
	v_rcp_f32_e32 v180, v180
	v_rcp_f32_e32 v181, v181
	v_add_f32_e32 v182, 1.0, v182
	v_add_f32_e32 v183, 1.0, v183
	v_rcp_f32_e32 v182, v182
	v_rcp_f32_e32 v183, v183
	v_cvt_pk_bf16_f32 v187, v114, v115
	v_cvt_pk_bf16_f32 v186, v112, v113
	v_pk_mul_f32 v[112:113], v[116:117], v[180:181]
	v_pk_mul_f32 v[114:115], v[118:119], v[182:183]
	v_cvt_pk_bf16_f32 v116, v112, v113
	v_cvt_pk_bf16_f32 v117, v114, v115
	v_pk_mul_f32 v[114:115], v[120:121], v[178:179] op_sel_hi:[1,0]
	v_add_u32_e32 v112, 0x800, v179
	v_mul_f32_e32 v113, 0xbfb8aa3b, v114
	v_exp_f32_e32 v113, v113
	v_mul_f32_e32 v118, 0xbfb8aa3b, v115
	v_exp_f32_e32 v118, v118
	ds_write2_b64 v112, v[186:187], v[116:117] offset1:2
	v_add_f32_e32 v113, 1.0, v113
	v_rcp_f32_e32 v116, v113
	v_add_f32_e32 v113, 1.0, v118
	v_pk_mul_f32 v[118:119], v[122:123], v[178:179] op_sel_hi:[1,0]
	v_rcp_f32_e32 v117, v113
; DI u32x2 pk4(float a, float b, float c, float d) { u32x2 r; r.x = pk2(a, b); r.y = pk2(c, d); return r; }
; DI float fsilu(float z) { return z * fsigmoid(z); }
; template <int WI, int WGJ, class GetF, class LdF, class FinF>
; DI void staged_rows_rmw(unsigned char* lds, int tid, GetF get, LdF ld, FinF fin) {
;     ...
;         unsigned char* wrow = lds + (wj * 32 + ln) * RS + (wi * WI * 32 + 4 * h) * 2;
; #pragma unroll
;         for (int it = 0; it < WI; ++it)
; #pragma unroll
;             for (int g = 0; g < 4; ++g) *(u32x2*)(wrow + (it * 32 + 8 * g) * 2) = get(it, jt, g);
; DI void phase3b(const Params& p, unsigned char* smem, int tid) {
;     ...
;             staged_rows_rmw<4, 4>(lds, te,
;                 [&](int it, int jt, int g) { const float sc = rsj[jt];
;                     return pk4(fsilu(acc[it][jt][4 * g] * sc), fsilu(acc[it][jt][4 * g + 1] * sc), fsilu(acc[it][jt][4 * g + 2] * sc), fsilu(acc[it][jt][4 * g + 3] * sc)); },
	v_mul_f32_e32 v113, 0xbfb8aa3b, v118
	v_exp_f32_e32 v113, v113
	v_mul_f32_e32 v120, 0xbfb8aa3b, v119
	v_exp_f32_e32 v120, v120
	v_pk_mul_f32 v[114:115], v[114:115], v[116:117]
	v_add_f32_e32 v113, 1.0, v113
	v_rcp_f32_e32 v116, v113
	v_add_f32_e32 v113, 1.0, v120
	v_pk_mul_f32 v[120:121], v[124:125], v[178:179] op_sel_hi:[1,0]
	v_rcp_f32_e32 v117, v113
	v_mul_f32_e32 v113, 0xbfb8aa3b, v120
	v_exp_f32_e32 v113, v113
	v_mul_f32_e32 v122, 0xbfb8aa3b, v121
	v_exp_f32_e32 v122, v122
	v_pk_mul_f32 v[116:117], v[118:119], v[116:117]
	v_add_f32_e32 v113, 1.0, v113
	v_rcp_f32_e32 v118, v113
	v_add_f32_e32 v113, 1.0, v122
	v_pk_mul_f32 v[122:123], v[126:127], v[178:179] op_sel_hi:[1,0]
	v_pk_mul_f32 v[96:97], v[96:97], v[178:179] op_sel_hi:[1,0]
	v_mul_f32_e32 v119, 0xbfb8aa3b, v122
	v_exp_f32_e32 v124, v119
	v_mul_f32_e32 v119, 0xbfb8aa3b, v123
	v_exp_f32_e32 v125, v119
	v_rcp_f32_e32 v119, v113
	v_add_f32_e32 v113, 1.0, v124
	v_rcp_f32_e32 v124, v113
	v_add_f32_e32 v113, 1.0, v125
	v_rcp_f32_e32 v125, v113
	v_cvt_pk_bf16_f32 v114, v114, v115
	v_cvt_pk_bf16_f32 v115, v116, v117
	v_pk_mul_f32 v[116:117], v[120:121], v[118:119]
	v_pk_mul_f32 v[118:119], v[122:123], v[124:125]
	v_mul_f32_e32 v113, 0xbfb8aa3b, v96
	v_cvt_pk_bf16_f32 v116, v116, v117
	v_cvt_pk_bf16_f32 v117, v118, v119
	v_exp_f32_e32 v113, v113
	v_mul_f32_e32 v118, 0xbfb8aa3b, v97
	v_exp_f32_e32 v118, v118
	ds_write2_b64 v112, v[114:115], v[116:117] offset0:4 offset1:6
	v_add_f32_e32 v113, 1.0, v113
	v_rcp_f32_e32 v114, v113
	v_add_f32_e32 v113, 1.0, v118
	v_pk_mul_f32 v[98:99], v[98:99], v[178:179] op_sel_hi:[1,0]
	v_rcp_f32_e32 v115, v113
	v_mul_f32_e32 v113, 0xbfb8aa3b, v98
	v_exp_f32_e32 v113, v113
	v_mul_f32_e32 v116, 0xbfb8aa3b, v99
	v_exp_f32_e32 v116, v116
	v_pk_mul_f32 v[96:97], v[96:97], v[114:115]
	v_add_f32_e32 v113, 1.0, v113
	v_rcp_f32_e32 v114, v113
	v_add_f32_e32 v113, 1.0, v116
	v_pk_mul_f32 v[100:101], v[100:101], v[178:179] op_sel_hi:[1,0]
	v_rcp_f32_e32 v115, v113
	v_mul_f32_e32 v113, 0xbfb8aa3b, v100
	v_exp_f32_e32 v113, v113
	v_mul_f32_e32 v116, 0xbfb8aa3b, v101
	v_exp_f32_e32 v116, v116
	v_pk_mul_f32 v[102:103], v[102:103], v[178:179] op_sel_hi:[1,0]
	v_pk_mul_f32 v[98:99], v[98:99], v[114:115]
	v_add_f32_e32 v113, 1.0, v113
	v_mul_f32_e32 v115, 0xbfb8aa3b, v102
	v_rcp_f32_e32 v114, v113
	v_add_f32_e32 v113, 1.0, v116
	v_exp_f32_e32 v116, v115
	v_mul_f32_e32 v115, 0xbfb8aa3b, v103
	v_exp_f32_e32 v117, v115
	v_rcp_f32_e32 v115, v113
	v_add_f32_e32 v113, 1.0, v116
	v_rcp_f32_e32 v116, v113
	v_add_f32_e32 v113, 1.0, v117
	v_rcp_f32_e32 v117, v113
	v_cvt_pk_bf16_f32 v96, v96, v97
	v_cvt_pk_bf16_f32 v97, v98, v99
	v_pk_mul_f32 v[98:99], v[100:101], v[114:115]
	v_pk_mul_f32 v[100:101], v[102:103], v[116:117]
	v_cvt_pk_bf16_f32 v98, v98, v99
	v_cvt_pk_bf16_f32 v99, v100, v101
	v_pk_mul_f32 v[100:101], v[104:105], v[178:179] op_sel_hi:[1,0]
	ds_write2_b64 v112, v[96:97], v[98:99] offset0:8 offset1:10
	v_mul_f32_e32 v102, 0xbfb8aa3b, v100
	v_mul_f32_e32 v103, 0xbfb8aa3b, v101
	v_exp_f32_e32 v102, v102
	v_exp_f32_e32 v103, v103
	v_pk_mul_f32 v[98:99], v[106:107], v[178:179] op_sel_hi:[1,0]
	v_pk_mul_f32 v[80:81], v[80:81], v[178:179] op_sel_hi:[1,0]
	v_add_f32_e32 v96, 1.0, v102
	v_add_f32_e32 v97, 1.0, v103
	v_mul_f32_e32 v102, 0xbfb8aa3b, v98
	v_mul_f32_e32 v103, 0xbfb8aa3b, v99
	v_rcp_f32_e32 v96, v96
	v_rcp_f32_e32 v97, v97
	v_exp_f32_e32 v102, v102
	v_exp_f32_e32 v103, v103
	v_pk_mul_f32 v[82:83], v[82:83], v[178:179] op_sel_hi:[1,0]
	v_pk_mul_f32 v[96:97], v[100:101], v[96:97]
	v_add_f32_e32 v100, 1.0, v102
	v_add_f32_e32 v101, 1.0, v103
	v_pk_mul_f32 v[102:103], v[108:109], v[178:179] op_sel_hi:[1,0]
	v_rcp_f32_e32 v100, v100
	v_mul_f32_e32 v104, 0xbfb8aa3b, v102
	v_mul_f32_e32 v105, 0xbfb8aa3b, v103
	v_rcp_f32_e32 v101, v101
	v_exp_f32_e32 v104, v104
	v_exp_f32_e32 v105, v105
	v_cvt_pk_bf16_f32 v96, v96, v97
	v_pk_mul_f32 v[98:99], v[98:99], v[100:101]
	v_add_f32_e32 v100, 1.0, v104
	v_add_f32_e32 v101, 1.0, v105
	v_pk_mul_f32 v[104:105], v[110:111], v[178:179] op_sel_hi:[1,0]
	v_rcp_f32_e32 v100, v100
	v_mul_f32_e32 v106, 0xbfb8aa3b, v104
	v_mul_f32_e32 v107, 0xbfb8aa3b, v105
	v_exp_f32_e32 v106, v106
	v_exp_f32_e32 v107, v107
	v_rcp_f32_e32 v101, v101
	v_cvt_pk_bf16_f32 v97, v98, v99
	v_add_f32_e32 v106, 1.0, v106
	v_add_f32_e32 v107, 1.0, v107
	v_rcp_f32_e32 v106, v106
	v_rcp_f32_e32 v107, v107
	v_pk_mul_f32 v[98:99], v[102:103], v[100:101]
	v_pk_mul_f32 v[84:85], v[84:85], v[178:179] op_sel_hi:[1,0]
	v_cvt_pk_bf16_f32 v98, v98, v99
	v_pk_mul_f32 v[100:101], v[104:105], v[106:107]
	v_pk_mul_f32 v[86:87], v[86:87], v[178:179] op_sel_hi:[1,0]
	v_cvt_pk_bf16_f32 v99, v100, v101
	v_mul_f32_e32 v100, 0xbfb8aa3b, v80
	v_mul_f32_e32 v101, 0xbfb8aa3b, v81
	v_exp_f32_e32 v100, v100
	v_exp_f32_e32 v101, v101
	ds_write2_b64 v112, v[96:97], v[98:99] offset0:12 offset1:14
	v_mul_f32_e32 v98, 0xbfb8aa3b, v82
	v_add_f32_e32 v96, 1.0, v100
	v_add_f32_e32 v97, 1.0, v101
	v_mul_f32_e32 v99, 0xbfb8aa3b, v83
	v_rcp_f32_e32 v96, v96
	v_rcp_f32_e32 v97, v97
	v_exp_f32_e32 v98, v98
	v_exp_f32_e32 v99, v99
	v_pk_mul_f32 v[64:65], v[64:65], v[178:179] op_sel_hi:[1,0]
	v_pk_mul_f32 v[80:81], v[80:81], v[96:97]
	v_add_f32_e32 v96, 1.0, v98
	v_add_f32_e32 v97, 1.0, v99
	v_mul_f32_e32 v98, 0xbfb8aa3b, v84
	v_mul_f32_e32 v99, 0xbfb8aa3b, v85
	v_rcp_f32_e32 v96, v96
	v_rcp_f32_e32 v97, v97
	v_exp_f32_e32 v98, v98
	v_exp_f32_e32 v99, v99
	v_cvt_pk_bf16_f32 v80, v80, v81
	v_pk_mul_f32 v[82:83], v[82:83], v[96:97]
	v_add_f32_e32 v96, 1.0, v98
	v_add_f32_e32 v97, 1.0, v99
	v_mul_f32_e32 v98, 0xbfb8aa3b, v86
	v_mul_f32_e32 v99, 0xbfb8aa3b, v87
	v_exp_f32_e32 v98, v98
	v_exp_f32_e32 v99, v99
; DI u32x2 pk4(float a, float b, float c, float d) { u32x2 r; r.x = pk2(a, b); r.y = pk2(c, d); return r; }
; DI float fsilu(float z) { return z * fsigmoid(z); }
; template <int WI, int WGJ, class GetF, class LdF, class FinF>
; DI void staged_rows_rmw(unsigned char* lds, int tid, GetF get, LdF ld, FinF fin) {
;     ...
;         unsigned char* wrow = lds + (wj * 32 + ln) * RS + (wi * WI * 32 + 4 * h) * 2;
; #pragma unroll
;         for (int it = 0; it < WI; ++it)
; #pragma unroll
;             for (int g = 0; g < 4; ++g) *(u32x2*)(wrow + (it * 32 + 8 * g) * 2) = get(it, jt, g);
;         constexpr int NGRP = 2, GSZ = NIT / NGRP;
;         __syncthreads();
; DI void phase3b(const Params& p, unsigned char* smem, int tid) {
;     ...
;             staged_rows_rmw<4, 4>(lds, te,
;                 [&](int it, int jt, int g) { const float sc = rsj[jt];
;                     return pk4(fsilu(acc[it][jt][4 * g] * sc), fsilu(acc[it][jt][4 * g + 1] * sc), fsilu(acc[it][jt][4 * g + 2] * sc), fsilu(acc[it][jt][4 * g + 3] * sc)); },
	v_rcp_f32_e32 v96, v96
	v_rcp_f32_e32 v97, v97
	v_add_f32_e32 v98, 1.0, v98
	v_add_f32_e32 v99, 1.0, v99
	v_rcp_f32_e32 v98, v98
	v_rcp_f32_e32 v99, v99
	v_cvt_pk_bf16_f32 v81, v82, v83
	v_pk_mul_f32 v[82:83], v[84:85], v[96:97]
	v_pk_mul_f32 v[66:67], v[66:67], v[178:179] op_sel_hi:[1,0]
	v_pk_mul_f32 v[84:85], v[86:87], v[98:99]
	v_cvt_pk_bf16_f32 v82, v82, v83
	v_cvt_pk_bf16_f32 v83, v84, v85
	v_pk_mul_f32 v[84:85], v[88:89], v[178:179] op_sel_hi:[1,0]
	ds_write2_b64 v112, v[80:81], v[82:83] offset0:16 offset1:18
	v_mul_f32_e32 v86, 0xbfb8aa3b, v84
	v_mul_f32_e32 v87, 0xbfb8aa3b, v85
	v_exp_f32_e32 v86, v86
	v_exp_f32_e32 v87, v87
	v_pk_mul_f32 v[82:83], v[90:91], v[178:179] op_sel_hi:[1,0]
	v_pk_mul_f32 v[68:69], v[68:69], v[178:179] op_sel_hi:[1,0]
	v_add_f32_e32 v80, 1.0, v86
	v_add_f32_e32 v81, 1.0, v87
	v_mul_f32_e32 v86, 0xbfb8aa3b, v82
	v_mul_f32_e32 v87, 0xbfb8aa3b, v83
	v_rcp_f32_e32 v80, v80
	v_rcp_f32_e32 v81, v81
	v_exp_f32_e32 v86, v86
	v_exp_f32_e32 v87, v87
	v_pk_mul_f32 v[70:71], v[70:71], v[178:179] op_sel_hi:[1,0]
	v_pk_mul_f32 v[80:81], v[84:85], v[80:81]
	v_add_f32_e32 v84, 1.0, v86
	v_add_f32_e32 v85, 1.0, v87
	v_pk_mul_f32 v[86:87], v[92:93], v[178:179] op_sel_hi:[1,0]
	v_rcp_f32_e32 v84, v84
	v_mul_f32_e32 v88, 0xbfb8aa3b, v86
	v_mul_f32_e32 v89, 0xbfb8aa3b, v87
	v_rcp_f32_e32 v85, v85
	v_exp_f32_e32 v88, v88
	v_exp_f32_e32 v89, v89
	v_cvt_pk_bf16_f32 v80, v80, v81
	v_pk_mul_f32 v[82:83], v[82:83], v[84:85]
	v_add_f32_e32 v84, 1.0, v88
	v_add_f32_e32 v85, 1.0, v89
	v_pk_mul_f32 v[88:89], v[94:95], v[178:179] op_sel_hi:[1,0]
	v_rcp_f32_e32 v84, v84
	v_mul_f32_e32 v90, 0xbfb8aa3b, v88
	v_mul_f32_e32 v91, 0xbfb8aa3b, v89
	v_exp_f32_e32 v90, v90
	v_exp_f32_e32 v91, v91
	v_rcp_f32_e32 v85, v85
	v_cvt_pk_bf16_f32 v81, v82, v83
	v_add_f32_e32 v90, 1.0, v90
	v_add_f32_e32 v91, 1.0, v91
	v_rcp_f32_e32 v90, v90
	v_rcp_f32_e32 v91, v91
	v_pk_mul_f32 v[82:83], v[86:87], v[84:85]
	s_lshr_b32 s22, s24, 2
	v_cvt_pk_bf16_f32 v82, v82, v83
	v_pk_mul_f32 v[84:85], v[88:89], v[90:91]
	s_cmp_lt_u32 s25, 4
	v_cvt_pk_bf16_f32 v83, v84, v85
	v_mul_f32_e32 v84, 0xbfb8aa3b, v64
	v_mul_f32_e32 v85, 0xbfb8aa3b, v65
	v_exp_f32_e32 v84, v84
	v_exp_f32_e32 v85, v85
	ds_write2_b64 v112, v[80:81], v[82:83] offset0:20 offset1:22
	v_mul_f32_e32 v82, 0xbfb8aa3b, v66
	v_add_f32_e32 v80, 1.0, v84
	v_add_f32_e32 v81, 1.0, v85
	v_mul_f32_e32 v83, 0xbfb8aa3b, v67
	v_rcp_f32_e32 v80, v80
	v_rcp_f32_e32 v81, v81
	v_exp_f32_e32 v82, v82
	v_exp_f32_e32 v83, v83
	s_cselect_b32 s23, s36, 0x398fc00
	v_pk_mul_f32 v[64:65], v[64:65], v[80:81]
	v_add_f32_e32 v80, 1.0, v82
	v_add_f32_e32 v81, 1.0, v83
	v_mul_f32_e32 v82, 0xbfb8aa3b, v68
	v_mul_f32_e32 v83, 0xbfb8aa3b, v69
	v_rcp_f32_e32 v80, v80
	v_rcp_f32_e32 v81, v81
	v_exp_f32_e32 v82, v82
	v_exp_f32_e32 v83, v83
	v_cvt_pk_bf16_f32 v64, v64, v65
	v_pk_mul_f32 v[66:67], v[66:67], v[80:81]
	v_add_f32_e32 v80, 1.0, v82
	v_add_f32_e32 v81, 1.0, v83
	v_mul_f32_e32 v82, 0xbfb8aa3b, v70
	v_mul_f32_e32 v83, 0xbfb8aa3b, v71
	v_exp_f32_e32 v82, v82
	v_exp_f32_e32 v83, v83
	v_rcp_f32_e32 v80, v80
	v_rcp_f32_e32 v81, v81
	v_add_f32_e32 v82, 1.0, v82
	v_add_f32_e32 v83, 1.0, v83
	v_rcp_f32_e32 v82, v82
	v_rcp_f32_e32 v83, v83
	v_cvt_pk_bf16_f32 v65, v66, v67
	v_pk_mul_f32 v[66:67], v[68:69], v[80:81]
	s_add_u32 s23, s56, s23
	v_pk_mul_f32 v[68:69], v[70:71], v[82:83]
	v_cvt_pk_bf16_f32 v66, v66, v67
	v_cvt_pk_bf16_f32 v67, v68, v69
	v_pk_mul_f32 v[68:69], v[72:73], v[178:179] op_sel_hi:[1,0]
	ds_write2_b64 v112, v[64:65], v[66:67] offset0:24 offset1:26
	v_mul_f32_e32 v70, 0xbfb8aa3b, v68
	v_mul_f32_e32 v71, 0xbfb8aa3b, v69
	v_exp_f32_e32 v70, v70
	v_exp_f32_e32 v71, v71
	v_pk_mul_f32 v[66:67], v[74:75], v[178:179] op_sel_hi:[1,0]
	s_addc_u32 s24, s57, 0
	v_add_f32_e32 v64, 1.0, v70
	v_add_f32_e32 v65, 1.0, v71
	v_mul_f32_e32 v70, 0xbfb8aa3b, v66
	v_mul_f32_e32 v71, 0xbfb8aa3b, v67
	v_rcp_f32_e32 v64, v64
	v_rcp_f32_e32 v65, v65
	v_exp_f32_e32 v70, v70
	v_exp_f32_e32 v71, v71
	s_lshl_b32 s22, s22, 9
	v_pk_mul_f32 v[64:65], v[68:69], v[64:65]
	v_add_f32_e32 v68, 1.0, v70
	v_add_f32_e32 v69, 1.0, v71
	v_pk_mul_f32 v[70:71], v[76:77], v[178:179] op_sel_hi:[1,0]
	v_rcp_f32_e32 v68, v68
	v_mul_f32_e32 v72, 0xbfb8aa3b, v70
	v_mul_f32_e32 v73, 0xbfb8aa3b, v71
	v_rcp_f32_e32 v69, v69
	v_exp_f32_e32 v72, v72
	v_exp_f32_e32 v73, v73
	s_and_b32 s22, s22, 0x600
	v_pk_mul_f32 v[66:67], v[66:67], v[68:69]
	v_add_f32_e32 v68, 1.0, v72
	v_add_f32_e32 v69, 1.0, v73
	v_pk_mul_f32 v[72:73], v[78:79], v[178:179] op_sel_hi:[1,0]
	v_rcp_f32_e32 v68, v68
	v_mul_f32_e32 v74, 0xbfb8aa3b, v72
	v_mul_f32_e32 v75, 0xbfb8aa3b, v73
	v_exp_f32_e32 v74, v74
	v_exp_f32_e32 v75, v75
	v_rcp_f32_e32 v69, v69
	s_add_u32 s22, s23, s22
	v_add_f32_e32 v74, 1.0, v74
	v_add_f32_e32 v75, 1.0, v75
	v_rcp_f32_e32 v74, v74
	v_rcp_f32_e32 v75, v75
	v_cvt_pk_bf16_f32 v64, v64, v65
	v_cvt_pk_bf16_f32 v65, v66, v67
	v_pk_mul_f32 v[66:67], v[70:71], v[68:69]
	v_pk_mul_f32 v[68:69], v[72:73], v[74:75]
	s_mov_b32 s14, 0
	s_addc_u32 s23, s24, 0
	v_cvt_pk_bf16_f32 v66, v66, v67
	v_cvt_pk_bf16_f32 v67, v68, v69
	s_mov_b64 s[24:25], -1
	ds_write2_b64 v112, v[64:65], v[66:67] offset0:28 offset1:30
	s_waitcnt lgkmcnt(0)
	s_barrier
; DI unsigned pk2(float lo, float hi) { f32x2 v = {lo, hi}; bf2_t b = __builtin_convertvector(v, bf2_t); return __builtin_bit_cast(unsigned, b); }
; DI float bf_lo(unsigned u) { return __uint_as_float(u << 16); }
; DI float bf_hi(unsigned u) { return __uint_as_float(u & 0xffff0000u); }
; template <int WI, int WGJ, class GetF, class LdF, class FinF>
; DI void staged_rows_rmw(unsigned char* lds, int tid, GetF get, LdF ld, FinF fin) {
;     ...
;         for (int gq = 0; gq < NGRP; ++gq) {
;             decltype(ld(0, 0)) fetched[GSZ];
; #pragma unroll
;             for (int c = 0; c < GSZ; ++c) {
;                 const int idx = tid + (gq * GSZ + c) * NT, lr = idx / NCH, ch = idx % NCH;
;                 fetched[c] = ld((lr >> 5) * 64 + jt * 32 + (lr & 31), ch * 8);
;             }
; #pragma unroll
;             for (int c = 0; c < GSZ; ++c) {
;                 const int idx = tid + (gq * GSZ + c) * NT, lr = idx / NCH, ch = idx % NCH;
;                 const u32x4 v = *(const u32x4*)(lds + lr * RS + ch * 16);
;                 fin((lr >> 5) * 64 + jt * 32 + (lr & 31), ch * 8, v, fetched[c]);
;             }
; DI void phase3b(const Params& p, unsigned char* smem, int tid) {
;     ...
;                 [&](int row, int col) { return *(const u32x4*)(obuf + (size_t)(r0 + row) * 1024 + col); },
;                 [&](int row, int col, u32x4 v, u32x4 o) { u32x4 w;
; #pragma unroll
;                     for (int e = 0; e < 4; ++e) w[e] = pk2(bf_lo(o[e]) * bf_lo(v[e]), bf_hi(o[e]) * bf_hi(v[e]));
;                     *(u32x4*)(obuf + (size_t)(r0 + row) * 1024 + col) = w; });
	ds_read_b128 v[64:67], v197 offset:2048
	ds_read_b128 v[68:71], v197 offset:10496
	ds_read_b128 v[72:75], v197 offset:18944
	ds_read_b128 v[76:79], v197 offset:27392
	s_waitcnt lgkmcnt(3)
	v_lshlrev_b32_e32 v80, 16, v64
	v_and_b32_e32 v81, 0xffff0000, v64
	v_lshlrev_b32_e32 v82, 16, v65
	v_and_b32_e32 v83, 0xffff0000, v65
	v_lshlrev_b32_e32 v84, 16, v66
	v_and_b32_e32 v85, 0xffff0000, v66
	v_lshlrev_b32_e32 v86, 16, v67
	v_and_b32_e32 v87, 0xffff0000, v67
	s_waitcnt vmcnt(11)
	v_lshlrev_b32_e32 v88, 16, v188
	v_and_b32_e32 v89, 0xffff0000, v188
	v_lshlrev_b32_e32 v90, 16, v189
	v_and_b32_e32 v91, 0xffff0000, v189
	v_lshlrev_b32_e32 v92, 16, v190
	v_and_b32_e32 v93, 0xffff0000, v190
	v_lshlrev_b32_e32 v94, 16, v191
	v_and_b32_e32 v95, 0xffff0000, v191
	v_pk_mul_f32 v[88:89], v[88:89], v[80:81]
	v_pk_mul_f32 v[90:91], v[90:91], v[82:83]
	v_pk_mul_f32 v[92:93], v[92:93], v[84:85]
	v_pk_mul_f32 v[94:95], v[94:95], v[86:87]
	v_cvt_pk_bf16_f32 v188, v88, v89
	v_cvt_pk_bf16_f32 v189, v90, v91
	v_cvt_pk_bf16_f32 v190, v92, v93
	v_cvt_pk_bf16_f32 v191, v94, v95
	global_store_dwordx4 v196, v[188:191], s[100:101] sc1
	s_waitcnt lgkmcnt(2)
	v_lshlrev_b32_e32 v80, 16, v68
	v_and_b32_e32 v81, 0xffff0000, v68
	v_lshlrev_b32_e32 v82, 16, v69
	v_and_b32_e32 v83, 0xffff0000, v69
	v_lshlrev_b32_e32 v84, 16, v70
	v_and_b32_e32 v85, 0xffff0000, v70
	v_lshlrev_b32_e32 v86, 16, v71
	v_and_b32_e32 v87, 0xffff0000, v71
	s_waitcnt vmcnt(11)
	v_lshlrev_b32_e32 v88, 16, v192
	v_and_b32_e32 v89, 0xffff0000, v192
	v_lshlrev_b32_e32 v90, 16, v193
	v_and_b32_e32 v91, 0xffff0000, v193
	v_lshlrev_b32_e32 v92, 16, v194
	v_and_b32_e32 v93, 0xffff0000, v194
	v_lshlrev_b32_e32 v94, 16, v195
	v_and_b32_e32 v95, 0xffff0000, v195
	v_pk_mul_f32 v[88:89], v[88:89], v[80:81]
	v_pk_mul_f32 v[90:91], v[90:91], v[82:83]
	v_pk_mul_f32 v[92:93], v[92:93], v[84:85]
	v_pk_mul_f32 v[94:95], v[94:95], v[86:87]
	v_cvt_pk_bf16_f32 v192, v88, v89
	v_cvt_pk_bf16_f32 v193, v90, v91
	v_cvt_pk_bf16_f32 v194, v92, v93
	v_cvt_pk_bf16_f32 v195, v94, v95
	v_add_u32_e32 v245, 0x8000, v196
	global_store_dwordx4 v245, v[192:195], s[100:101] sc1
	s_waitcnt lgkmcnt(1)
	v_lshlrev_b32_e32 v80, 16, v72
	v_and_b32_e32 v81, 0xffff0000, v72
	v_lshlrev_b32_e32 v82, 16, v73
	v_and_b32_e32 v83, 0xffff0000, v73
	v_lshlrev_b32_e32 v84, 16, v74
	v_and_b32_e32 v85, 0xffff0000, v74
	v_lshlrev_b32_e32 v86, 16, v75
	v_and_b32_e32 v87, 0xffff0000, v75
	s_waitcnt vmcnt(11)
	v_lshlrev_b32_e32 v88, 16, v200
	v_and_b32_e32 v89, 0xffff0000, v200
	v_lshlrev_b32_e32 v90, 16, v201
	v_and_b32_e32 v91, 0xffff0000, v201
	v_lshlrev_b32_e32 v92, 16, v202
	v_and_b32_e32 v93, 0xffff0000, v202
	v_lshlrev_b32_e32 v94, 16, v203
	v_and_b32_e32 v95, 0xffff0000, v203
	v_pk_mul_f32 v[88:89], v[88:89], v[80:81]
	v_pk_mul_f32 v[90:91], v[90:91], v[82:83]
	v_pk_mul_f32 v[92:93], v[92:93], v[84:85]
	v_pk_mul_f32 v[94:95], v[94:95], v[86:87]
	v_cvt_pk_bf16_f32 v200, v88, v89
	v_cvt_pk_bf16_f32 v201, v90, v91
	v_cvt_pk_bf16_f32 v202, v92, v93
	v_cvt_pk_bf16_f32 v203, v94, v95
	v_add_u32_e32 v244, 0x20000, v196
	global_store_dwordx4 v244, v[200:203], s[100:101] sc1
	s_waitcnt lgkmcnt(0)
	v_lshlrev_b32_e32 v80, 16, v76
	v_and_b32_e32 v81, 0xffff0000, v76
	v_lshlrev_b32_e32 v82, 16, v77
	v_and_b32_e32 v83, 0xffff0000, v77
	v_lshlrev_b32_e32 v84, 16, v78
	v_and_b32_e32 v85, 0xffff0000, v78
	v_lshlrev_b32_e32 v86, 16, v79
	v_and_b32_e32 v87, 0xffff0000, v79
	s_waitcnt vmcnt(11)
	v_lshlrev_b32_e32 v88, 16, v204
	v_and_b32_e32 v89, 0xffff0000, v204
	v_lshlrev_b32_e32 v90, 16, v205
	v_and_b32_e32 v91, 0xffff0000, v205
	v_lshlrev_b32_e32 v92, 16, v206
	v_and_b32_e32 v93, 0xffff0000, v206
	v_lshlrev_b32_e32 v94, 16, v207
	v_and_b32_e32 v95, 0xffff0000, v207
	v_pk_mul_f32 v[88:89], v[88:89], v[80:81]
	v_pk_mul_f32 v[90:91], v[90:91], v[82:83]
	v_pk_mul_f32 v[92:93], v[92:93], v[84:85]
	v_pk_mul_f32 v[94:95], v[94:95], v[86:87]
	v_cvt_pk_bf16_f32 v204, v88, v89
	v_cvt_pk_bf16_f32 v205, v90, v91
	v_cvt_pk_bf16_f32 v206, v92, v93
	v_cvt_pk_bf16_f32 v207, v94, v95
	v_add_u32_e32 v245, 0x28000, v196
	global_store_dwordx4 v245, v[204:207], s[100:101] sc1
	v_add_u32_e32 v244, 0x50000, v196
	global_load_dwordx4 v[188:191], v244, s[100:101]
	v_add_u32_e32 v245, 0x58000, v196
	global_load_dwordx4 v[192:195], v245, s[100:101]
	v_add_u32_e32 v244, 0x70000, v196
	global_load_dwordx4 v[200:203], v244, s[100:101]
	v_add_u32_e32 v245, 0x78000, v196
	global_load_dwordx4 v[204:207], v245, s[100:101]
	ds_read_b128 v[64:67], v197 offset:35840
	ds_read_b128 v[68:71], v197 offset:44288
	ds_read_b128 v[72:75], v197 offset:52736
	ds_read_b128 v[76:79], v197 offset:61184
	s_waitcnt lgkmcnt(3)
	v_lshlrev_b32_e32 v80, 16, v64
	v_and_b32_e32 v81, 0xffff0000, v64
	v_lshlrev_b32_e32 v82, 16, v65
	v_and_b32_e32 v83, 0xffff0000, v65
	v_lshlrev_b32_e32 v84, 16, v66
	v_and_b32_e32 v85, 0xffff0000, v66
	v_lshlrev_b32_e32 v86, 16, v67
	v_and_b32_e32 v87, 0xffff0000, v67
	s_waitcnt vmcnt(15)
	v_lshlrev_b32_e32 v88, 16, v208
	v_and_b32_e32 v89, 0xffff0000, v208
	v_lshlrev_b32_e32 v90, 16, v209
	v_and_b32_e32 v91, 0xffff0000, v209
	v_lshlrev_b32_e32 v92, 16, v210
	v_and_b32_e32 v93, 0xffff0000, v210
	v_lshlrev_b32_e32 v94, 16, v211
	v_and_b32_e32 v95, 0xffff0000, v211
	v_pk_mul_f32 v[88:89], v[88:89], v[80:81]
	v_pk_mul_f32 v[90:91], v[90:91], v[82:83]
	v_pk_mul_f32 v[92:93], v[92:93], v[84:85]
	v_pk_mul_f32 v[94:95], v[94:95], v[86:87]
	v_cvt_pk_bf16_f32 v208, v88, v89
	v_cvt_pk_bf16_f32 v209, v90, v91
	v_cvt_pk_bf16_f32 v210, v92, v93
	v_cvt_pk_bf16_f32 v211, v94, v95
	v_add_u32_e32 v244, 0x40000, v196
	global_store_dwordx4 v244, v[208:211], s[100:101] sc1
	s_waitcnt lgkmcnt(2)
; DI unsigned pk2(float lo, float hi) { f32x2 v = {lo, hi}; bf2_t b = __builtin_convertvector(v, bf2_t); return __builtin_bit_cast(unsigned, b); }
; DI u32x2 pk4(float a, float b, float c, float d) { u32x2 r; r.x = pk2(a, b); r.y = pk2(c, d); return r; }
; DI float bf_lo(unsigned u) { return __uint_as_float(u << 16); }
; DI float bf_hi(unsigned u) { return __uint_as_float(u & 0xffff0000u); }
; DI float fsilu(float z) { return z * fsigmoid(z); }
; template <int WI, int WGJ, class GetF, class LdF, class FinF>
; DI void staged_rows_rmw(unsigned char* lds, int tid, GetF get, LdF ld, FinF fin) {
;     ...
;         for (int gq = 0; gq < NGRP; ++gq) {
;             decltype(ld(0, 0)) fetched[GSZ];
; #pragma unroll
;             for (int c = 0; c < GSZ; ++c) {
;                 const int idx = tid + (gq * GSZ + c) * NT, lr = idx / NCH, ch = idx % NCH;
;                 fetched[c] = ld((lr >> 5) * 64 + jt * 32 + (lr & 31), ch * 8);
;             }
; #pragma unroll
;             for (int c = 0; c < GSZ; ++c) {
;                 const int idx = tid + (gq * GSZ + c) * NT, lr = idx / NCH, ch = idx % NCH;
;                 const u32x4 v = *(const u32x4*)(lds + lr * RS + ch * 16);
;                 fin((lr >> 5) * 64 + jt * 32 + (lr & 31), ch * 8, v, fetched[c]);
;             }
; DI void phase3b(const Params& p, unsigned char* smem, int tid) {
;     ...
;             staged_rows_rmw<4, 4>(lds, te,
;                 [&](int it, int jt, int g) { const float sc = rsj[jt];
;                     return pk4(fsilu(acc[it][jt][4 * g] * sc), fsilu(acc[it][jt][4 * g + 1] * sc), fsilu(acc[it][jt][4 * g + 2] * sc), fsilu(acc[it][jt][4 * g + 3] * sc)); },
;                 [&](int row, int col) { return *(const u32x4*)(obuf + (size_t)(r0 + row) * 1024 + col); },
;                 [&](int row, int col, u32x4 v, u32x4 o) { u32x4 w;
; #pragma unroll
;                     for (int e = 0; e < 4; ++e) w[e] = pk2(bf_lo(o[e]) * bf_lo(v[e]), bf_hi(o[e]) * bf_hi(v[e]));
;                     *(u32x4*)(obuf + (size_t)(r0 + row) * 1024 + col) = w; });
	v_lshlrev_b32_e32 v80, 16, v68
	v_and_b32_e32 v81, 0xffff0000, v68
	v_lshlrev_b32_e32 v82, 16, v69
	v_and_b32_e32 v83, 0xffff0000, v69
	v_lshlrev_b32_e32 v84, 16, v70
	v_and_b32_e32 v85, 0xffff0000, v70
	v_lshlrev_b32_e32 v86, 16, v71
	v_and_b32_e32 v87, 0xffff0000, v71
	s_waitcnt vmcnt(15)
	v_lshlrev_b32_e32 v88, 16, v212
	v_and_b32_e32 v89, 0xffff0000, v212
	v_lshlrev_b32_e32 v90, 16, v213
	v_and_b32_e32 v91, 0xffff0000, v213
	v_lshlrev_b32_e32 v92, 16, v214
	v_and_b32_e32 v93, 0xffff0000, v214
	v_lshlrev_b32_e32 v94, 16, v215
	v_and_b32_e32 v95, 0xffff0000, v215
	v_pk_mul_f32 v[88:89], v[88:89], v[80:81]
	v_pk_mul_f32 v[90:91], v[90:91], v[82:83]
	v_pk_mul_f32 v[92:93], v[92:93], v[84:85]
	v_pk_mul_f32 v[94:95], v[94:95], v[86:87]
	v_cvt_pk_bf16_f32 v212, v88, v89
	v_cvt_pk_bf16_f32 v213, v90, v91
	v_cvt_pk_bf16_f32 v214, v92, v93
	v_cvt_pk_bf16_f32 v215, v94, v95
	v_add_u32_e32 v245, 0x48000, v196
	global_store_dwordx4 v245, v[212:215], s[100:101] sc1
	s_waitcnt lgkmcnt(1)
	v_lshlrev_b32_e32 v80, 16, v72
	v_and_b32_e32 v81, 0xffff0000, v72
	v_lshlrev_b32_e32 v82, 16, v73
	v_and_b32_e32 v83, 0xffff0000, v73
	v_lshlrev_b32_e32 v84, 16, v74
	v_and_b32_e32 v85, 0xffff0000, v74
	v_lshlrev_b32_e32 v86, 16, v75
	v_and_b32_e32 v87, 0xffff0000, v75
	s_waitcnt vmcnt(15)
	v_lshlrev_b32_e32 v88, 16, v216
	v_and_b32_e32 v89, 0xffff0000, v216
	v_lshlrev_b32_e32 v90, 16, v217
	v_and_b32_e32 v91, 0xffff0000, v217
	v_lshlrev_b32_e32 v92, 16, v218
	v_and_b32_e32 v93, 0xffff0000, v218
	v_lshlrev_b32_e32 v94, 16, v219
	v_and_b32_e32 v95, 0xffff0000, v219
	v_pk_mul_f32 v[88:89], v[88:89], v[80:81]
	v_pk_mul_f32 v[90:91], v[90:91], v[82:83]
	v_pk_mul_f32 v[92:93], v[92:93], v[84:85]
	v_pk_mul_f32 v[94:95], v[94:95], v[86:87]
	v_cvt_pk_bf16_f32 v216, v88, v89
	v_cvt_pk_bf16_f32 v217, v90, v91
	v_cvt_pk_bf16_f32 v218, v92, v93
	v_cvt_pk_bf16_f32 v219, v94, v95
	v_add_u32_e32 v244, 0x60000, v196
	global_store_dwordx4 v244, v[216:219], s[100:101] sc1
	s_waitcnt lgkmcnt(0)
	v_lshlrev_b32_e32 v80, 16, v76
	v_and_b32_e32 v81, 0xffff0000, v76
	v_lshlrev_b32_e32 v82, 16, v77
	v_and_b32_e32 v83, 0xffff0000, v77
	v_lshlrev_b32_e32 v84, 16, v78
	v_and_b32_e32 v85, 0xffff0000, v78
	v_lshlrev_b32_e32 v86, 16, v79
	v_and_b32_e32 v87, 0xffff0000, v79
	s_waitcnt vmcnt(15)
	v_lshlrev_b32_e32 v88, 16, v220
	v_and_b32_e32 v89, 0xffff0000, v220
	v_lshlrev_b32_e32 v90, 16, v221
	v_and_b32_e32 v91, 0xffff0000, v221
	v_lshlrev_b32_e32 v92, 16, v222
	v_and_b32_e32 v93, 0xffff0000, v222
	v_lshlrev_b32_e32 v94, 16, v223
	v_and_b32_e32 v95, 0xffff0000, v223
	v_pk_mul_f32 v[88:89], v[88:89], v[80:81]
	v_pk_mul_f32 v[90:91], v[90:91], v[82:83]
	v_pk_mul_f32 v[92:93], v[92:93], v[84:85]
	v_pk_mul_f32 v[94:95], v[94:95], v[86:87]
	v_cvt_pk_bf16_f32 v220, v88, v89
	v_cvt_pk_bf16_f32 v221, v90, v91
	v_cvt_pk_bf16_f32 v222, v92, v93
	v_cvt_pk_bf16_f32 v223, v94, v95
	v_add_u32_e32 v245, 0x68000, v196
	global_store_dwordx4 v245, v[220:223], s[100:101] sc1
	v_pk_mul_f32 v[48:49], v[48:49], v[176:177] op_sel_hi:[1,0]
	v_pk_mul_f32 v[50:51], v[50:51], v[176:177] op_sel_hi:[1,0]
	v_mul_f32_e32 v64, 0xbfb8aa3b, v48
	v_mul_f32_e32 v65, 0xbfb8aa3b, v49
	v_exp_f32_e32 v64, v64
	v_exp_f32_e32 v65, v65
	v_mul_f32_e32 v66, 0xbfb8aa3b, v50
	v_mul_f32_e32 v67, 0xbfb8aa3b, v51
	v_add_f32_e32 v64, 1.0, v64
	v_add_f32_e32 v65, 1.0, v65
	v_rcp_f32_e32 v64, v64
	v_rcp_f32_e32 v65, v65
	v_exp_f32_e32 v66, v66
	v_exp_f32_e32 v67, v67
	v_pk_mul_f32 v[52:53], v[52:53], v[176:177] op_sel_hi:[1,0]
	v_pk_mul_f32 v[48:49], v[48:49], v[64:65]
	v_add_f32_e32 v64, 1.0, v66
	v_add_f32_e32 v65, 1.0, v67
	v_mul_f32_e32 v66, 0xbfb8aa3b, v52
	v_mul_f32_e32 v67, 0xbfb8aa3b, v53
	v_rcp_f32_e32 v64, v64
	v_rcp_f32_e32 v65, v65
	v_exp_f32_e32 v66, v66
	v_exp_f32_e32 v67, v67
	v_pk_mul_f32 v[54:55], v[54:55], v[176:177] op_sel_hi:[1,0]
	v_pk_mul_f32 v[50:51], v[50:51], v[64:65]
	v_add_f32_e32 v64, 1.0, v66
	v_add_f32_e32 v65, 1.0, v67
	v_mul_f32_e32 v66, 0xbfb8aa3b, v54
	v_mul_f32_e32 v67, 0xbfb8aa3b, v55
	v_exp_f32_e32 v66, v66
	v_exp_f32_e32 v67, v67
	v_rcp_f32_e32 v64, v64
	v_rcp_f32_e32 v65, v65
	v_add_f32_e32 v66, 1.0, v66
	v_add_f32_e32 v67, 1.0, v67
	v_rcp_f32_e32 v66, v66
	v_rcp_f32_e32 v67, v67
	v_cvt_pk_bf16_f32 v48, v48, v49
	v_cvt_pk_bf16_f32 v49, v50, v51
	v_pk_mul_f32 v[50:51], v[52:53], v[64:65]
	v_pk_mul_f32 v[52:53], v[54:55], v[66:67]
	v_cvt_pk_bf16_f32 v50, v50, v51
	v_cvt_pk_bf16_f32 v51, v52, v53
	v_pk_mul_f32 v[52:53], v[56:57], v[176:177] op_sel_hi:[1,0]
	s_nop 0
	v_mul_f32_e32 v54, 0xbfb8aa3b, v52
	v_mul_f32_e32 v55, 0xbfb8aa3b, v53
	v_exp_f32_e32 v54, v54
	v_exp_f32_e32 v55, v55
	s_barrier
; DI u32x2 pk4(float a, float b, float c, float d) { u32x2 r; r.x = pk2(a, b); r.y = pk2(c, d); return r; }
; DI float fsilu(float z) { return z * fsigmoid(z); }
; template <int WI, int WGJ, class GetF, class LdF, class FinF>
; DI void staged_rows_rmw(unsigned char* lds, int tid, GetF get, LdF ld, FinF fin) {
;     ...
;         unsigned char* wrow = lds + (wj * 32 + ln) * RS + (wi * WI * 32 + 4 * h) * 2;
; #pragma unroll
;         for (int it = 0; it < WI; ++it)
; #pragma unroll
;             for (int g = 0; g < 4; ++g) *(u32x2*)(wrow + (it * 32 + 8 * g) * 2) = get(it, jt, g);
; DI void phase3b(const Params& p, unsigned char* smem, int tid) {
;     ...
;             staged_rows_rmw<4, 4>(lds, te,
;                 [&](int it, int jt, int g) { const float sc = rsj[jt];
;                     return pk4(fsilu(acc[it][jt][4 * g] * sc), fsilu(acc[it][jt][4 * g + 1] * sc), fsilu(acc[it][jt][4 * g + 2] * sc), fsilu(acc[it][jt][4 * g + 3] * sc)); },
	ds_write2_b64 v112, v[48:49], v[50:51] offset1:2
	v_pk_mul_f32 v[50:51], v[58:59], v[176:177] op_sel_hi:[1,0]
	v_add_f32_e32 v48, 1.0, v54
	v_add_f32_e32 v49, 1.0, v55
	v_mul_f32_e32 v54, 0xbfb8aa3b, v50
	v_mul_f32_e32 v55, 0xbfb8aa3b, v51
	v_rcp_f32_e32 v48, v48
	v_rcp_f32_e32 v49, v49
	v_exp_f32_e32 v54, v54
	v_exp_f32_e32 v55, v55
	v_pk_mul_f32 v[32:33], v[32:33], v[176:177] op_sel_hi:[1,0]
	v_pk_mul_f32 v[48:49], v[52:53], v[48:49]
	v_add_f32_e32 v52, 1.0, v54
	v_add_f32_e32 v53, 1.0, v55
	v_pk_mul_f32 v[54:55], v[60:61], v[176:177] op_sel_hi:[1,0]
	v_rcp_f32_e32 v52, v52
	v_mul_f32_e32 v56, 0xbfb8aa3b, v54
	v_mul_f32_e32 v57, 0xbfb8aa3b, v55
	v_rcp_f32_e32 v53, v53
	v_exp_f32_e32 v56, v56
	v_exp_f32_e32 v57, v57
	v_cvt_pk_bf16_f32 v48, v48, v49
	v_pk_mul_f32 v[50:51], v[50:51], v[52:53]
	v_add_f32_e32 v52, 1.0, v56
	v_add_f32_e32 v53, 1.0, v57
	v_pk_mul_f32 v[56:57], v[62:63], v[176:177] op_sel_hi:[1,0]
	v_rcp_f32_e32 v52, v52
	v_mul_f32_e32 v58, 0xbfb8aa3b, v56
	v_mul_f32_e32 v59, 0xbfb8aa3b, v57
	v_exp_f32_e32 v58, v58
	v_exp_f32_e32 v59, v59
	v_rcp_f32_e32 v53, v53
	v_cvt_pk_bf16_f32 v49, v50, v51
	v_add_f32_e32 v58, 1.0, v58
	v_add_f32_e32 v59, 1.0, v59
	v_rcp_f32_e32 v58, v58
	v_rcp_f32_e32 v59, v59
	v_pk_mul_f32 v[50:51], v[54:55], v[52:53]
	v_pk_mul_f32 v[34:35], v[34:35], v[176:177] op_sel_hi:[1,0]
	v_cvt_pk_bf16_f32 v50, v50, v51
	v_pk_mul_f32 v[52:53], v[56:57], v[58:59]
	v_pk_mul_f32 v[36:37], v[36:37], v[176:177] op_sel_hi:[1,0]
	v_cvt_pk_bf16_f32 v51, v52, v53
	v_mul_f32_e32 v52, 0xbfb8aa3b, v32
	v_mul_f32_e32 v53, 0xbfb8aa3b, v33
	v_exp_f32_e32 v52, v52
	v_exp_f32_e32 v53, v53
	ds_write2_b64 v112, v[48:49], v[50:51] offset0:4 offset1:6
	v_mul_f32_e32 v50, 0xbfb8aa3b, v34
	v_add_f32_e32 v48, 1.0, v52
	v_add_f32_e32 v49, 1.0, v53
	v_mul_f32_e32 v51, 0xbfb8aa3b, v35
	v_rcp_f32_e32 v48, v48
	v_rcp_f32_e32 v49, v49
	v_exp_f32_e32 v50, v50
	v_exp_f32_e32 v51, v51
	v_pk_mul_f32 v[38:39], v[38:39], v[176:177] op_sel_hi:[1,0]
	v_pk_mul_f32 v[32:33], v[32:33], v[48:49]
	v_add_f32_e32 v48, 1.0, v50
	v_add_f32_e32 v49, 1.0, v51
	v_mul_f32_e32 v50, 0xbfb8aa3b, v36
	v_mul_f32_e32 v51, 0xbfb8aa3b, v37
	v_rcp_f32_e32 v48, v48
	v_rcp_f32_e32 v49, v49
	v_exp_f32_e32 v50, v50
	v_exp_f32_e32 v51, v51
	v_cvt_pk_bf16_f32 v32, v32, v33
	v_pk_mul_f32 v[34:35], v[34:35], v[48:49]
	v_add_f32_e32 v48, 1.0, v50
	v_add_f32_e32 v49, 1.0, v51
	v_mul_f32_e32 v50, 0xbfb8aa3b, v38
	v_mul_f32_e32 v51, 0xbfb8aa3b, v39
	v_exp_f32_e32 v50, v50
	v_exp_f32_e32 v51, v51
	v_rcp_f32_e32 v48, v48
	v_rcp_f32_e32 v49, v49
	v_add_f32_e32 v50, 1.0, v50
	v_add_f32_e32 v51, 1.0, v51
	v_rcp_f32_e32 v50, v50
	v_rcp_f32_e32 v51, v51
	v_cvt_pk_bf16_f32 v33, v34, v35
	v_pk_mul_f32 v[34:35], v[36:37], v[48:49]
	v_pk_mul_f32 v[16:17], v[16:17], v[176:177] op_sel_hi:[1,0]
	v_pk_mul_f32 v[36:37], v[38:39], v[50:51]
	v_cvt_pk_bf16_f32 v34, v34, v35
	v_cvt_pk_bf16_f32 v35, v36, v37
	v_pk_mul_f32 v[36:37], v[40:41], v[176:177] op_sel_hi:[1,0]
	ds_write2_b64 v112, v[32:33], v[34:35] offset0:8 offset1:10
	v_mul_f32_e32 v38, 0xbfb8aa3b, v36
	v_mul_f32_e32 v39, 0xbfb8aa3b, v37
	v_exp_f32_e32 v38, v38
	v_exp_f32_e32 v39, v39
	v_pk_mul_f32 v[34:35], v[42:43], v[176:177] op_sel_hi:[1,0]
	v_pk_mul_f32 v[18:19], v[18:19], v[176:177] op_sel_hi:[1,0]
	v_add_f32_e32 v32, 1.0, v38
	v_add_f32_e32 v33, 1.0, v39
	v_mul_f32_e32 v38, 0xbfb8aa3b, v34
	v_mul_f32_e32 v39, 0xbfb8aa3b, v35
	v_rcp_f32_e32 v32, v32
	v_rcp_f32_e32 v33, v33
	v_exp_f32_e32 v38, v38
	v_exp_f32_e32 v39, v39
	v_pk_mul_f32 v[20:21], v[20:21], v[176:177] op_sel_hi:[1,0]
	v_pk_mul_f32 v[32:33], v[36:37], v[32:33]
	v_add_f32_e32 v36, 1.0, v38
	v_add_f32_e32 v37, 1.0, v39
	v_pk_mul_f32 v[38:39], v[44:45], v[176:177] op_sel_hi:[1,0]
	v_rcp_f32_e32 v36, v36
	v_mul_f32_e32 v40, 0xbfb8aa3b, v38
	v_mul_f32_e32 v41, 0xbfb8aa3b, v39
	v_rcp_f32_e32 v37, v37
	v_exp_f32_e32 v40, v40
	v_exp_f32_e32 v41, v41
	v_cvt_pk_bf16_f32 v32, v32, v33
	v_pk_mul_f32 v[34:35], v[34:35], v[36:37]
	v_add_f32_e32 v36, 1.0, v40
	v_add_f32_e32 v37, 1.0, v41
	v_pk_mul_f32 v[40:41], v[46:47], v[176:177] op_sel_hi:[1,0]
	v_rcp_f32_e32 v36, v36
	v_mul_f32_e32 v42, 0xbfb8aa3b, v40
	v_mul_f32_e32 v43, 0xbfb8aa3b, v41
	v_exp_f32_e32 v42, v42
	v_exp_f32_e32 v43, v43
	v_rcp_f32_e32 v37, v37
	v_cvt_pk_bf16_f32 v33, v34, v35
	v_add_f32_e32 v42, 1.0, v42
	v_add_f32_e32 v43, 1.0, v43
	v_rcp_f32_e32 v42, v42
	v_rcp_f32_e32 v43, v43
	v_pk_mul_f32 v[34:35], v[38:39], v[36:37]
	v_pk_mul_f32 v[22:23], v[22:23], v[176:177] op_sel_hi:[1,0]
	v_cvt_pk_bf16_f32 v34, v34, v35
	v_pk_mul_f32 v[36:37], v[40:41], v[42:43]
	v_pk_mul_f32 v[0:1], v[0:1], v[176:177] op_sel_hi:[1,0]
	v_cvt_pk_bf16_f32 v35, v36, v37
	v_mul_f32_e32 v36, 0xbfb8aa3b, v16
	v_mul_f32_e32 v37, 0xbfb8aa3b, v17
	v_exp_f32_e32 v36, v36
	v_exp_f32_e32 v37, v37
	ds_write2_b64 v112, v[32:33], v[34:35] offset0:12 offset1:14
	v_mul_f32_e32 v34, 0xbfb8aa3b, v18
	v_add_f32_e32 v32, 1.0, v36
	v_add_f32_e32 v33, 1.0, v37
	v_mul_f32_e32 v35, 0xbfb8aa3b, v19
	v_rcp_f32_e32 v32, v32
	v_rcp_f32_e32 v33, v33
	v_exp_f32_e32 v34, v34
	v_exp_f32_e32 v35, v35
	v_pk_mul_f32 v[2:3], v[2:3], v[176:177] op_sel_hi:[1,0]
	v_pk_mul_f32 v[16:17], v[16:17], v[32:33]
	v_add_f32_e32 v32, 1.0, v34
	v_add_f32_e32 v33, 1.0, v35
	v_mul_f32_e32 v34, 0xbfb8aa3b, v20
	v_mul_f32_e32 v35, 0xbfb8aa3b, v21
	v_rcp_f32_e32 v32, v32
	v_rcp_f32_e32 v33, v33
	v_exp_f32_e32 v34, v34
	v_exp_f32_e32 v35, v35
	v_cvt_pk_bf16_f32 v16, v16, v17
	v_pk_mul_f32 v[18:19], v[18:19], v[32:33]
	v_add_f32_e32 v32, 1.0, v34
	v_add_f32_e32 v33, 1.0, v35
	v_mul_f32_e32 v34, 0xbfb8aa3b, v22
	v_mul_f32_e32 v35, 0xbfb8aa3b, v23
	v_exp_f32_e32 v34, v34
	v_exp_f32_e32 v35, v35
; DI u32x2 pk4(float a, float b, float c, float d) { u32x2 r; r.x = pk2(a, b); r.y = pk2(c, d); return r; }
; DI float fsilu(float z) { return z * fsigmoid(z); }
; template <int WI, int WGJ, class GetF, class LdF, class FinF>
; DI void staged_rows_rmw(unsigned char* lds, int tid, GetF get, LdF ld, FinF fin) {
;     ...
;         unsigned char* wrow = lds + (wj * 32 + ln) * RS + (wi * WI * 32 + 4 * h) * 2;
; #pragma unroll
;         for (int it = 0; it < WI; ++it)
; #pragma unroll
;             for (int g = 0; g < 4; ++g) *(u32x2*)(wrow + (it * 32 + 8 * g) * 2) = get(it, jt, g);
;         constexpr int NGRP = 2, GSZ = NIT / NGRP;
;         __syncthreads();
; DI void phase3b(const Params& p, unsigned char* smem, int tid) {
;     ...
;             staged_rows_rmw<4, 4>(lds, te,
;                 [&](int it, int jt, int g) { const float sc = rsj[jt];
;                     return pk4(fsilu(acc[it][jt][4 * g] * sc), fsilu(acc[it][jt][4 * g + 1] * sc), fsilu(acc[it][jt][4 * g + 2] * sc), fsilu(acc[it][jt][4 * g + 3] * sc)); },
	v_rcp_f32_e32 v32, v32
	v_rcp_f32_e32 v33, v33
	v_add_f32_e32 v34, 1.0, v34
	v_add_f32_e32 v35, 1.0, v35
	v_rcp_f32_e32 v34, v34
	v_rcp_f32_e32 v35, v35
	v_cvt_pk_bf16_f32 v17, v18, v19
	v_pk_mul_f32 v[18:19], v[20:21], v[32:33]
	v_pk_mul_f32 v[4:5], v[4:5], v[176:177] op_sel_hi:[1,0]
	v_pk_mul_f32 v[20:21], v[22:23], v[34:35]
	v_cvt_pk_bf16_f32 v18, v18, v19
	v_cvt_pk_bf16_f32 v19, v20, v21
	v_pk_mul_f32 v[20:21], v[24:25], v[176:177] op_sel_hi:[1,0]
	ds_write2_b64 v112, v[16:17], v[18:19] offset0:16 offset1:18
	v_mul_f32_e32 v22, 0xbfb8aa3b, v20
	v_mul_f32_e32 v23, 0xbfb8aa3b, v21
	v_exp_f32_e32 v22, v22
	v_exp_f32_e32 v23, v23
	v_pk_mul_f32 v[18:19], v[26:27], v[176:177] op_sel_hi:[1,0]
	v_pk_mul_f32 v[6:7], v[6:7], v[176:177] op_sel_hi:[1,0]
	v_add_f32_e32 v16, 1.0, v22
	v_add_f32_e32 v17, 1.0, v23
	v_mul_f32_e32 v22, 0xbfb8aa3b, v18
	v_mul_f32_e32 v23, 0xbfb8aa3b, v19
	v_rcp_f32_e32 v16, v16
	v_rcp_f32_e32 v17, v17
	v_exp_f32_e32 v22, v22
	v_exp_f32_e32 v23, v23
	s_add_i32 s26, s26, 32
	v_pk_mul_f32 v[16:17], v[20:21], v[16:17]
	v_add_f32_e32 v20, 1.0, v22
	v_add_f32_e32 v21, 1.0, v23
	v_pk_mul_f32 v[22:23], v[28:29], v[176:177] op_sel_hi:[1,0]
	v_rcp_f32_e32 v20, v20
	v_mul_f32_e32 v24, 0xbfb8aa3b, v22
	v_mul_f32_e32 v25, 0xbfb8aa3b, v23
	v_rcp_f32_e32 v21, v21
	v_exp_f32_e32 v24, v24
	v_exp_f32_e32 v25, v25
	v_cvt_pk_bf16_f32 v16, v16, v17
	v_pk_mul_f32 v[18:19], v[18:19], v[20:21]
	v_add_f32_e32 v20, 1.0, v24
	v_add_f32_e32 v21, 1.0, v25
	v_pk_mul_f32 v[24:25], v[30:31], v[176:177] op_sel_hi:[1,0]
	v_rcp_f32_e32 v20, v20
	v_mul_f32_e32 v26, 0xbfb8aa3b, v24
	v_mul_f32_e32 v27, 0xbfb8aa3b, v25
	v_exp_f32_e32 v26, v26
	v_exp_f32_e32 v27, v27
	v_rcp_f32_e32 v21, v21
	v_cvt_pk_bf16_f32 v17, v18, v19
	v_add_f32_e32 v26, 1.0, v26
	v_add_f32_e32 v27, 1.0, v27
	v_rcp_f32_e32 v26, v26
	v_rcp_f32_e32 v27, v27
	v_pk_mul_f32 v[18:19], v[22:23], v[20:21]
	s_mov_b32 s14, 0
	v_cvt_pk_bf16_f32 v18, v18, v19
	v_pk_mul_f32 v[20:21], v[24:25], v[26:27]
	s_mov_b64 s[24:25], -1
	v_cvt_pk_bf16_f32 v19, v20, v21
	v_mul_f32_e32 v20, 0xbfb8aa3b, v0
	v_mul_f32_e32 v21, 0xbfb8aa3b, v1
	v_exp_f32_e32 v20, v20
	v_exp_f32_e32 v21, v21
	ds_write2_b64 v112, v[16:17], v[18:19] offset0:20 offset1:22
	v_mul_f32_e32 v18, 0xbfb8aa3b, v2
	v_add_f32_e32 v16, 1.0, v20
	v_add_f32_e32 v17, 1.0, v21
	v_mul_f32_e32 v19, 0xbfb8aa3b, v3
	v_rcp_f32_e32 v16, v16
	v_rcp_f32_e32 v17, v17
	v_exp_f32_e32 v18, v18
	v_exp_f32_e32 v19, v19
	v_pk_mul_f32 v[0:1], v[0:1], v[16:17]
	v_add_f32_e32 v16, 1.0, v18
	v_add_f32_e32 v17, 1.0, v19
	v_mul_f32_e32 v18, 0xbfb8aa3b, v4
	v_mul_f32_e32 v19, 0xbfb8aa3b, v5
	v_rcp_f32_e32 v16, v16
	v_rcp_f32_e32 v17, v17
	v_exp_f32_e32 v18, v18
	v_exp_f32_e32 v19, v19
	v_cvt_pk_bf16_f32 v0, v0, v1
	v_pk_mul_f32 v[2:3], v[2:3], v[16:17]
	v_add_f32_e32 v16, 1.0, v18
	v_add_f32_e32 v17, 1.0, v19
	v_mul_f32_e32 v18, 0xbfb8aa3b, v6
	v_mul_f32_e32 v19, 0xbfb8aa3b, v7
	v_exp_f32_e32 v18, v18
	v_exp_f32_e32 v19, v19
	v_rcp_f32_e32 v16, v16
	v_rcp_f32_e32 v17, v17
	v_add_f32_e32 v18, 1.0, v18
	v_add_f32_e32 v19, 1.0, v19
	v_rcp_f32_e32 v18, v18
	v_rcp_f32_e32 v19, v19
	v_cvt_pk_bf16_f32 v1, v2, v3
	v_pk_mul_f32 v[2:3], v[4:5], v[16:17]
	v_pk_mul_f32 v[4:5], v[6:7], v[18:19]
	v_cvt_pk_bf16_f32 v2, v2, v3
	v_cvt_pk_bf16_f32 v3, v4, v5
	v_pk_mul_f32 v[4:5], v[8:9], v[176:177] op_sel_hi:[1,0]
	ds_write2_b64 v112, v[0:1], v[2:3] offset0:24 offset1:26
	v_mul_f32_e32 v6, 0xbfb8aa3b, v4
	v_mul_f32_e32 v7, 0xbfb8aa3b, v5
	v_exp_f32_e32 v6, v6
	v_exp_f32_e32 v7, v7
	v_pk_mul_f32 v[2:3], v[10:11], v[176:177] op_sel_hi:[1,0]
	v_add_f32_e32 v0, 1.0, v6
	v_add_f32_e32 v1, 1.0, v7
	v_mul_f32_e32 v6, 0xbfb8aa3b, v2
	v_mul_f32_e32 v7, 0xbfb8aa3b, v3
	v_rcp_f32_e32 v0, v0
	v_rcp_f32_e32 v1, v1
	v_exp_f32_e32 v6, v6
	v_exp_f32_e32 v7, v7
	v_pk_mul_f32 v[0:1], v[4:5], v[0:1]
	v_add_f32_e32 v4, 1.0, v6
	v_add_f32_e32 v5, 1.0, v7
	v_pk_mul_f32 v[6:7], v[12:13], v[176:177] op_sel_hi:[1,0]
	v_rcp_f32_e32 v4, v4
	v_mul_f32_e32 v8, 0xbfb8aa3b, v6
	v_mul_f32_e32 v9, 0xbfb8aa3b, v7
	v_rcp_f32_e32 v5, v5
	v_exp_f32_e32 v8, v8
	v_exp_f32_e32 v9, v9
	v_cvt_pk_bf16_f32 v0, v0, v1
	v_pk_mul_f32 v[2:3], v[2:3], v[4:5]
	v_add_f32_e32 v4, 1.0, v8
	v_add_f32_e32 v5, 1.0, v9
	v_pk_mul_f32 v[8:9], v[14:15], v[176:177] op_sel_hi:[1,0]
	v_rcp_f32_e32 v4, v4
	v_mul_f32_e32 v10, 0xbfb8aa3b, v8
	v_mul_f32_e32 v11, 0xbfb8aa3b, v9
	v_exp_f32_e32 v10, v10
	v_exp_f32_e32 v11, v11
	v_rcp_f32_e32 v5, v5
	v_cvt_pk_bf16_f32 v1, v2, v3
	v_add_f32_e32 v10, 1.0, v10
	v_add_f32_e32 v11, 1.0, v11
	v_rcp_f32_e32 v10, v10
	v_rcp_f32_e32 v11, v11
	v_pk_mul_f32 v[2:3], v[6:7], v[4:5]
	v_pk_mul_f32 v[4:5], v[8:9], v[10:11]
	v_cvt_pk_bf16_f32 v2, v2, v3
	v_cvt_pk_bf16_f32 v3, v4, v5
	ds_write2_b64 v112, v[0:1], v[2:3] offset0:28 offset1:30
	s_waitcnt lgkmcnt(0)
	s_barrier
; DI unsigned pk2(float lo, float hi) { f32x2 v = {lo, hi}; bf2_t b = __builtin_convertvector(v, bf2_t); return __builtin_bit_cast(unsigned, b); }
; DI float bf_lo(unsigned u) { return __uint_as_float(u << 16); }
; DI float bf_hi(unsigned u) { return __uint_as_float(u & 0xffff0000u); }
; template <int WI, int WGJ, class GetF, class LdF, class FinF>
; DI void staged_rows_rmw(unsigned char* lds, int tid, GetF get, LdF ld, FinF fin) {
;     ...
;         for (int gq = 0; gq < NGRP; ++gq) {
;             decltype(ld(0, 0)) fetched[GSZ];
; #pragma unroll
;             for (int c = 0; c < GSZ; ++c) {
;                 const int idx = tid + (gq * GSZ + c) * NT, lr = idx / NCH, ch = idx % NCH;
;                 fetched[c] = ld((lr >> 5) * 64 + jt * 32 + (lr & 31), ch * 8);
;             }
; #pragma unroll
;             for (int c = 0; c < GSZ; ++c) {
;                 const int idx = tid + (gq * GSZ + c) * NT, lr = idx / NCH, ch = idx % NCH;
;                 const u32x4 v = *(const u32x4*)(lds + lr * RS + ch * 16);
;                 fin((lr >> 5) * 64 + jt * 32 + (lr & 31), ch * 8, v, fetched[c]);
;             }
; DI void phase3b(const Params& p, unsigned char* smem, int tid) {
;     ...
;                 [&](int row, int col) { return *(const u32x4*)(obuf + (size_t)(r0 + row) * 1024 + col); },
;                 [&](int row, int col, u32x4 v, u32x4 o) { u32x4 w;
; #pragma unroll
;                     for (int e = 0; e < 4; ++e) w[e] = pk2(bf_lo(o[e]) * bf_lo(v[e]), bf_hi(o[e]) * bf_hi(v[e]));
;                     *(u32x4*)(obuf + (size_t)(r0 + row) * 1024 + col) = w; });
	ds_read_b128 v[64:67], v197 offset:2048
	ds_read_b128 v[68:71], v197 offset:10496
	ds_read_b128 v[72:75], v197 offset:18944
	ds_read_b128 v[76:79], v197 offset:27392
	s_waitcnt lgkmcnt(3)
	v_lshlrev_b32_e32 v80, 16, v64
	v_and_b32_e32 v81, 0xffff0000, v64
	v_lshlrev_b32_e32 v82, 16, v65
	v_and_b32_e32 v83, 0xffff0000, v65
	v_lshlrev_b32_e32 v84, 16, v66
	v_and_b32_e32 v85, 0xffff0000, v66
	v_lshlrev_b32_e32 v86, 16, v67
	v_and_b32_e32 v87, 0xffff0000, v67
	s_waitcnt vmcnt(15)
	v_lshlrev_b32_e32 v88, 16, v224
	v_and_b32_e32 v89, 0xffff0000, v224
	v_lshlrev_b32_e32 v90, 16, v225
	v_and_b32_e32 v91, 0xffff0000, v225
	v_lshlrev_b32_e32 v92, 16, v226
	v_and_b32_e32 v93, 0xffff0000, v226
	v_lshlrev_b32_e32 v94, 16, v227
	v_and_b32_e32 v95, 0xffff0000, v227
	v_pk_mul_f32 v[88:89], v[88:89], v[80:81]
	v_pk_mul_f32 v[90:91], v[90:91], v[82:83]
	v_pk_mul_f32 v[92:93], v[92:93], v[84:85]
	v_pk_mul_f32 v[94:95], v[94:95], v[86:87]
	v_cvt_pk_bf16_f32 v224, v88, v89
	v_cvt_pk_bf16_f32 v225, v90, v91
	v_cvt_pk_bf16_f32 v226, v92, v93
	v_cvt_pk_bf16_f32 v227, v94, v95
	v_add_u32_e32 v244, 0x10000, v196
	global_store_dwordx4 v244, v[224:227], s[100:101] sc1
	s_waitcnt lgkmcnt(2)
	v_lshlrev_b32_e32 v80, 16, v68
	v_and_b32_e32 v81, 0xffff0000, v68
	v_lshlrev_b32_e32 v82, 16, v69
	v_and_b32_e32 v83, 0xffff0000, v69
	v_lshlrev_b32_e32 v84, 16, v70
	v_and_b32_e32 v85, 0xffff0000, v70
	v_lshlrev_b32_e32 v86, 16, v71
	v_and_b32_e32 v87, 0xffff0000, v71
	s_waitcnt vmcnt(15)
	v_lshlrev_b32_e32 v88, 16, v228
	v_and_b32_e32 v89, 0xffff0000, v228
	v_lshlrev_b32_e32 v90, 16, v229
	v_and_b32_e32 v91, 0xffff0000, v229
	v_lshlrev_b32_e32 v92, 16, v230
	v_and_b32_e32 v93, 0xffff0000, v230
	v_lshlrev_b32_e32 v94, 16, v231
	v_and_b32_e32 v95, 0xffff0000, v231
	v_pk_mul_f32 v[88:89], v[88:89], v[80:81]
	v_pk_mul_f32 v[90:91], v[90:91], v[82:83]
	v_pk_mul_f32 v[92:93], v[92:93], v[84:85]
	v_pk_mul_f32 v[94:95], v[94:95], v[86:87]
	v_cvt_pk_bf16_f32 v228, v88, v89
	v_cvt_pk_bf16_f32 v229, v90, v91
	v_cvt_pk_bf16_f32 v230, v92, v93
	v_cvt_pk_bf16_f32 v231, v94, v95
	v_add_u32_e32 v245, 0x18000, v196
	global_store_dwordx4 v245, v[228:231], s[100:101] sc1
	s_waitcnt lgkmcnt(1)
	v_lshlrev_b32_e32 v80, 16, v72
	v_and_b32_e32 v81, 0xffff0000, v72
	v_lshlrev_b32_e32 v82, 16, v73
	v_and_b32_e32 v83, 0xffff0000, v73
	v_lshlrev_b32_e32 v84, 16, v74
	v_and_b32_e32 v85, 0xffff0000, v74
	v_lshlrev_b32_e32 v86, 16, v75
	v_and_b32_e32 v87, 0xffff0000, v75
	s_waitcnt vmcnt(15)
	v_lshlrev_b32_e32 v88, 16, v232
	v_and_b32_e32 v89, 0xffff0000, v232
	v_lshlrev_b32_e32 v90, 16, v233
	v_and_b32_e32 v91, 0xffff0000, v233
	v_lshlrev_b32_e32 v92, 16, v234
	v_and_b32_e32 v93, 0xffff0000, v234
	v_lshlrev_b32_e32 v94, 16, v235
	v_and_b32_e32 v95, 0xffff0000, v235
	v_pk_mul_f32 v[88:89], v[88:89], v[80:81]
	v_pk_mul_f32 v[90:91], v[90:91], v[82:83]
	v_pk_mul_f32 v[92:93], v[92:93], v[84:85]
	v_pk_mul_f32 v[94:95], v[94:95], v[86:87]
	v_cvt_pk_bf16_f32 v232, v88, v89
	v_cvt_pk_bf16_f32 v233, v90, v91
	v_cvt_pk_bf16_f32 v234, v92, v93
	v_cvt_pk_bf16_f32 v235, v94, v95
	v_add_u32_e32 v244, 0x30000, v196
	global_store_dwordx4 v244, v[232:235], s[100:101] sc1
	s_waitcnt lgkmcnt(0)
	v_lshlrev_b32_e32 v80, 16, v76
	v_and_b32_e32 v81, 0xffff0000, v76
	v_lshlrev_b32_e32 v82, 16, v77
	v_and_b32_e32 v83, 0xffff0000, v77
	v_lshlrev_b32_e32 v84, 16, v78
	v_and_b32_e32 v85, 0xffff0000, v78
	v_lshlrev_b32_e32 v86, 16, v79
	v_and_b32_e32 v87, 0xffff0000, v79
	s_waitcnt vmcnt(15)
	v_lshlrev_b32_e32 v88, 16, v236
	v_and_b32_e32 v89, 0xffff0000, v236
	v_lshlrev_b32_e32 v90, 16, v237
	v_and_b32_e32 v91, 0xffff0000, v237
	v_lshlrev_b32_e32 v92, 16, v238
	v_and_b32_e32 v93, 0xffff0000, v238
	v_lshlrev_b32_e32 v94, 16, v239
	v_and_b32_e32 v95, 0xffff0000, v239
	v_pk_mul_f32 v[88:89], v[88:89], v[80:81]
	v_pk_mul_f32 v[90:91], v[90:91], v[82:83]
	v_pk_mul_f32 v[92:93], v[92:93], v[84:85]
	v_pk_mul_f32 v[94:95], v[94:95], v[86:87]
	v_cvt_pk_bf16_f32 v236, v88, v89
	v_cvt_pk_bf16_f32 v237, v90, v91
	v_cvt_pk_bf16_f32 v238, v92, v93
	v_cvt_pk_bf16_f32 v239, v94, v95
	v_add_u32_e32 v245, 0x38000, v196
	global_store_dwordx4 v245, v[236:239], s[100:101] sc1
	ds_read_b128 v[64:67], v197 offset:35840
	ds_read_b128 v[68:71], v197 offset:44288
	ds_read_b128 v[72:75], v197 offset:52736
	ds_read_b128 v[76:79], v197 offset:61184
	s_waitcnt lgkmcnt(3)
; DI unsigned pk2(float lo, float hi) { f32x2 v = {lo, hi}; bf2_t b = __builtin_convertvector(v, bf2_t); return __builtin_bit_cast(unsigned, b); }
; DI float bf_lo(unsigned u) { return __uint_as_float(u << 16); }
; DI float bf_hi(unsigned u) { return __uint_as_float(u & 0xffff0000u); }
; template <int WI, int WGJ, class GetF, class LdF, class FinF>
; DI void staged_rows_rmw(unsigned char* lds, int tid, GetF get, LdF ld, FinF fin) {
;     ...
;         for (int gq = 0; gq < NGRP; ++gq) {
;             decltype(ld(0, 0)) fetched[GSZ];
; #pragma unroll
;             for (int c = 0; c < GSZ; ++c) {
;                 const int idx = tid + (gq * GSZ + c) * NT, lr = idx / NCH, ch = idx % NCH;
;                 fetched[c] = ld((lr >> 5) * 64 + jt * 32 + (lr & 31), ch * 8);
;             }
; #pragma unroll
;             for (int c = 0; c < GSZ; ++c) {
;                 const int idx = tid + (gq * GSZ + c) * NT, lr = idx / NCH, ch = idx % NCH;
;                 const u32x4 v = *(const u32x4*)(lds + lr * RS + ch * 16);
;                 fin((lr >> 5) * 64 + jt * 32 + (lr & 31), ch * 8, v, fetched[c]);
;             }
;         }
;         __syncthreads();
; DI void phase3b(const Params& p, unsigned char* smem, int tid) {
;     ...
;                 [&](int row, int col) { return *(const u32x4*)(obuf + (size_t)(r0 + row) * 1024 + col); },
;                 [&](int row, int col, u32x4 v, u32x4 o) { u32x4 w;
; #pragma unroll
;                     for (int e = 0; e < 4; ++e) w[e] = pk2(bf_lo(o[e]) * bf_lo(v[e]), bf_hi(o[e]) * bf_hi(v[e]));
;                     *(u32x4*)(obuf + (size_t)(r0 + row) * 1024 + col) = w; });
	v_lshlrev_b32_e32 v80, 16, v64
	v_and_b32_e32 v81, 0xffff0000, v64
	v_lshlrev_b32_e32 v82, 16, v65
	v_and_b32_e32 v83, 0xffff0000, v65
	v_lshlrev_b32_e32 v84, 16, v66
	v_and_b32_e32 v85, 0xffff0000, v66
	v_lshlrev_b32_e32 v86, 16, v67
	v_and_b32_e32 v87, 0xffff0000, v67
	s_waitcnt vmcnt(11)
	v_lshlrev_b32_e32 v88, 16, v188
	v_and_b32_e32 v89, 0xffff0000, v188
	v_lshlrev_b32_e32 v90, 16, v189
	v_and_b32_e32 v91, 0xffff0000, v189
	v_lshlrev_b32_e32 v92, 16, v190
	v_and_b32_e32 v93, 0xffff0000, v190
	v_lshlrev_b32_e32 v94, 16, v191
	v_and_b32_e32 v95, 0xffff0000, v191
	v_pk_mul_f32 v[88:89], v[88:89], v[80:81]
	v_pk_mul_f32 v[90:91], v[90:91], v[82:83]
	v_pk_mul_f32 v[92:93], v[92:93], v[84:85]
	v_pk_mul_f32 v[94:95], v[94:95], v[86:87]
	v_cvt_pk_bf16_f32 v188, v88, v89
	v_cvt_pk_bf16_f32 v189, v90, v91
	v_cvt_pk_bf16_f32 v190, v92, v93
	v_cvt_pk_bf16_f32 v191, v94, v95
	v_add_u32_e32 v244, 0x50000, v196
	global_store_dwordx4 v244, v[188:191], s[100:101] sc1
	s_waitcnt lgkmcnt(2)
	v_lshlrev_b32_e32 v80, 16, v68
	v_and_b32_e32 v81, 0xffff0000, v68
	v_lshlrev_b32_e32 v82, 16, v69
	v_and_b32_e32 v83, 0xffff0000, v69
	v_lshlrev_b32_e32 v84, 16, v70
	v_and_b32_e32 v85, 0xffff0000, v70
	v_lshlrev_b32_e32 v86, 16, v71
	v_and_b32_e32 v87, 0xffff0000, v71
	s_waitcnt vmcnt(11)
	v_lshlrev_b32_e32 v88, 16, v192
	v_and_b32_e32 v89, 0xffff0000, v192
	v_lshlrev_b32_e32 v90, 16, v193
	v_and_b32_e32 v91, 0xffff0000, v193
	v_lshlrev_b32_e32 v92, 16, v194
	v_and_b32_e32 v93, 0xffff0000, v194
	v_lshlrev_b32_e32 v94, 16, v195
	v_and_b32_e32 v95, 0xffff0000, v195
	v_pk_mul_f32 v[88:89], v[88:89], v[80:81]
	v_pk_mul_f32 v[90:91], v[90:91], v[82:83]
	v_pk_mul_f32 v[92:93], v[92:93], v[84:85]
	v_pk_mul_f32 v[94:95], v[94:95], v[86:87]
	v_cvt_pk_bf16_f32 v192, v88, v89
	v_cvt_pk_bf16_f32 v193, v90, v91
	v_cvt_pk_bf16_f32 v194, v92, v93
	v_cvt_pk_bf16_f32 v195, v94, v95
	v_add_u32_e32 v245, 0x58000, v196
	global_store_dwordx4 v245, v[192:195], s[100:101] sc1
	s_waitcnt lgkmcnt(1)
	v_lshlrev_b32_e32 v80, 16, v72
	v_and_b32_e32 v81, 0xffff0000, v72
	v_lshlrev_b32_e32 v82, 16, v73
	v_and_b32_e32 v83, 0xffff0000, v73
	v_lshlrev_b32_e32 v84, 16, v74
	v_and_b32_e32 v85, 0xffff0000, v74
	v_lshlrev_b32_e32 v86, 16, v75
	v_and_b32_e32 v87, 0xffff0000, v75
	s_waitcnt vmcnt(11)
	v_lshlrev_b32_e32 v88, 16, v200
	v_and_b32_e32 v89, 0xffff0000, v200
	v_lshlrev_b32_e32 v90, 16, v201
	v_and_b32_e32 v91, 0xffff0000, v201
	v_lshlrev_b32_e32 v92, 16, v202
	v_and_b32_e32 v93, 0xffff0000, v202
	v_lshlrev_b32_e32 v94, 16, v203
	v_and_b32_e32 v95, 0xffff0000, v203
	v_pk_mul_f32 v[88:89], v[88:89], v[80:81]
	v_pk_mul_f32 v[90:91], v[90:91], v[82:83]
	v_pk_mul_f32 v[92:93], v[92:93], v[84:85]
	v_pk_mul_f32 v[94:95], v[94:95], v[86:87]
	v_cvt_pk_bf16_f32 v200, v88, v89
	v_cvt_pk_bf16_f32 v201, v90, v91
	v_cvt_pk_bf16_f32 v202, v92, v93
	v_cvt_pk_bf16_f32 v203, v94, v95
	v_add_u32_e32 v244, 0x70000, v196
	global_store_dwordx4 v244, v[200:203], s[100:101] sc1
	s_waitcnt lgkmcnt(0)
	v_lshlrev_b32_e32 v80, 16, v76
	v_and_b32_e32 v81, 0xffff0000, v76
	v_lshlrev_b32_e32 v82, 16, v77
	v_and_b32_e32 v83, 0xffff0000, v77
	v_lshlrev_b32_e32 v84, 16, v78
	v_and_b32_e32 v85, 0xffff0000, v78
	v_lshlrev_b32_e32 v86, 16, v79
	v_and_b32_e32 v87, 0xffff0000, v79
	s_waitcnt vmcnt(11)
	v_lshlrev_b32_e32 v88, 16, v204
	v_and_b32_e32 v89, 0xffff0000, v204
	v_lshlrev_b32_e32 v90, 16, v205
	v_and_b32_e32 v91, 0xffff0000, v205
	v_lshlrev_b32_e32 v92, 16, v206
	v_and_b32_e32 v93, 0xffff0000, v206
	v_lshlrev_b32_e32 v94, 16, v207
	v_and_b32_e32 v95, 0xffff0000, v207
	v_pk_mul_f32 v[88:89], v[88:89], v[80:81]
	v_pk_mul_f32 v[90:91], v[90:91], v[82:83]
	v_pk_mul_f32 v[92:93], v[92:93], v[84:85]
	v_pk_mul_f32 v[94:95], v[94:95], v[86:87]
	v_cvt_pk_bf16_f32 v204, v88, v89
	v_cvt_pk_bf16_f32 v205, v90, v91
	v_cvt_pk_bf16_f32 v206, v92, v93
	v_cvt_pk_bf16_f32 v207, v94, v95
	v_add_u32_e32 v245, 0x78000, v196
	global_store_dwordx4 v245, v[204:207], s[100:101] sc1
	s_barrier
	s_branch .LBB0_912

; DI u32x2 pk4(float a, float b, float c, float d) { u32x2 r; r.x = pk2(a, b); r.y = pk2(c, d); return r; }
; DI float bf_lo(unsigned u) { return __uint_as_float(u << 16); }
; DI float bf_hi(unsigned u) { return __uint_as_float(u & 0xffff0000u); }
; template <int WI, int WGJ, class GetF, class FinF>
; DI void staged_rows(unsigned char* lds, int tid, GetF get, FinF fin) {
;     ...
;     for (int jt = 0; jt < 2; ++jt) {
;         unsigned char* wrow = lds + (wj * 32 + ln) * RS + (wi * WI * 32 + 4 * h) * 2;
; #pragma unroll
;         for (int it = 0; it < WI; ++it)
; #pragma unroll
;             for (int g = 0; g < 4; ++g) *(u32x2*)(wrow + (it * 32 + 8 * g) * 2) = get(it, jt, g);
;         __syncthreads();
; #pragma unroll 1
;         for (int c = 0; c < ROWS * NCH / NT; ++c) {
;             const int idx = tid + c * NT, lr = idx / NCH, ch = idx % NCH;
;             const u32x4 v = *(const u32x4*)(lds + lr * RS + ch * 16);
;             fin((lr >> 5) * 64 + jt * 32 + (lr & 31), ch * 8, v);
;         }
; DI void phase4(const Params& p, unsigned char* smem, int tid) {
;     ...
;             staged_rows<4, 4>(lds, te,
;                 [&](int it, int jt, int g) { const u32x4 b4 = *(const u32x4*)(gb + ((it * 2 + jt) * 2 + (g >> 1)) * 1024); const int e0 = (g & 1) * 2;
;                     const float g0 = fmaxf(bf_lo(b4[e0]), 8.6736174e-19f), g1 = fmaxf(bf_hi(b4[e0]), 8.6736174e-19f);
;                     const float g2 = fmaxf(bf_lo(b4[e0 + 1]), 8.6736174e-19f), g3 = fmaxf(bf_hi(b4[e0 + 1]), 8.6736174e-19f);
;                     return pk4(acc[it][jt][4 * g] * g0, acc[it][jt][4 * g + 1] * g1, acc[it][jt][4 * g + 2] * g2, acc[it][jt][4 * g + 3] * g3); },
;                 [&](int row, int col, u32x4 v) { __builtin_nontemporal_store(v, (u32x4*)(mx + (size_t)(r0 + row) * 1024 + f * 256 + col)); });
.LBB0_997:
	s_nop 0
	v_add_u32_e32 v64, s6, v221
	v_ashrrev_i32_e32 v65, 31, v64
	v_lshrrev_b32_e32 v65, 27, v65
	v_add_u32_e32 v65, v64, v65
	v_ashrrev_i32_e32 v66, 5, v65
	v_and_b32_e32 v65, 0xffffffe0, v65
	v_sub_u32_e32 v64, v64, v65
	v_mul_lo_u32 v65, v66, s50
	v_lshlrev_b32_e32 v67, 1, v66
	v_lshlrev_b32_e32 v69, 4, v64
	v_and_b32_e32 v66, 31, v66
	v_and_b32_e32 v67, 0xffffffc0, v67
	v_lshlrev_b32_e32 v68, 3, v64
	v_add3_u32 v64, 0, v65, v69
	v_add3_u32 v70, v66, s10, v67
	ds_read_b128 v[64:67], v64 offset:2048
	v_ashrrev_i32_e32 v71, 31, v70
	v_lshlrev_b64 v[70:71], 11, v[70:71]
	s_addk_i32 s6, 0x200
	v_ashrrev_i32_e32 v69, 31, v68
	v_lshl_add_u64 v[70:71], s[12:13], 0, v[70:71]
	s_cmpk_eq_i32 s6, 0x1000
	v_lshl_add_u64 v[68:69], v[68:69], 1, v[70:71]
	s_waitcnt lgkmcnt(0)
	global_store_dwordx4 v[68:69], v[64:67], off nt sc1
	s_cbranch_scc0 .LBB0_997
	s_barrier
	global_load_dwordx4 v[76:79], v[216:217], off offset:2048
	global_load_dwordx4 v[80:83], v[216:217], off offset:3072
	global_load_dwordx4 v[72:75], v[218:219], off offset:2048
	global_load_dwordx4 v[68:71], v[218:219], off offset:3072
	global_load_dwordx4 v[64:67], v[214:215], off offset:2048
	v_mfma_f32_32x32x16_bf16 v[0:15], v[144:147], v[128:131], v[0:15]
	s_mov_b32 s6, 0
	s_add_i32 s10, s10, 32
	s_waitcnt vmcnt(4)
	v_lshlrev_b32_e32 v84, 16, v76
	v_mfma_f32_32x32x16_bf16 v[32:47], v[140:143], v[128:131], v[32:47]
	v_and_b32_e32 v76, 0xffff0000, v76
	v_lshlrev_b32_e32 v85, 16, v77
	v_and_b32_e32 v77, 0xffff0000, v77
	v_lshlrev_b32_e32 v86, 16, v78
	v_and_b32_e32 v78, 0xffff0000, v78
	v_lshlrev_b32_e32 v87, 16, v79
	v_and_b32_e32 v79, 0xffff0000, v79
	v_mfma_f32_32x32x16_bf16 v[0:15], v[200:203], v[188:191], v[0:15]
	s_waitcnt vmcnt(3)
	v_lshlrev_b32_e32 v88, 16, v80
	v_and_b32_e32 v80, 0xffff0000, v80
	v_lshlrev_b32_e32 v89, 16, v81
	v_and_b32_e32 v81, 0xffff0000, v81
	v_lshlrev_b32_e32 v90, 16, v82
	v_and_b32_e32 v82, 0xffff0000, v82
	v_lshlrev_b32_e32 v91, 16, v83
	v_mfma_f32_32x32x16_bf16 v[32:47], v[204:207], v[188:191], v[32:47]
	v_and_b32_e32 v83, 0xffff0000, v83
	v_max_f32_e32 v84, v84, v84
	v_max_f32_e32 v93, v76, v76
	v_max_f32_e32 v85, v85, v85
	v_max_f32_e32 v94, v77, v77
	v_max_f32_e32 v86, v86, v86
	v_max_f32_e32 v95, v78, v78
	v_mfma_f32_32x32x16_bf16 v[0:15], v[184:187], v[164:167], v[0:15]
	v_max_f32_e32 v87, v87, v87
	v_max_f32_e32 v98, v79, v79
	v_max_f32_e32 v88, v88, v88
	v_max_f32_e32 v99, v80, v80
	v_max_f32_e32 v89, v89, v89
	v_max_f32_e32 v100, v81, v81
	v_max_f32_e32 v90, v90, v90
	v_mfma_f32_32x32x16_bf16 v[32:47], v[176:179], v[164:167], v[32:47]
	v_max_f32_e32 v101, v82, v82
	v_max_f32_e32 v91, v91, v91
	v_max_f32_e32 v102, v83, v83
	v_max_f32_e32 v76, 0x21800000, v84
	v_max_f32_e32 v77, 0x21800000, v93
	v_max_f32_e32 v78, 0x21800000, v85
	v_max_f32_e32 v79, 0x21800000, v94
	v_mfma_f32_32x32x16_bf16 v[0:15], v[180:183], v[160:163], v[0:15]
	v_max_f32_e32 v80, 0x21800000, v86
	v_max_f32_e32 v81, 0x21800000, v95
	v_max_f32_e32 v82, 0x21800000, v87
	v_max_f32_e32 v83, 0x21800000, v98
	v_max_f32_e32 v84, 0x21800000, v88
	v_max_f32_e32 v85, 0x21800000, v99
	v_max_f32_e32 v86, 0x21800000, v89
	v_mfma_f32_32x32x16_bf16 v[48:63], v[136:139], v[128:131], v[48:63]
	v_max_f32_e32 v87, 0x21800000, v100
	v_max_f32_e32 v88, 0x21800000, v90
	v_max_f32_e32 v89, 0x21800000, v101
	v_max_f32_e32 v90, 0x21800000, v91
	v_max_f32_e32 v91, 0x21800000, v102
	v_pk_mul_f32 v[0:1], v[0:1], v[76:77]
	v_pk_mul_f32 v[2:3], v[2:3], v[78:79]
	v_mfma_f32_32x32x16_bf16 v[32:47], v[156:159], v[160:163], v[32:47]
	v_mul_f32_e64 v4, v4, v80
	v_mul_f32_e64 v5, v5, v81
	v_mul_f32_e64 v6, v6, v82
	v_mul_f32_e64 v7, v7, v83
	v_mul_f32_e64 v8, v8, v84
	v_mul_f32_e64 v9, v9, v85
	v_pk_mul_f32 v[10:11], v[10:11], v[86:87]
	v_pk_mul_f32 v[12:13], v[12:13], v[88:89]
	v_pk_mul_f32 v[14:15], v[14:15], v[90:91]
	v_cvt_pk_bf16_f32 v0, v0, v1
	v_cvt_pk_bf16_f32 v1, v2, v3
	v_cvt_pk_bf16_f32 v2, v4, v5
	v_cvt_pk_bf16_f32 v3, v6, v7
	s_waitcnt vmcnt(2)
	v_lshlrev_b32_e32 v92, 16, v72
	v_cvt_pk_bf16_f32 v4, v8, v9
	v_cvt_pk_bf16_f32 v5, v10, v11
	v_cvt_pk_bf16_f32 v6, v12, v13
	v_cvt_pk_bf16_f32 v7, v14, v15
	ds_write2_b64 v212, v[0:1], v[2:3] offset1:2
	ds_write2_b64 v212, v[4:5], v[6:7] offset0:4 offset1:6
	v_and_b32_e32 v1, 0xffff0000, v72
	v_max_f32_e32 v0, v92, v92
	v_max_f32_e32 v1, v1, v1
	v_max_f32_e32 v0, 0x21800000, v0
	v_max_f32_e32 v1, 0x21800000, v1
	v_mfma_f32_32x32x16_bf16 v[48:63], v[192:195], v[188:191], v[48:63]
	v_mul_f32_e64 v0, v32, v0
	v_mul_f32_e64 v1, v33, v1
	v_lshlrev_b32_e32 v2, 16, v73
	v_cvt_pk_bf16_f32 v4, v0, v1
	v_lshlrev_b32_e32 v0, 16, v74
	v_max_f32_e32 v0, v0, v0
	v_and_b32_e32 v3, 0xffff0000, v73
	v_max_f32_e32 v6, 0x21800000, v0
	v_and_b32_e32 v0, 0xffff0000, v74
	v_max_f32_e32 v2, v2, v2
	v_max_f32_e32 v3, v3, v3
	v_max_f32_e32 v0, v0, v0
	v_max_f32_e32 v2, 0x21800000, v2
	v_max_f32_e32 v3, 0x21800000, v3
	v_max_f32_e32 v7, 0x21800000, v0
	v_lshlrev_b32_e32 v0, 16, v75
	v_and_b32_e32 v9, 0xffff0000, v75
	v_pk_mul_f32 v[2:3], v[34:35], v[2:3]
	v_max_f32_e32 v8, v0, v0
	v_max_f32_e32 v9, v9, v9
	v_cvt_pk_bf16_f32 v5, v2, v3
	global_load_dwordx4 v[0:3], v[214:215], off offset:3072
	v_max_f32_e32 v8, 0x21800000, v8
	v_max_f32_e32 v9, 0x21800000, v9
	v_mfma_f32_32x32x16_bf16 v[48:63], v[172:175], v[164:167], v[48:63]
	v_mul_f32_e64 v6, v36, v6
	v_mul_f32_e64 v7, v37, v7
	v_mul_f32_e64 v8, v38, v8
	v_mul_f32_e64 v9, v39, v9
	v_cvt_pk_bf16_f32 v6, v6, v7
	v_cvt_pk_bf16_f32 v7, v8, v9
	ds_write2_b64 v212, v[4:5], v[6:7] offset0:8 offset1:10
	s_waitcnt vmcnt(2)
; DI u32x2 pk4(float a, float b, float c, float d) { u32x2 r; r.x = pk2(a, b); r.y = pk2(c, d); return r; }
; DI float bf_lo(unsigned u) { return __uint_as_float(u << 16); }
; DI float bf_hi(unsigned u) { return __uint_as_float(u & 0xffff0000u); }
; template <int WI, int WGJ, class GetF, class FinF>
; DI void staged_rows(unsigned char* lds, int tid, GetF get, FinF fin) {
;     ...
;     for (int jt = 0; jt < 2; ++jt) {
;         unsigned char* wrow = lds + (wj * 32 + ln) * RS + (wi * WI * 32 + 4 * h) * 2;
; #pragma unroll
;         for (int it = 0; it < WI; ++it)
; #pragma unroll
;             for (int g = 0; g < 4; ++g) *(u32x2*)(wrow + (it * 32 + 8 * g) * 2) = get(it, jt, g);
;         __syncthreads();
; #pragma unroll 1
;         for (int c = 0; c < ROWS * NCH / NT; ++c) {
;             const int idx = tid + c * NT, lr = idx / NCH, ch = idx % NCH;
;             const u32x4 v = *(const u32x4*)(lds + lr * RS + ch * 16);
;             fin((lr >> 5) * 64 + jt * 32 + (lr & 31), ch * 8, v);
;         }
;         __syncthreads();
;     }
; DI void phase4(const Params& p, unsigned char* smem, int tid) {
;     ...
;             staged_rows<4, 4>(lds, te,
;                 [&](int it, int jt, int g) { const u32x4 b4 = *(const u32x4*)(gb + ((it * 2 + jt) * 2 + (g >> 1)) * 1024); const int e0 = (g & 1) * 2;
;                     const float g0 = fmaxf(bf_lo(b4[e0]), 8.6736174e-19f), g1 = fmaxf(bf_hi(b4[e0]), 8.6736174e-19f);
;                     const float g2 = fmaxf(bf_lo(b4[e0 + 1]), 8.6736174e-19f), g3 = fmaxf(bf_hi(b4[e0 + 1]), 8.6736174e-19f);
;                     return pk4(acc[it][jt][4 * g] * g0, acc[it][jt][4 * g + 1] * g1, acc[it][jt][4 * g + 2] * g2, acc[it][jt][4 * g + 3] * g3); },
;                 [&](int row, int col, u32x4 v) { __builtin_nontemporal_store(v, (u32x4*)(mx + (size_t)(r0 + row) * 1024 + f * 256 + col)); });
	v_lshlrev_b32_e32 v4, 16, v68
	v_and_b32_e32 v5, 0xffff0000, v68
	v_max_f32_e32 v4, v4, v4
	v_max_f32_e32 v5, v5, v5
	v_max_f32_e32 v4, 0x21800000, v4
	v_max_f32_e32 v5, 0x21800000, v5
	v_pk_mul_f32 v[4:5], v[40:41], v[4:5]
	v_lshlrev_b32_e32 v6, 16, v69
	v_and_b32_e32 v7, 0xffff0000, v69
	v_cvt_pk_bf16_f32 v8, v4, v5
	v_lshlrev_b32_e32 v4, 16, v70
	v_max_f32_e32 v6, v6, v6
	v_max_f32_e32 v7, v7, v7
	v_max_f32_e32 v4, v4, v4
	v_mfma_f32_32x32x16_bf16 v[48:63], v[152:155], v[160:163], v[48:63]
	v_max_f32_e32 v6, 0x21800000, v6
	v_max_f32_e32 v7, 0x21800000, v7
	v_max_f32_e32 v10, 0x21800000, v4
	v_and_b32_e32 v4, 0xffff0000, v70
	v_lshlrev_b32_e32 v12, 16, v71
	v_and_b32_e32 v13, 0xffff0000, v71
	v_pk_mul_f32 v[6:7], v[42:43], v[6:7]
	v_max_f32_e32 v11, v4, v4
	v_max_f32_e32 v12, v12, v12
	v_max_f32_e32 v13, v13, v13
	v_cvt_pk_bf16_f32 v9, v6, v7
	global_load_dwordx4 v[4:7], v[96:97], off offset:2048
	v_max_f32_e32 v11, 0x21800000, v11
	v_max_f32_e32 v12, 0x21800000, v12
	v_max_f32_e32 v13, 0x21800000, v13
	v_pk_mul_f32 v[10:11], v[44:45], v[10:11]
	v_pk_mul_f32 v[12:13], v[46:47], v[12:13]
	v_cvt_pk_bf16_f32 v10, v10, v11
	v_cvt_pk_bf16_f32 v11, v12, v13
	ds_write2_b64 v212, v[8:9], v[10:11] offset0:12 offset1:14
	s_waitcnt vmcnt(2)
	v_lshlrev_b32_e32 v8, 16, v64
	v_and_b32_e32 v9, 0xffff0000, v64
	v_max_f32_e32 v8, v8, v8
	v_max_f32_e32 v9, v9, v9
	v_max_f32_e32 v8, 0x21800000, v8
	v_max_f32_e32 v9, 0x21800000, v9
	v_lshlrev_b32_e32 v10, 16, v65
	v_and_b32_e32 v11, 0xffff0000, v65
	v_max_f32_e32 v10, v10, v10
	v_max_f32_e32 v11, v11, v11
	v_pk_mul_f32 v[8:9], v[48:49], v[8:9]
	v_max_f32_e32 v10, 0x21800000, v10
	v_max_f32_e32 v11, 0x21800000, v11
	v_cvt_pk_bf16_f32 v12, v8, v9
	v_lshlrev_b32_e32 v8, 16, v66
	v_pk_mul_f32 v[10:11], v[50:51], v[10:11]
	v_max_f32_e32 v8, v8, v8
	v_cvt_pk_bf16_f32 v13, v10, v11
	v_max_f32_e32 v14, 0x21800000, v8
	global_load_dwordx4 v[8:11], v[96:97], off offset:3072
	v_mfma_f32_32x32x16_bf16 v[16:31], v[132:135], v[128:131], v[16:31]
	v_and_b32_e32 v15, 0xffff0000, v66
	v_lshlrev_b32_e32 v32, 16, v67
	v_and_b32_e32 v33, 0xffff0000, v67
	v_max_f32_e32 v15, v15, v15
	v_max_f32_e32 v32, v32, v32
	v_max_f32_e32 v33, v33, v33
	v_max_f32_e32 v15, 0x21800000, v15
	v_mfma_f32_32x32x16_bf16 v[16:31], v[196:199], v[188:191], v[16:31]
	v_max_f32_e32 v32, 0x21800000, v32
	v_max_f32_e32 v33, 0x21800000, v33
	v_mul_f32_e64 v14, v52, v14
	v_mul_f32_e64 v15, v53, v15
	v_mul_f32_e64 v32, v54, v32
	v_mul_f32_e64 v33, v55, v33
	v_cvt_pk_bf16_f32 v14, v14, v15
	v_cvt_pk_bf16_f32 v15, v32, v33
	ds_write2_b64 v212, v[12:13], v[14:15] offset0:16 offset1:18
	v_mfma_f32_32x32x16_bf16 v[16:31], v[168:171], v[164:167], v[16:31]
	s_waitcnt vmcnt(2)
	v_lshlrev_b32_e32 v12, 16, v0
	v_and_b32_e32 v0, 0xffff0000, v0
	v_max_f32_e32 v0, v0, v0
	v_max_f32_e32 v13, 0x21800000, v0
	v_lshlrev_b32_e32 v0, 16, v1
	v_and_b32_e32 v1, 0xffff0000, v1
	v_max_f32_e32 v12, v12, v12
	v_max_f32_e32 v0, v0, v0
	v_max_f32_e32 v1, v1, v1
	v_max_f32_e32 v12, 0x21800000, v12
	v_max_f32_e32 v0, 0x21800000, v0
	v_max_f32_e32 v1, 0x21800000, v1
	v_pk_mul_f32 v[12:13], v[56:57], v[12:13]
	v_pk_mul_f32 v[0:1], v[58:59], v[0:1]
	v_mfma_f32_32x32x16_bf16 v[16:31], v[148:151], v[160:163], v[16:31]
	v_cvt_pk_bf16_f32 v12, v12, v13
	v_cvt_pk_bf16_f32 v13, v0, v1
	v_lshlrev_b32_e32 v0, 16, v2
	v_and_b32_e32 v1, 0xffff0000, v2
	v_lshlrev_b32_e32 v2, 16, v3
	v_and_b32_e32 v3, 0xffff0000, v3
	v_max_f32_e32 v0, v0, v0
	v_max_f32_e32 v1, v1, v1
	v_max_f32_e32 v2, v2, v2
	v_max_f32_e32 v3, v3, v3
	v_max_f32_e32 v0, 0x21800000, v0
	v_max_f32_e32 v1, 0x21800000, v1
	v_max_f32_e32 v2, 0x21800000, v2
	v_max_f32_e32 v3, 0x21800000, v3
	v_pk_mul_f32 v[0:1], v[60:61], v[0:1]
	v_pk_mul_f32 v[2:3], v[62:63], v[2:3]
	v_cvt_pk_bf16_f32 v0, v0, v1
	v_cvt_pk_bf16_f32 v1, v2, v3
	ds_write2_b64 v212, v[12:13], v[0:1] offset0:20 offset1:22
	s_waitcnt vmcnt(1)
	v_lshlrev_b32_e32 v0, 16, v4
	v_and_b32_e32 v1, 0xffff0000, v4
	v_lshlrev_b32_e32 v2, 16, v5
	v_and_b32_e32 v3, 0xffff0000, v5
	v_max_f32_e32 v0, v0, v0
	v_max_f32_e32 v1, v1, v1
	v_max_f32_e32 v2, v2, v2
	v_max_f32_e32 v3, v3, v3
	v_max_f32_e32 v0, 0x21800000, v0
	v_max_f32_e32 v1, 0x21800000, v1
	v_max_f32_e32 v2, 0x21800000, v2
	v_max_f32_e32 v3, 0x21800000, v3
	v_pk_mul_f32 v[0:1], v[16:17], v[0:1]
	v_pk_mul_f32 v[2:3], v[18:19], v[2:3]
	v_cvt_pk_bf16_f32 v0, v0, v1
	v_cvt_pk_bf16_f32 v1, v2, v3
	v_lshlrev_b32_e32 v2, 16, v6
	v_and_b32_e32 v3, 0xffff0000, v6
	v_lshlrev_b32_e32 v4, 16, v7
	v_and_b32_e32 v5, 0xffff0000, v7
	v_max_f32_e32 v2, v2, v2
	v_max_f32_e32 v3, v3, v3
	v_max_f32_e32 v4, v4, v4
	v_max_f32_e32 v5, v5, v5
	v_max_f32_e32 v2, 0x21800000, v2
	v_max_f32_e32 v3, 0x21800000, v3
	v_max_f32_e32 v4, 0x21800000, v4
	v_max_f32_e32 v5, 0x21800000, v5
	v_pk_mul_f32 v[2:3], v[20:21], v[2:3]
	v_pk_mul_f32 v[4:5], v[22:23], v[4:5]
	v_cvt_pk_bf16_f32 v2, v2, v3
	v_cvt_pk_bf16_f32 v3, v4, v5
	ds_write2_b64 v212, v[0:1], v[2:3] offset0:24 offset1:26
	s_waitcnt vmcnt(0)
	v_lshlrev_b32_e32 v0, 16, v8
	v_and_b32_e32 v1, 0xffff0000, v8
	v_lshlrev_b32_e32 v2, 16, v9
	v_and_b32_e32 v3, 0xffff0000, v9
	v_max_f32_e32 v0, v0, v0
	v_max_f32_e32 v1, v1, v1
	v_max_f32_e32 v2, v2, v2
	v_max_f32_e32 v3, v3, v3
	v_max_f32_e32 v0, 0x21800000, v0
	v_max_f32_e32 v1, 0x21800000, v1
	v_max_f32_e32 v2, 0x21800000, v2
	v_max_f32_e32 v3, 0x21800000, v3
	v_pk_mul_f32 v[0:1], v[24:25], v[0:1]
	v_pk_mul_f32 v[2:3], v[26:27], v[2:3]
	v_cvt_pk_bf16_f32 v0, v0, v1
	v_cvt_pk_bf16_f32 v1, v2, v3
	v_lshlrev_b32_e32 v2, 16, v10
	v_and_b32_e32 v3, 0xffff0000, v10
	v_lshlrev_b32_e32 v4, 16, v11
	v_and_b32_e32 v5, 0xffff0000, v11
	v_max_f32_e32 v2, v2, v2
	v_max_f32_e32 v3, v3, v3
	v_max_f32_e32 v4, v4, v4
	v_max_f32_e32 v5, v5, v5
	v_max_f32_e32 v2, 0x21800000, v2
	v_max_f32_e32 v3, 0x21800000, v3
	v_max_f32_e32 v4, 0x21800000, v4
	v_max_f32_e32 v5, 0x21800000, v5
	v_pk_mul_f32 v[2:3], v[28:29], v[2:3]
	v_pk_mul_f32 v[4:5], v[30:31], v[4:5]
	v_cvt_pk_bf16_f32 v2, v2, v3
	v_cvt_pk_bf16_f32 v3, v4, v5
	ds_write2_b64 v212, v[0:1], v[2:3] offset0:28 offset1:30
	s_waitcnt lgkmcnt(0)
	s_barrier
.LBB0_999:
	s_nop 0
	v_add_u32_e32 v0, s6, v221
	v_ashrrev_i32_e32 v1, 31, v0
	v_lshrrev_b32_e32 v1, 27, v1
	v_add_u32_e32 v1, v0, v1
	v_ashrrev_i32_e32 v2, 5, v1
	v_and_b32_e32 v1, 0xffffffe0, v1
	v_sub_u32_e32 v0, v0, v1
	v_mul_lo_u32 v1, v2, s50
	v_lshlrev_b32_e32 v3, 1, v2
	v_lshlrev_b32_e32 v5, 4, v0
	v_and_b32_e32 v2, 31, v2
	v_and_b32_e32 v3, 0xffffffc0, v3
	v_lshlrev_b32_e32 v4, 3, v0
	v_add3_u32 v0, 0, v1, v5
	v_add3_u32 v6, s10, v2, v3
	ds_read_b128 v[0:3], v0 offset:2048
	v_ashrrev_i32_e32 v7, 31, v6
	v_lshlrev_b64 v[6:7], 11, v[6:7]
	s_addk_i32 s6, 0x200
	v_ashrrev_i32_e32 v5, 31, v4
	v_lshl_add_u64 v[6:7], s[12:13], 0, v[6:7]
	s_cmpk_eq_i32 s6, 0x1000
	v_lshl_add_u64 v[4:5], v[4:5], 1, v[6:7]
	s_waitcnt lgkmcnt(0)
	global_store_dwordx4 v[4:5], v[0:3], off nt sc1
	s_cbranch_scc0 .LBB0_999
	s_barrier
	s_branch .LBB0_990
